# K-loops: m0 wait states before LDS-DMA loads filled with the segment's own ds_reads instead of s_nop (12 fewer instructions per iteration)
# baseline (speedup 1.0000x reference)
.LBB0_161:
	s_add_u32 s86, s69, s6
	s_addc_u32 s87, s70, s7
	s_add_u32 s88, s71, s8
	s_addc_u32 s89, s72, s9
	s_ashr_i32 s23, s22, 31
	s_lshl_b64 s[6:7], s[22:23], 19
	s_add_u32 s24, s34, s6
	s_addc_u32 s25, s35, s7
	s_and_b64 s[8:9], s[0:1], exec
	s_cselect_b32 s23, s25, s43
	s_cselect_b32 s90, s24, s42
	s_ashr_i32 s21, s20, 31
	s_lshl_b64 s[8:9], s[20:21], 19
	s_add_u32 s26, s17, s8
	s_addc_u32 s27, s19, s9
	s_and_b64 s[48:49], s[0:1], exec
	s_cselect_b32 s21, s27, s39
	s_cselect_b32 s91, s26, s38
	s_add_u32 s48, s90, 0x80
	s_addc_u32 s49, s23, 0
	s_add_u32 s54, s91, 0x80
	s_addc_u32 s55, s21, 0
	v_lshl_add_u64 v[128:129], s[42:43], 0, v[150:151]
	v_lshl_add_u64 v[130:131], s[42:43], 0, v[152:153]
	s_mov_b32 s92, 0
	s_mov_b64 s[56:57], 0
	s_cmpk_eq_i32 s56, 0x700
	s_cselect_b64 s[62:63], -1, 0
	s_add_u32 s64, s42, s56
	s_addc_u32 s65, s43, s57
	s_add_u32 s94, s38, s56
	s_addc_u32 s93, s39, s57
	s_add_u32 s58, s64, 0x180
	s_addc_u32 s59, s65, 0
	s_add_u32 s60, s94, 0x180
	s_addc_u32 s61, s93, 0
	s_cmpk_eq_i32 s56, 0x700
	s_cselect_b32 s58, s48, s58
	s_cselect_b32 s59, s49, s59
	s_cselect_b32 s60, s54, s60
	s_cselect_b32 s61, s55, s61
	v_add_u32_e32 v144, s82, v171
	ds_read_b128 v[132:135], v144
	ds_read_b128 v[158:161], v144 offset:1024
	ds_read_b128 v[162:165], v144 offset:2048
	ds_read_b128 v[166:169], v144 offset:3072
	v_add_u32_e32 v144, s83, v171
	ds_read_b128 v[184:187], v144
	ds_read_b128 v[188:191], v144 offset:1024
	ds_read_b128 v[192:195], v144 offset:2048
	ds_read_b128 v[196:199], v144 offset:3072
	s_add_u32 s10, s64, 0x100
	s_addc_u32 s95, s65, 0
	s_and_b64 s[64:65], exec, s[62:63]
	s_cselect_b32 s65, s23, s95
	s_cselect_b32 s64, s90, s10
	s_add_u32 s10, s94, 0x100
	s_addc_u32 s93, s93, 0
	s_and_b64 s[62:63], exec, s[62:63]
	s_cselect_b32 s63, s21, s93
	s_cselect_b32 s62, s91, s10
	v_lshl_add_u64 v[232:233], v[128:129], 0, s[56:57]
	s_add_i32 m0, s29, 0xc000
	ds_read_b128 v[200:203], v181
	ds_read_b128 v[204:207], v181 offset:1024
	ds_read_b128 v[208:211], v181 offset:2048
	ds_read_b128 v[212:215], v181 offset:3072
	ds_read_b128 v[216:219], v181 offset:4096
	ds_read_b128 v[220:223], v181 offset:5120
	ds_read_b128 v[224:227], v181 offset:6144
	global_load_lds_dwordx4 v[232:233], off
	v_lshl_add_u64 v[232:233], v[130:131], 0, s[56:57]
	s_add_i32 m0, s29, 0xe000
	ds_read_b128 v[228:231], v181 offset:7168
	global_load_lds_dwordx4 v[232:233], off
	s_waitcnt vmcnt(8)
	s_waitcnt lgkmcnt(0)
	s_barrier
	s_setprio 1
	s_waitcnt lgkmcnt(0)
	v_mfma_f32_16x16x32_bf16 v[124:127], v[132:135], v[200:203], 0
	v_mfma_f32_16x16x32_bf16 v[120:123], v[162:165], v[200:203], 0
	v_mfma_f32_16x16x32_bf16 v[108:111], v[132:135], v[208:211], 0
	v_mfma_f32_16x16x32_bf16 v[104:107], v[162:165], v[208:211], 0
	v_mfma_f32_16x16x32_bf16 v[92:95], v[132:135], v[216:219], 0
	v_mfma_f32_16x16x32_bf16 v[88:91], v[162:165], v[216:219], 0
	v_mfma_f32_16x16x32_bf16 v[76:79], v[132:135], v[224:227], 0
	v_mfma_f32_16x16x32_bf16 v[72:75], v[162:165], v[224:227], 0
	v_mfma_f32_16x16x32_bf16 v[124:127], v[158:161], v[204:207], v[124:127]
	v_mfma_f32_16x16x32_bf16 v[120:123], v[166:169], v[204:207], v[120:123]
	v_mfma_f32_16x16x32_bf16 v[108:111], v[158:161], v[212:215], v[108:111]
	v_mfma_f32_16x16x32_bf16 v[104:107], v[166:169], v[212:215], v[104:107]
	v_mfma_f32_16x16x32_bf16 v[92:95], v[158:161], v[220:223], v[92:95]
	v_mfma_f32_16x16x32_bf16 v[88:91], v[166:169], v[220:223], v[88:91]
	v_mfma_f32_16x16x32_bf16 v[76:79], v[158:161], v[228:231], v[76:79]
	v_mfma_f32_16x16x32_bf16 v[72:75], v[166:169], v[228:231], v[72:75]
	s_setprio 0
	s_setprio 1
	v_mfma_f32_16x16x32_bf16 v[116:119], v[184:187], v[200:203], 0
	v_mfma_f32_16x16x32_bf16 v[112:115], v[192:195], v[200:203], 0
	v_mfma_f32_16x16x32_bf16 v[100:103], v[184:187], v[208:211], 0
	v_mfma_f32_16x16x32_bf16 v[96:99], v[192:195], v[208:211], 0
	v_mfma_f32_16x16x32_bf16 v[84:87], v[184:187], v[216:219], 0
	v_mfma_f32_16x16x32_bf16 v[80:83], v[192:195], v[216:219], 0
	v_mfma_f32_16x16x32_bf16 v[68:71], v[184:187], v[224:227], 0
	v_mfma_f32_16x16x32_bf16 v[64:67], v[192:195], v[224:227], 0
	v_mfma_f32_16x16x32_bf16 v[116:119], v[188:191], v[204:207], v[116:119]
	v_mfma_f32_16x16x32_bf16 v[112:115], v[196:199], v[204:207], v[112:115]
	v_mfma_f32_16x16x32_bf16 v[100:103], v[188:191], v[212:215], v[100:103]
	v_mfma_f32_16x16x32_bf16 v[96:99], v[196:199], v[212:215], v[96:99]
	v_mfma_f32_16x16x32_bf16 v[84:87], v[188:191], v[220:223], v[84:87]
	v_mfma_f32_16x16x32_bf16 v[80:83], v[196:199], v[220:223], v[80:83]
	v_mfma_f32_16x16x32_bf16 v[68:71], v[188:191], v[228:231], v[68:71]
	v_mfma_f32_16x16x32_bf16 v[64:67], v[196:199], v[228:231], v[64:67]
	s_setprio 0
	s_barrier
	s_add_i32 s10, s82, s66
	s_mov_b32 m0, s10
	ds_read_b128 v[200:203], v181 offset:16384
	ds_read_b128 v[204:207], v181 offset:17408
	ds_read_b128 v[208:211], v181 offset:18432
	global_load_lds_dwordx4 v138, s[62:63]
	s_add_i32 m0, s10, 0x2000
	ds_read_b128 v[212:215], v181 offset:19456
	global_load_lds_dwordx4 v142, s[62:63]
	s_add_u32 s62, s62, 0x40000
	s_addc_u32 s63, s63, 0
	s_add_i32 s10, s83, s66
	s_mov_b32 m0, s10
	ds_read_b128 v[216:219], v181 offset:20480
	global_load_lds_dwordx4 v138, s[62:63]
	s_add_i32 m0, s10, 0x2000
	ds_read_b128 v[220:223], v181 offset:21504
	global_load_lds_dwordx4 v142, s[62:63]
	s_mov_b32 m0, s29
	ds_read_b128 v[224:227], v181 offset:22528
	global_load_lds_dwordx4 v136, s[64:65]
	s_mov_b32 m0, s31
	ds_read_b128 v[228:231], v181 offset:23552
	global_load_lds_dwordx4 v140, s[64:65]
	s_waitcnt vmcnt(8)
	s_waitcnt lgkmcnt(0)
	s_barrier
	s_setprio 1
	s_waitcnt lgkmcnt(0)
	v_mfma_f32_16x16x32_bf16 v[60:63], v[132:135], v[200:203], 0
	v_mfma_f32_16x16x32_bf16 v[56:59], v[162:165], v[200:203], 0
	v_mfma_f32_16x16x32_bf16 v[44:47], v[132:135], v[208:211], 0
	v_mfma_f32_16x16x32_bf16 v[40:43], v[162:165], v[208:211], 0
	v_mfma_f32_16x16x32_bf16 v[28:31], v[132:135], v[216:219], 0
	v_mfma_f32_16x16x32_bf16 v[24:27], v[162:165], v[216:219], 0
	v_mfma_f32_16x16x32_bf16 v[12:15], v[132:135], v[224:227], 0
	v_mfma_f32_16x16x32_bf16 v[8:11], v[162:165], v[224:227], 0
	v_mfma_f32_16x16x32_bf16 v[60:63], v[158:161], v[204:207], v[60:63]
	v_mfma_f32_16x16x32_bf16 v[56:59], v[166:169], v[204:207], v[56:59]
	v_mfma_f32_16x16x32_bf16 v[44:47], v[158:161], v[212:215], v[44:47]
	v_mfma_f32_16x16x32_bf16 v[40:43], v[166:169], v[212:215], v[40:43]
	v_mfma_f32_16x16x32_bf16 v[28:31], v[158:161], v[220:223], v[28:31]
	v_mfma_f32_16x16x32_bf16 v[24:27], v[166:169], v[220:223], v[24:27]
	v_mfma_f32_16x16x32_bf16 v[12:15], v[158:161], v[228:231], v[12:15]
	v_mfma_f32_16x16x32_bf16 v[8:11], v[166:169], v[228:231], v[8:11]
	s_setprio 0
	s_setprio 1
	v_mfma_f32_16x16x32_bf16 v[52:55], v[184:187], v[200:203], 0
	v_mfma_f32_16x16x32_bf16 v[48:51], v[192:195], v[200:203], 0
	v_mfma_f32_16x16x32_bf16 v[36:39], v[184:187], v[208:211], 0
	v_mfma_f32_16x16x32_bf16 v[32:35], v[192:195], v[208:211], 0
	v_mfma_f32_16x16x32_bf16 v[20:23], v[184:187], v[216:219], 0
	v_mfma_f32_16x16x32_bf16 v[16:19], v[192:195], v[216:219], 0
	v_mfma_f32_16x16x32_bf16 v[4:7], v[184:187], v[224:227], 0
	v_mfma_f32_16x16x32_bf16 v[0:3], v[192:195], v[224:227], 0
	v_mfma_f32_16x16x32_bf16 v[52:55], v[188:191], v[204:207], v[52:55]
	v_mfma_f32_16x16x32_bf16 v[48:51], v[196:199], v[204:207], v[48:51]
	v_mfma_f32_16x16x32_bf16 v[36:39], v[188:191], v[212:215], v[36:39]
	v_mfma_f32_16x16x32_bf16 v[32:35], v[196:199], v[212:215], v[32:35]
	v_mfma_f32_16x16x32_bf16 v[20:23], v[188:191], v[220:223], v[20:23]
	v_mfma_f32_16x16x32_bf16 v[16:19], v[196:199], v[220:223], v[16:19]
	v_mfma_f32_16x16x32_bf16 v[4:7], v[188:191], v[228:231], v[4:7]
	v_mfma_f32_16x16x32_bf16 v[0:3], v[196:199], v[228:231], v[0:3]
	s_setprio 0
	s_barrier
	s_add_i32 s10, 0, 0x18000
	v_add_u32_e32 v144, s10, v171
	s_add_i32 s93, 0, 0x1c000
	ds_read_b128 v[132:135], v144
	ds_read_b128 v[158:161], v144 offset:1024
	ds_read_b128 v[162:165], v144 offset:2048
	ds_read_b128 v[166:169], v144 offset:3072
	v_add_u32_e32 v144, s93, v171
	ds_read_b128 v[184:187], v144
	ds_read_b128 v[188:191], v144 offset:1024
	ds_read_b128 v[192:195], v144 offset:2048
	ds_read_b128 v[196:199], v144 offset:3072
	s_add_u32 s62, s64, 0x40000
	s_addc_u32 s63, s65, 0
	s_mov_b32 m0, s67
	ds_read_b128 v[200:203], v181 offset:32768
	ds_read_b128 v[204:207], v181 offset:33792
	ds_read_b128 v[208:211], v181 offset:34816
	ds_read_b128 v[212:215], v181 offset:35840
	ds_read_b128 v[216:219], v181 offset:36864
	ds_read_b128 v[220:223], v181 offset:37888
	ds_read_b128 v[224:227], v181 offset:38912
	global_load_lds_dwordx4 v136, s[62:63]
	s_mov_b32 m0, s68
	ds_read_b128 v[228:231], v181 offset:39936
	global_load_lds_dwordx4 v140, s[62:63]
	s_waitcnt vmcnt(8)
	s_waitcnt lgkmcnt(0)
	s_barrier
	s_setprio 1
	s_waitcnt lgkmcnt(0)
	v_mfma_f32_16x16x32_bf16 v[124:127], v[132:135], v[200:203], v[124:127]
	v_mfma_f32_16x16x32_bf16 v[120:123], v[162:165], v[200:203], v[120:123]
	v_mfma_f32_16x16x32_bf16 v[108:111], v[132:135], v[208:211], v[108:111]
	v_mfma_f32_16x16x32_bf16 v[104:107], v[162:165], v[208:211], v[104:107]
	v_mfma_f32_16x16x32_bf16 v[92:95], v[132:135], v[216:219], v[92:95]
	v_mfma_f32_16x16x32_bf16 v[88:91], v[162:165], v[216:219], v[88:91]
	v_mfma_f32_16x16x32_bf16 v[76:79], v[132:135], v[224:227], v[76:79]
	v_mfma_f32_16x16x32_bf16 v[72:75], v[162:165], v[224:227], v[72:75]
	v_mfma_f32_16x16x32_bf16 v[124:127], v[158:161], v[204:207], v[124:127]
	v_mfma_f32_16x16x32_bf16 v[120:123], v[166:169], v[204:207], v[120:123]
	v_mfma_f32_16x16x32_bf16 v[108:111], v[158:161], v[212:215], v[108:111]
	v_mfma_f32_16x16x32_bf16 v[104:107], v[166:169], v[212:215], v[104:107]
	v_mfma_f32_16x16x32_bf16 v[92:95], v[158:161], v[220:223], v[92:95]
	v_mfma_f32_16x16x32_bf16 v[88:91], v[166:169], v[220:223], v[88:91]
	v_mfma_f32_16x16x32_bf16 v[76:79], v[158:161], v[228:231], v[76:79]
	v_mfma_f32_16x16x32_bf16 v[72:75], v[166:169], v[228:231], v[72:75]
	s_setprio 0
	s_setprio 1
	v_mfma_f32_16x16x32_bf16 v[116:119], v[184:187], v[200:203], v[116:119]
	v_mfma_f32_16x16x32_bf16 v[112:115], v[192:195], v[200:203], v[112:115]
	v_mfma_f32_16x16x32_bf16 v[100:103], v[184:187], v[208:211], v[100:103]
	v_mfma_f32_16x16x32_bf16 v[96:99], v[192:195], v[208:211], v[96:99]
	v_mfma_f32_16x16x32_bf16 v[84:87], v[184:187], v[216:219], v[84:87]
	v_mfma_f32_16x16x32_bf16 v[80:83], v[192:195], v[216:219], v[80:83]
	v_mfma_f32_16x16x32_bf16 v[68:71], v[184:187], v[224:227], v[68:71]
	v_mfma_f32_16x16x32_bf16 v[64:67], v[192:195], v[224:227], v[64:67]
	v_mfma_f32_16x16x32_bf16 v[116:119], v[188:191], v[204:207], v[116:119]
	v_mfma_f32_16x16x32_bf16 v[112:115], v[196:199], v[204:207], v[112:115]
	v_mfma_f32_16x16x32_bf16 v[100:103], v[188:191], v[212:215], v[100:103]
	v_mfma_f32_16x16x32_bf16 v[96:99], v[196:199], v[212:215], v[96:99]
	v_mfma_f32_16x16x32_bf16 v[84:87], v[188:191], v[220:223], v[84:87]
	v_mfma_f32_16x16x32_bf16 v[80:83], v[196:199], v[220:223], v[80:83]
	v_mfma_f32_16x16x32_bf16 v[68:71], v[188:191], v[228:231], v[68:71]
	v_mfma_f32_16x16x32_bf16 v[64:67], v[196:199], v[228:231], v[64:67]
	s_setprio 0
	s_barrier
	s_add_i32 s10, s10, s66
	s_mov_b32 m0, s10
	ds_read_b128 v[200:203], v181 offset:49152
	ds_read_b128 v[204:207], v181 offset:50176
	ds_read_b128 v[208:211], v181 offset:51200
	global_load_lds_dwordx4 v138, s[60:61]
	s_add_i32 m0, s10, 0x2000
	ds_read_b128 v[212:215], v181 offset:52224
	global_load_lds_dwordx4 v142, s[60:61]
	s_add_u32 s60, s60, 0x40000
	s_addc_u32 s61, s61, 0
	s_add_i32 s10, s93, s66
	s_mov_b32 m0, s10
	ds_read_b128 v[216:219], v181 offset:53248
	global_load_lds_dwordx4 v138, s[60:61]
	s_add_i32 m0, s10, 0x2000
	ds_read_b128 v[220:223], v181 offset:54272
	global_load_lds_dwordx4 v142, s[60:61]
	s_mov_b32 m0, s73
	ds_read_b128 v[224:227], v181 offset:55296
	global_load_lds_dwordx4 v136, s[58:59]
	v_lshl_add_u64 v[232:233], s[58:59], 0, v[140:141]
	s_mov_b32 m0, s78
	ds_read_b128 v[228:231], v181 offset:56320
	global_load_lds_dwordx4 v[232:233], off
	s_waitcnt vmcnt(8)
	s_waitcnt lgkmcnt(0)
	s_barrier
	s_setprio 1
	s_waitcnt lgkmcnt(0)
	v_mfma_f32_16x16x32_bf16 v[60:63], v[132:135], v[200:203], v[60:63]
	v_mfma_f32_16x16x32_bf16 v[56:59], v[162:165], v[200:203], v[56:59]
	v_mfma_f32_16x16x32_bf16 v[44:47], v[132:135], v[208:211], v[44:47]
	v_mfma_f32_16x16x32_bf16 v[40:43], v[162:165], v[208:211], v[40:43]
	v_mfma_f32_16x16x32_bf16 v[28:31], v[132:135], v[216:219], v[28:31]
	v_mfma_f32_16x16x32_bf16 v[24:27], v[162:165], v[216:219], v[24:27]
	v_mfma_f32_16x16x32_bf16 v[12:15], v[132:135], v[224:227], v[12:15]
	v_mfma_f32_16x16x32_bf16 v[8:11], v[162:165], v[224:227], v[8:11]
	v_mfma_f32_16x16x32_bf16 v[60:63], v[158:161], v[204:207], v[60:63]
	v_mfma_f32_16x16x32_bf16 v[56:59], v[166:169], v[204:207], v[56:59]
	v_mfma_f32_16x16x32_bf16 v[44:47], v[158:161], v[212:215], v[44:47]
	v_mfma_f32_16x16x32_bf16 v[40:43], v[166:169], v[212:215], v[40:43]
	v_mfma_f32_16x16x32_bf16 v[28:31], v[158:161], v[220:223], v[28:31]
	v_mfma_f32_16x16x32_bf16 v[24:27], v[166:169], v[220:223], v[24:27]
	v_mfma_f32_16x16x32_bf16 v[12:15], v[158:161], v[228:231], v[12:15]
	v_mfma_f32_16x16x32_bf16 v[8:11], v[166:169], v[228:231], v[8:11]
	s_setprio 0
	s_setprio 1
	v_mfma_f32_16x16x32_bf16 v[52:55], v[184:187], v[200:203], v[52:55]
	v_mfma_f32_16x16x32_bf16 v[48:51], v[192:195], v[200:203], v[48:51]
	v_mfma_f32_16x16x32_bf16 v[36:39], v[184:187], v[208:211], v[36:39]
	v_mfma_f32_16x16x32_bf16 v[32:35], v[192:195], v[208:211], v[32:35]
	v_mfma_f32_16x16x32_bf16 v[20:23], v[184:187], v[216:219], v[20:23]
	v_mfma_f32_16x16x32_bf16 v[16:19], v[192:195], v[216:219], v[16:19]
	v_mfma_f32_16x16x32_bf16 v[4:7], v[184:187], v[224:227], v[4:7]
	v_mfma_f32_16x16x32_bf16 v[0:3], v[192:195], v[224:227], v[0:3]
	v_mfma_f32_16x16x32_bf16 v[52:55], v[188:191], v[204:207], v[52:55]
	v_mfma_f32_16x16x32_bf16 v[48:51], v[196:199], v[204:207], v[48:51]
	v_mfma_f32_16x16x32_bf16 v[36:39], v[188:191], v[212:215], v[36:39]
	v_mfma_f32_16x16x32_bf16 v[32:35], v[196:199], v[212:215], v[32:35]
	v_mfma_f32_16x16x32_bf16 v[20:23], v[188:191], v[220:223], v[20:23]
	v_mfma_f32_16x16x32_bf16 v[16:19], v[196:199], v[220:223], v[16:19]
	v_mfma_f32_16x16x32_bf16 v[4:7], v[188:191], v[228:231], v[4:7]
	v_mfma_f32_16x16x32_bf16 v[0:3], v[196:199], v[228:231], v[0:3]
	s_setprio 0
	s_barrier
	s_add_i32 s10, s92, 2
	s_add_u32 s56, s56, 0x100
	s_addc_u32 s57, s57, 0
	s_cmp_gt_u32 s92, 13
	s_mov_b32 s92, s10
	s_cbranch_scc1 .LBB0_169
	s_branch .LBB0_163
.LBB0_162:
	v_add_u32_e32 v144, s82, v171
	ds_read_b128 v[132:135], v144
	ds_read_b128 v[158:161], v144 offset:1024
	ds_read_b128 v[162:165], v144 offset:2048
	ds_read_b128 v[166:169], v144 offset:3072
	v_add_u32_e32 v144, s83, v171
	ds_read_b128 v[184:187], v144
	ds_read_b128 v[188:191], v144 offset:1024
	ds_read_b128 v[192:195], v144 offset:2048
	ds_read_b128 v[196:199], v144 offset:3072
	s_add_u32 s10, s64, 0x100
	s_addc_u32 s95, s65, 0
	s_and_b64 s[64:65], exec, s[62:63]
	s_cselect_b32 s65, s23, s95
	s_cselect_b32 s64, s90, s10
	s_add_u32 s10, s94, 0x100
	s_addc_u32 s93, s93, 0
	s_and_b64 s[62:63], exec, s[62:63]
	s_cselect_b32 s63, s21, s93
	s_cselect_b32 s62, s91, s10
	v_lshl_add_u64 v[232:233], v[128:129], 0, s[56:57]
	s_add_i32 m0, s29, 0xc000
	ds_read_b128 v[200:203], v181
	ds_read_b128 v[204:207], v181 offset:1024
	ds_read_b128 v[208:211], v181 offset:2048
	ds_read_b128 v[212:215], v181 offset:3072
	ds_read_b128 v[216:219], v181 offset:4096
	ds_read_b128 v[220:223], v181 offset:5120
	ds_read_b128 v[224:227], v181 offset:6144
	global_load_lds_dwordx4 v[232:233], off
	v_lshl_add_u64 v[232:233], v[130:131], 0, s[56:57]
	s_add_i32 m0, s29, 0xe000
	ds_read_b128 v[228:231], v181 offset:7168
	global_load_lds_dwordx4 v[232:233], off
	s_waitcnt vmcnt(8)
	s_waitcnt lgkmcnt(0)
	s_barrier
	s_setprio 1
	s_waitcnt lgkmcnt(0)
	v_mfma_f32_16x16x32_bf16 v[124:127], v[132:135], v[200:203], v[124:127]
	v_mfma_f32_16x16x32_bf16 v[120:123], v[162:165], v[200:203], v[120:123]
	v_mfma_f32_16x16x32_bf16 v[108:111], v[132:135], v[208:211], v[108:111]
	v_mfma_f32_16x16x32_bf16 v[104:107], v[162:165], v[208:211], v[104:107]
	v_mfma_f32_16x16x32_bf16 v[92:95], v[132:135], v[216:219], v[92:95]
	v_mfma_f32_16x16x32_bf16 v[88:91], v[162:165], v[216:219], v[88:91]
	v_mfma_f32_16x16x32_bf16 v[76:79], v[132:135], v[224:227], v[76:79]
	v_mfma_f32_16x16x32_bf16 v[72:75], v[162:165], v[224:227], v[72:75]
	v_mfma_f32_16x16x32_bf16 v[124:127], v[158:161], v[204:207], v[124:127]
	v_mfma_f32_16x16x32_bf16 v[120:123], v[166:169], v[204:207], v[120:123]
	v_mfma_f32_16x16x32_bf16 v[108:111], v[158:161], v[212:215], v[108:111]
	v_mfma_f32_16x16x32_bf16 v[104:107], v[166:169], v[212:215], v[104:107]
	v_mfma_f32_16x16x32_bf16 v[92:95], v[158:161], v[220:223], v[92:95]
	v_mfma_f32_16x16x32_bf16 v[88:91], v[166:169], v[220:223], v[88:91]
	v_mfma_f32_16x16x32_bf16 v[76:79], v[158:161], v[228:231], v[76:79]
	v_mfma_f32_16x16x32_bf16 v[72:75], v[166:169], v[228:231], v[72:75]
	s_setprio 0
	s_setprio 1
	v_mfma_f32_16x16x32_bf16 v[116:119], v[184:187], v[200:203], v[116:119]
	v_mfma_f32_16x16x32_bf16 v[112:115], v[192:195], v[200:203], v[112:115]
	v_mfma_f32_16x16x32_bf16 v[100:103], v[184:187], v[208:211], v[100:103]
	v_mfma_f32_16x16x32_bf16 v[96:99], v[192:195], v[208:211], v[96:99]
	v_mfma_f32_16x16x32_bf16 v[84:87], v[184:187], v[216:219], v[84:87]
	v_mfma_f32_16x16x32_bf16 v[80:83], v[192:195], v[216:219], v[80:83]
	v_mfma_f32_16x16x32_bf16 v[68:71], v[184:187], v[224:227], v[68:71]
	v_mfma_f32_16x16x32_bf16 v[64:67], v[192:195], v[224:227], v[64:67]
	v_mfma_f32_16x16x32_bf16 v[116:119], v[188:191], v[204:207], v[116:119]
	v_mfma_f32_16x16x32_bf16 v[112:115], v[196:199], v[204:207], v[112:115]
	v_mfma_f32_16x16x32_bf16 v[100:103], v[188:191], v[212:215], v[100:103]
	v_mfma_f32_16x16x32_bf16 v[96:99], v[196:199], v[212:215], v[96:99]
	v_mfma_f32_16x16x32_bf16 v[84:87], v[188:191], v[220:223], v[84:87]
	v_mfma_f32_16x16x32_bf16 v[80:83], v[196:199], v[220:223], v[80:83]
	v_mfma_f32_16x16x32_bf16 v[68:71], v[188:191], v[228:231], v[68:71]
	v_mfma_f32_16x16x32_bf16 v[64:67], v[196:199], v[228:231], v[64:67]
	s_setprio 0
	s_barrier
	s_add_i32 s10, s82, s66
	s_mov_b32 m0, s10
	ds_read_b128 v[200:203], v181 offset:16384
	ds_read_b128 v[204:207], v181 offset:17408
	ds_read_b128 v[208:211], v181 offset:18432
	global_load_lds_dwordx4 v138, s[62:63]
	s_add_i32 m0, s10, 0x2000
	ds_read_b128 v[212:215], v181 offset:19456
	global_load_lds_dwordx4 v142, s[62:63]
	s_add_u32 s62, s62, 0x40000
	s_addc_u32 s63, s63, 0
	s_add_i32 s10, s83, s66
	s_mov_b32 m0, s10
	ds_read_b128 v[216:219], v181 offset:20480
	global_load_lds_dwordx4 v138, s[62:63]
	s_add_i32 m0, s10, 0x2000
	ds_read_b128 v[220:223], v181 offset:21504
	global_load_lds_dwordx4 v142, s[62:63]
	s_mov_b32 m0, s29
	ds_read_b128 v[224:227], v181 offset:22528
	global_load_lds_dwordx4 v136, s[64:65]
	s_mov_b32 m0, s31
	ds_read_b128 v[228:231], v181 offset:23552
	global_load_lds_dwordx4 v140, s[64:65]
	s_waitcnt vmcnt(8)
	s_waitcnt lgkmcnt(0)
	s_barrier
	s_setprio 1
	s_waitcnt lgkmcnt(0)
	v_mfma_f32_16x16x32_bf16 v[60:63], v[132:135], v[200:203], v[60:63]
	v_mfma_f32_16x16x32_bf16 v[56:59], v[162:165], v[200:203], v[56:59]
	v_mfma_f32_16x16x32_bf16 v[44:47], v[132:135], v[208:211], v[44:47]
	v_mfma_f32_16x16x32_bf16 v[40:43], v[162:165], v[208:211], v[40:43]
	v_mfma_f32_16x16x32_bf16 v[28:31], v[132:135], v[216:219], v[28:31]
	v_mfma_f32_16x16x32_bf16 v[24:27], v[162:165], v[216:219], v[24:27]
	v_mfma_f32_16x16x32_bf16 v[12:15], v[132:135], v[224:227], v[12:15]
	v_mfma_f32_16x16x32_bf16 v[8:11], v[162:165], v[224:227], v[8:11]
	v_mfma_f32_16x16x32_bf16 v[60:63], v[158:161], v[204:207], v[60:63]
	v_mfma_f32_16x16x32_bf16 v[56:59], v[166:169], v[204:207], v[56:59]
	v_mfma_f32_16x16x32_bf16 v[44:47], v[158:161], v[212:215], v[44:47]
	v_mfma_f32_16x16x32_bf16 v[40:43], v[166:169], v[212:215], v[40:43]
	v_mfma_f32_16x16x32_bf16 v[28:31], v[158:161], v[220:223], v[28:31]
	v_mfma_f32_16x16x32_bf16 v[24:27], v[166:169], v[220:223], v[24:27]
	v_mfma_f32_16x16x32_bf16 v[12:15], v[158:161], v[228:231], v[12:15]
	v_mfma_f32_16x16x32_bf16 v[8:11], v[166:169], v[228:231], v[8:11]
	s_setprio 0
	s_setprio 1
	v_mfma_f32_16x16x32_bf16 v[52:55], v[184:187], v[200:203], v[52:55]
	v_mfma_f32_16x16x32_bf16 v[48:51], v[192:195], v[200:203], v[48:51]
	v_mfma_f32_16x16x32_bf16 v[36:39], v[184:187], v[208:211], v[36:39]
	v_mfma_f32_16x16x32_bf16 v[32:35], v[192:195], v[208:211], v[32:35]
	v_mfma_f32_16x16x32_bf16 v[20:23], v[184:187], v[216:219], v[20:23]
	v_mfma_f32_16x16x32_bf16 v[16:19], v[192:195], v[216:219], v[16:19]
	v_mfma_f32_16x16x32_bf16 v[4:7], v[184:187], v[224:227], v[4:7]
	v_mfma_f32_16x16x32_bf16 v[0:3], v[192:195], v[224:227], v[0:3]
	v_mfma_f32_16x16x32_bf16 v[52:55], v[188:191], v[204:207], v[52:55]
	v_mfma_f32_16x16x32_bf16 v[48:51], v[196:199], v[204:207], v[48:51]
	v_mfma_f32_16x16x32_bf16 v[36:39], v[188:191], v[212:215], v[36:39]
	v_mfma_f32_16x16x32_bf16 v[32:35], v[196:199], v[212:215], v[32:35]
	v_mfma_f32_16x16x32_bf16 v[20:23], v[188:191], v[220:223], v[20:23]
	v_mfma_f32_16x16x32_bf16 v[16:19], v[196:199], v[220:223], v[16:19]
	v_mfma_f32_16x16x32_bf16 v[4:7], v[188:191], v[228:231], v[4:7]
	v_mfma_f32_16x16x32_bf16 v[0:3], v[196:199], v[228:231], v[0:3]
	s_setprio 0
	s_barrier
	s_add_i32 s10, 0, 0x18000
	v_add_u32_e32 v144, s10, v171
	s_add_i32 s93, 0, 0x1c000
	ds_read_b128 v[132:135], v144
	ds_read_b128 v[158:161], v144 offset:1024
	ds_read_b128 v[162:165], v144 offset:2048
	ds_read_b128 v[166:169], v144 offset:3072
	v_add_u32_e32 v144, s93, v171
	ds_read_b128 v[184:187], v144
	ds_read_b128 v[188:191], v144 offset:1024
	ds_read_b128 v[192:195], v144 offset:2048
	ds_read_b128 v[196:199], v144 offset:3072
	s_add_u32 s62, s64, 0x40000
	s_addc_u32 s63, s65, 0
	s_mov_b32 m0, s67
	ds_read_b128 v[200:203], v181 offset:32768
	ds_read_b128 v[204:207], v181 offset:33792
	ds_read_b128 v[208:211], v181 offset:34816
	ds_read_b128 v[212:215], v181 offset:35840
	ds_read_b128 v[216:219], v181 offset:36864
	ds_read_b128 v[220:223], v181 offset:37888
	ds_read_b128 v[224:227], v181 offset:38912
	global_load_lds_dwordx4 v136, s[62:63]
	s_mov_b32 m0, s68
	ds_read_b128 v[228:231], v181 offset:39936
	global_load_lds_dwordx4 v140, s[62:63]
	s_waitcnt vmcnt(8)
	s_waitcnt lgkmcnt(0)
	s_barrier
	s_setprio 1
	s_waitcnt lgkmcnt(0)
	v_mfma_f32_16x16x32_bf16 v[124:127], v[132:135], v[200:203], v[124:127]
	v_mfma_f32_16x16x32_bf16 v[120:123], v[162:165], v[200:203], v[120:123]
	v_mfma_f32_16x16x32_bf16 v[108:111], v[132:135], v[208:211], v[108:111]
	v_mfma_f32_16x16x32_bf16 v[104:107], v[162:165], v[208:211], v[104:107]
	v_mfma_f32_16x16x32_bf16 v[92:95], v[132:135], v[216:219], v[92:95]
	v_mfma_f32_16x16x32_bf16 v[88:91], v[162:165], v[216:219], v[88:91]
	v_mfma_f32_16x16x32_bf16 v[76:79], v[132:135], v[224:227], v[76:79]
	v_mfma_f32_16x16x32_bf16 v[72:75], v[162:165], v[224:227], v[72:75]
	v_mfma_f32_16x16x32_bf16 v[124:127], v[158:161], v[204:207], v[124:127]
	v_mfma_f32_16x16x32_bf16 v[120:123], v[166:169], v[204:207], v[120:123]
	v_mfma_f32_16x16x32_bf16 v[108:111], v[158:161], v[212:215], v[108:111]
	v_mfma_f32_16x16x32_bf16 v[104:107], v[166:169], v[212:215], v[104:107]
	v_mfma_f32_16x16x32_bf16 v[92:95], v[158:161], v[220:223], v[92:95]
	v_mfma_f32_16x16x32_bf16 v[88:91], v[166:169], v[220:223], v[88:91]
	v_mfma_f32_16x16x32_bf16 v[76:79], v[158:161], v[228:231], v[76:79]
	v_mfma_f32_16x16x32_bf16 v[72:75], v[166:169], v[228:231], v[72:75]
	s_setprio 0
	s_setprio 1
	v_mfma_f32_16x16x32_bf16 v[116:119], v[184:187], v[200:203], v[116:119]
	v_mfma_f32_16x16x32_bf16 v[112:115], v[192:195], v[200:203], v[112:115]
	v_mfma_f32_16x16x32_bf16 v[100:103], v[184:187], v[208:211], v[100:103]
	v_mfma_f32_16x16x32_bf16 v[96:99], v[192:195], v[208:211], v[96:99]
	v_mfma_f32_16x16x32_bf16 v[84:87], v[184:187], v[216:219], v[84:87]
	v_mfma_f32_16x16x32_bf16 v[80:83], v[192:195], v[216:219], v[80:83]
	v_mfma_f32_16x16x32_bf16 v[68:71], v[184:187], v[224:227], v[68:71]
	v_mfma_f32_16x16x32_bf16 v[64:67], v[192:195], v[224:227], v[64:67]
	v_mfma_f32_16x16x32_bf16 v[116:119], v[188:191], v[204:207], v[116:119]
	v_mfma_f32_16x16x32_bf16 v[112:115], v[196:199], v[204:207], v[112:115]
	v_mfma_f32_16x16x32_bf16 v[100:103], v[188:191], v[212:215], v[100:103]
	v_mfma_f32_16x16x32_bf16 v[96:99], v[196:199], v[212:215], v[96:99]
	v_mfma_f32_16x16x32_bf16 v[84:87], v[188:191], v[220:223], v[84:87]
	v_mfma_f32_16x16x32_bf16 v[80:83], v[196:199], v[220:223], v[80:83]
	v_mfma_f32_16x16x32_bf16 v[68:71], v[188:191], v[228:231], v[68:71]
	v_mfma_f32_16x16x32_bf16 v[64:67], v[196:199], v[228:231], v[64:67]
	s_setprio 0
	s_barrier
	s_add_i32 s10, s10, s66
	s_mov_b32 m0, s10
	ds_read_b128 v[200:203], v181 offset:49152
	ds_read_b128 v[204:207], v181 offset:50176
	ds_read_b128 v[208:211], v181 offset:51200
	global_load_lds_dwordx4 v138, s[60:61]
	s_add_i32 m0, s10, 0x2000
	ds_read_b128 v[212:215], v181 offset:52224
	global_load_lds_dwordx4 v142, s[60:61]
	s_add_u32 s60, s60, 0x40000
	s_addc_u32 s61, s61, 0
	s_add_i32 s10, s93, s66
	s_mov_b32 m0, s10
	ds_read_b128 v[216:219], v181 offset:53248
	global_load_lds_dwordx4 v138, s[60:61]
	s_add_i32 m0, s10, 0x2000
	ds_read_b128 v[220:223], v181 offset:54272
	global_load_lds_dwordx4 v142, s[60:61]
	s_mov_b32 m0, s73
	ds_read_b128 v[224:227], v181 offset:55296
	global_load_lds_dwordx4 v136, s[58:59]
	v_lshl_add_u64 v[232:233], s[58:59], 0, v[140:141]
	s_mov_b32 m0, s78
	ds_read_b128 v[228:231], v181 offset:56320
	global_load_lds_dwordx4 v[232:233], off
	s_waitcnt vmcnt(8)
	s_waitcnt lgkmcnt(0)
	s_barrier
	s_setprio 1
	s_waitcnt lgkmcnt(0)
	v_mfma_f32_16x16x32_bf16 v[60:63], v[132:135], v[200:203], v[60:63]
	v_mfma_f32_16x16x32_bf16 v[56:59], v[162:165], v[200:203], v[56:59]
	v_mfma_f32_16x16x32_bf16 v[44:47], v[132:135], v[208:211], v[44:47]
	v_mfma_f32_16x16x32_bf16 v[40:43], v[162:165], v[208:211], v[40:43]
	v_mfma_f32_16x16x32_bf16 v[28:31], v[132:135], v[216:219], v[28:31]
	v_mfma_f32_16x16x32_bf16 v[24:27], v[162:165], v[216:219], v[24:27]
	v_mfma_f32_16x16x32_bf16 v[12:15], v[132:135], v[224:227], v[12:15]
	v_mfma_f32_16x16x32_bf16 v[8:11], v[162:165], v[224:227], v[8:11]
	v_mfma_f32_16x16x32_bf16 v[60:63], v[158:161], v[204:207], v[60:63]
	v_mfma_f32_16x16x32_bf16 v[56:59], v[166:169], v[204:207], v[56:59]
	v_mfma_f32_16x16x32_bf16 v[44:47], v[158:161], v[212:215], v[44:47]
	v_mfma_f32_16x16x32_bf16 v[40:43], v[166:169], v[212:215], v[40:43]
	v_mfma_f32_16x16x32_bf16 v[28:31], v[158:161], v[220:223], v[28:31]
	v_mfma_f32_16x16x32_bf16 v[24:27], v[166:169], v[220:223], v[24:27]
	v_mfma_f32_16x16x32_bf16 v[12:15], v[158:161], v[228:231], v[12:15]
	v_mfma_f32_16x16x32_bf16 v[8:11], v[166:169], v[228:231], v[8:11]
	s_setprio 0
	s_setprio 1
	v_mfma_f32_16x16x32_bf16 v[52:55], v[184:187], v[200:203], v[52:55]
	v_mfma_f32_16x16x32_bf16 v[48:51], v[192:195], v[200:203], v[48:51]
	v_mfma_f32_16x16x32_bf16 v[36:39], v[184:187], v[208:211], v[36:39]
	v_mfma_f32_16x16x32_bf16 v[32:35], v[192:195], v[208:211], v[32:35]
	v_mfma_f32_16x16x32_bf16 v[20:23], v[184:187], v[216:219], v[20:23]
	v_mfma_f32_16x16x32_bf16 v[16:19], v[192:195], v[216:219], v[16:19]
	v_mfma_f32_16x16x32_bf16 v[4:7], v[184:187], v[224:227], v[4:7]
	v_mfma_f32_16x16x32_bf16 v[0:3], v[192:195], v[224:227], v[0:3]
	v_mfma_f32_16x16x32_bf16 v[52:55], v[188:191], v[204:207], v[52:55]
	v_mfma_f32_16x16x32_bf16 v[48:51], v[196:199], v[204:207], v[48:51]
	v_mfma_f32_16x16x32_bf16 v[36:39], v[188:191], v[212:215], v[36:39]
	v_mfma_f32_16x16x32_bf16 v[32:35], v[196:199], v[212:215], v[32:35]
	v_mfma_f32_16x16x32_bf16 v[20:23], v[188:191], v[220:223], v[20:23]
	v_mfma_f32_16x16x32_bf16 v[16:19], v[196:199], v[220:223], v[16:19]
	v_mfma_f32_16x16x32_bf16 v[4:7], v[188:191], v[228:231], v[4:7]
	v_mfma_f32_16x16x32_bf16 v[0:3], v[196:199], v[228:231], v[0:3]
	s_setprio 0
	s_barrier
	s_add_i32 s10, s92, 2
	s_add_u32 s56, s56, 0x100
	s_addc_u32 s57, s57, 0
	s_cmp_gt_u32 s92, 13
	s_mov_b32 s92, s10
	s_cbranch_scc1 .LBB0_169

.LBB0_713:
	s_add_u32 s19, s63, s6
	s_addc_u32 s29, s64, s7
	s_add_u32 s31, s65, s8
	s_addc_u32 s79, s66, s9
	s_ashr_i32 s23, s22, 31
	s_lshl_b64 s[6:7], s[22:23], 19
	s_add_u32 s24, s34, s6
	s_addc_u32 s25, s35, s7
	s_and_b64 s[8:9], s[4:5], exec
	s_cselect_b32 s23, s25, s45
	s_cselect_b32 s80, s24, s44
	s_ashr_i32 s21, s20, 31
	s_lshl_b64 s[8:9], s[20:21], 19
	s_add_u32 s26, s42, s8
	s_addc_u32 s27, s43, s9
	s_and_b64 s[36:37], s[4:5], exec
	s_cselect_b32 s21, s27, s39
	s_cselect_b32 s81, s26, s38
	s_add_u32 s36, s80, 0x80
	s_addc_u32 s37, s23, 0
	s_add_u32 s46, s81, 0x80
	s_addc_u32 s47, s21, 0
	v_lshl_add_u64 v[128:129], s[44:45], 0, v[156:157]
	v_lshl_add_u64 v[130:131], s[44:45], 0, v[158:159]
	s_mov_b32 s82, 0
	s_mov_b64 s[48:49], 0
	s_cmpk_eq_i32 s48, 0x700
	s_cselect_b64 s[54:55], -1, 0
	s_add_u32 s56, s44, s48
	s_addc_u32 s57, s45, s49
	s_add_u32 s84, s38, s48
	s_addc_u32 s83, s39, s49
	s_add_u32 s50, s56, 0x180
	s_addc_u32 s51, s57, 0
	s_add_u32 s52, s84, 0x180
	s_addc_u32 s53, s83, 0
	s_cmpk_eq_i32 s48, 0x700
	s_cselect_b32 s50, s36, s50
	s_cselect_b32 s51, s37, s51
	s_cselect_b32 s52, s46, s52
	s_cselect_b32 s53, s47, s53
	v_add_u32_e32 v164, s72, v171
	v_add_u32_e32 v168, s73, v171
	ds_read_b128 v[132:135], v164
	ds_read_b128 v[136:139], v164 offset:1024
	ds_read_b128 v[140:143], v164 offset:2048
	ds_read_b128 v[164:167], v164 offset:3072
	ds_read_b128 v[174:177], v168
	ds_read_b128 v[178:181], v168 offset:1024
	ds_read_b128 v[182:185], v168 offset:2048
	ds_read_b128 v[186:189], v168 offset:3072
	s_add_u32 s10, s56, 0x100
	s_addc_u32 s85, s57, 0
	s_and_b64 s[56:57], exec, s[54:55]
	s_cselect_b32 s57, s23, s85
	s_cselect_b32 s56, s80, s10
	s_add_u32 s10, s84, 0x100
	s_addc_u32 s83, s83, 0
	s_and_b64 s[54:55], exec, s[54:55]
	s_cselect_b32 s55, s21, s83
	s_cselect_b32 s54, s81, s10
	v_lshl_add_u64 v[168:169], v[128:129], 0, s[48:49]
	s_add_i32 m0, s59, 0xc000
	ds_read_b128 v[190:193], v172
	ds_read_b128 v[194:197], v172 offset:1024
	ds_read_b128 v[198:201], v172 offset:2048
	ds_read_b128 v[202:205], v172 offset:3072
	ds_read_b128 v[206:209], v172 offset:4096
	ds_read_b128 v[210:213], v172 offset:5120
	ds_read_b128 v[214:217], v172 offset:6144
	global_load_lds_dwordx4 v[168:169], off
	v_lshl_add_u64 v[168:169], v[130:131], 0, s[48:49]
	s_add_i32 m0, s59, 0xe000
	ds_read_b128 v[218:221], v172 offset:7168
	global_load_lds_dwordx4 v[168:169], off
	s_waitcnt vmcnt(8)
	s_waitcnt lgkmcnt(0)
	s_barrier
	s_setprio 1
	s_waitcnt lgkmcnt(0)
	v_mfma_f32_16x16x32_bf16 v[124:127], v[132:135], v[190:193], 0
	v_mfma_f32_16x16x32_bf16 v[120:123], v[140:143], v[190:193], 0
	v_mfma_f32_16x16x32_bf16 v[108:111], v[132:135], v[198:201], 0
	v_mfma_f32_16x16x32_bf16 v[104:107], v[140:143], v[198:201], 0
	v_mfma_f32_16x16x32_bf16 v[92:95], v[132:135], v[206:209], 0
	v_mfma_f32_16x16x32_bf16 v[88:91], v[140:143], v[206:209], 0
	v_mfma_f32_16x16x32_bf16 v[76:79], v[132:135], v[214:217], 0
	v_mfma_f32_16x16x32_bf16 v[72:75], v[140:143], v[214:217], 0
	v_mfma_f32_16x16x32_bf16 v[124:127], v[136:139], v[194:197], v[124:127]
	v_mfma_f32_16x16x32_bf16 v[120:123], v[164:167], v[194:197], v[120:123]
	v_mfma_f32_16x16x32_bf16 v[108:111], v[136:139], v[202:205], v[108:111]
	v_mfma_f32_16x16x32_bf16 v[104:107], v[164:167], v[202:205], v[104:107]
	v_mfma_f32_16x16x32_bf16 v[92:95], v[136:139], v[210:213], v[92:95]
	v_mfma_f32_16x16x32_bf16 v[88:91], v[164:167], v[210:213], v[88:91]
	v_mfma_f32_16x16x32_bf16 v[76:79], v[136:139], v[218:221], v[76:79]
	v_mfma_f32_16x16x32_bf16 v[72:75], v[164:167], v[218:221], v[72:75]
	s_setprio 0
	s_setprio 1
	v_mfma_f32_16x16x32_bf16 v[116:119], v[174:177], v[190:193], 0
	v_mfma_f32_16x16x32_bf16 v[112:115], v[182:185], v[190:193], 0
	v_mfma_f32_16x16x32_bf16 v[100:103], v[174:177], v[198:201], 0
	v_mfma_f32_16x16x32_bf16 v[96:99], v[182:185], v[198:201], 0
	v_mfma_f32_16x16x32_bf16 v[84:87], v[174:177], v[206:209], 0
	v_mfma_f32_16x16x32_bf16 v[80:83], v[182:185], v[206:209], 0
	v_mfma_f32_16x16x32_bf16 v[68:71], v[174:177], v[214:217], 0
	v_mfma_f32_16x16x32_bf16 v[64:67], v[182:185], v[214:217], 0
	v_mfma_f32_16x16x32_bf16 v[116:119], v[178:181], v[194:197], v[116:119]
	v_mfma_f32_16x16x32_bf16 v[112:115], v[186:189], v[194:197], v[112:115]
	v_mfma_f32_16x16x32_bf16 v[100:103], v[178:181], v[202:205], v[100:103]
	v_mfma_f32_16x16x32_bf16 v[96:99], v[186:189], v[202:205], v[96:99]
	v_mfma_f32_16x16x32_bf16 v[84:87], v[178:181], v[210:213], v[84:87]
	v_mfma_f32_16x16x32_bf16 v[80:83], v[186:189], v[210:213], v[80:83]
	v_mfma_f32_16x16x32_bf16 v[68:71], v[178:181], v[218:221], v[68:71]
	v_mfma_f32_16x16x32_bf16 v[64:67], v[186:189], v[218:221], v[64:67]
	s_setprio 0
	s_barrier
	s_add_i32 s10, s72, s58
	s_mov_b32 m0, s10
	ds_read_b128 v[190:193], v172 offset:16384
	ds_read_b128 v[194:197], v172 offset:17408
	ds_read_b128 v[198:201], v172 offset:18432
	global_load_lds_dwordx4 v146, s[54:55]
	s_add_i32 m0, s10, 0x2000
	ds_read_b128 v[202:205], v172 offset:19456
	global_load_lds_dwordx4 v150, s[54:55]
	s_add_u32 s54, s54, 0x40000
	s_addc_u32 s55, s55, 0
	s_add_i32 s10, s73, s58
	s_mov_b32 m0, s10
	ds_read_b128 v[206:209], v172 offset:20480
	global_load_lds_dwordx4 v146, s[54:55]
	s_add_i32 m0, s10, 0x2000
	ds_read_b128 v[210:213], v172 offset:21504
	global_load_lds_dwordx4 v150, s[54:55]
	s_mov_b32 m0, s59
	ds_read_b128 v[214:217], v172 offset:22528
	global_load_lds_dwordx4 v144, s[56:57]
	s_mov_b32 m0, s60
	ds_read_b128 v[218:221], v172 offset:23552
	global_load_lds_dwordx4 v148, s[56:57]
	s_waitcnt vmcnt(8)
	s_waitcnt lgkmcnt(0)
	s_barrier
	s_setprio 1
	s_waitcnt lgkmcnt(0)
	v_mfma_f32_16x16x32_bf16 v[60:63], v[132:135], v[190:193], 0
	v_mfma_f32_16x16x32_bf16 v[56:59], v[140:143], v[190:193], 0
	v_mfma_f32_16x16x32_bf16 v[44:47], v[132:135], v[198:201], 0
	v_mfma_f32_16x16x32_bf16 v[40:43], v[140:143], v[198:201], 0
	v_mfma_f32_16x16x32_bf16 v[28:31], v[132:135], v[206:209], 0
	v_mfma_f32_16x16x32_bf16 v[24:27], v[140:143], v[206:209], 0
	v_mfma_f32_16x16x32_bf16 v[12:15], v[132:135], v[214:217], 0
	v_mfma_f32_16x16x32_bf16 v[8:11], v[140:143], v[214:217], 0
	v_mfma_f32_16x16x32_bf16 v[60:63], v[136:139], v[194:197], v[60:63]
	v_mfma_f32_16x16x32_bf16 v[56:59], v[164:167], v[194:197], v[56:59]
	v_mfma_f32_16x16x32_bf16 v[44:47], v[136:139], v[202:205], v[44:47]
	v_mfma_f32_16x16x32_bf16 v[40:43], v[164:167], v[202:205], v[40:43]
	v_mfma_f32_16x16x32_bf16 v[28:31], v[136:139], v[210:213], v[28:31]
	v_mfma_f32_16x16x32_bf16 v[24:27], v[164:167], v[210:213], v[24:27]
	v_mfma_f32_16x16x32_bf16 v[12:15], v[136:139], v[218:221], v[12:15]
	v_mfma_f32_16x16x32_bf16 v[8:11], v[164:167], v[218:221], v[8:11]
	s_setprio 0
	s_setprio 1
	v_mfma_f32_16x16x32_bf16 v[52:55], v[174:177], v[190:193], 0
	v_mfma_f32_16x16x32_bf16 v[48:51], v[182:185], v[190:193], 0
	v_mfma_f32_16x16x32_bf16 v[36:39], v[174:177], v[198:201], 0
	v_mfma_f32_16x16x32_bf16 v[32:35], v[182:185], v[198:201], 0
	v_mfma_f32_16x16x32_bf16 v[20:23], v[174:177], v[206:209], 0
	v_mfma_f32_16x16x32_bf16 v[16:19], v[182:185], v[206:209], 0
	v_mfma_f32_16x16x32_bf16 v[4:7], v[174:177], v[214:217], 0
	v_mfma_f32_16x16x32_bf16 v[0:3], v[182:185], v[214:217], 0
	v_mfma_f32_16x16x32_bf16 v[52:55], v[178:181], v[194:197], v[52:55]
	v_mfma_f32_16x16x32_bf16 v[48:51], v[186:189], v[194:197], v[48:51]
	v_mfma_f32_16x16x32_bf16 v[36:39], v[178:181], v[202:205], v[36:39]
	v_mfma_f32_16x16x32_bf16 v[32:35], v[186:189], v[202:205], v[32:35]
	v_mfma_f32_16x16x32_bf16 v[20:23], v[178:181], v[210:213], v[20:23]
	v_mfma_f32_16x16x32_bf16 v[16:19], v[186:189], v[210:213], v[16:19]
	v_mfma_f32_16x16x32_bf16 v[4:7], v[178:181], v[218:221], v[4:7]
	v_mfma_f32_16x16x32_bf16 v[0:3], v[186:189], v[218:221], v[0:3]
	s_setprio 0
	s_barrier
	s_add_i32 s10, 0, 0x18000
	s_add_i32 s83, 0, 0x1c000
	v_add_u32_e32 v164, s10, v171
	v_add_u32_e32 v168, s83, v171
	ds_read_b128 v[132:135], v164
	ds_read_b128 v[136:139], v164 offset:1024
	ds_read_b128 v[140:143], v164 offset:2048
	ds_read_b128 v[164:167], v164 offset:3072
	ds_read_b128 v[174:177], v168
	ds_read_b128 v[178:181], v168 offset:1024
	ds_read_b128 v[182:185], v168 offset:2048
	ds_read_b128 v[186:189], v168 offset:3072
	s_add_u32 s54, s56, 0x40000
	s_addc_u32 s55, s57, 0
	s_mov_b32 m0, s61
	ds_read_b128 v[190:193], v172 offset:32768
	ds_read_b128 v[194:197], v172 offset:33792
	ds_read_b128 v[198:201], v172 offset:34816
	ds_read_b128 v[202:205], v172 offset:35840
	ds_read_b128 v[206:209], v172 offset:36864
	ds_read_b128 v[210:213], v172 offset:37888
	ds_read_b128 v[214:217], v172 offset:38912
	global_load_lds_dwordx4 v144, s[54:55]
	s_mov_b32 m0, s62
	ds_read_b128 v[218:221], v172 offset:39936
	global_load_lds_dwordx4 v148, s[54:55]
	s_waitcnt vmcnt(8)
	s_waitcnt lgkmcnt(0)
	s_barrier
	s_setprio 1
	s_waitcnt lgkmcnt(0)
	v_mfma_f32_16x16x32_bf16 v[124:127], v[132:135], v[190:193], v[124:127]
	v_mfma_f32_16x16x32_bf16 v[120:123], v[140:143], v[190:193], v[120:123]
	v_mfma_f32_16x16x32_bf16 v[108:111], v[132:135], v[198:201], v[108:111]
	v_mfma_f32_16x16x32_bf16 v[104:107], v[140:143], v[198:201], v[104:107]
	v_mfma_f32_16x16x32_bf16 v[92:95], v[132:135], v[206:209], v[92:95]
	v_mfma_f32_16x16x32_bf16 v[88:91], v[140:143], v[206:209], v[88:91]
	v_mfma_f32_16x16x32_bf16 v[76:79], v[132:135], v[214:217], v[76:79]
	v_mfma_f32_16x16x32_bf16 v[72:75], v[140:143], v[214:217], v[72:75]
	v_mfma_f32_16x16x32_bf16 v[124:127], v[136:139], v[194:197], v[124:127]
	v_mfma_f32_16x16x32_bf16 v[120:123], v[164:167], v[194:197], v[120:123]
	v_mfma_f32_16x16x32_bf16 v[108:111], v[136:139], v[202:205], v[108:111]
	v_mfma_f32_16x16x32_bf16 v[104:107], v[164:167], v[202:205], v[104:107]
	v_mfma_f32_16x16x32_bf16 v[92:95], v[136:139], v[210:213], v[92:95]
	v_mfma_f32_16x16x32_bf16 v[88:91], v[164:167], v[210:213], v[88:91]
	v_mfma_f32_16x16x32_bf16 v[76:79], v[136:139], v[218:221], v[76:79]
	v_mfma_f32_16x16x32_bf16 v[72:75], v[164:167], v[218:221], v[72:75]
	s_setprio 0
	s_setprio 1
	v_mfma_f32_16x16x32_bf16 v[116:119], v[174:177], v[190:193], v[116:119]
	v_mfma_f32_16x16x32_bf16 v[112:115], v[182:185], v[190:193], v[112:115]
	v_mfma_f32_16x16x32_bf16 v[100:103], v[174:177], v[198:201], v[100:103]
	v_mfma_f32_16x16x32_bf16 v[96:99], v[182:185], v[198:201], v[96:99]
	v_mfma_f32_16x16x32_bf16 v[84:87], v[174:177], v[206:209], v[84:87]
	v_mfma_f32_16x16x32_bf16 v[80:83], v[182:185], v[206:209], v[80:83]
	v_mfma_f32_16x16x32_bf16 v[68:71], v[174:177], v[214:217], v[68:71]
	v_mfma_f32_16x16x32_bf16 v[64:67], v[182:185], v[214:217], v[64:67]
	v_mfma_f32_16x16x32_bf16 v[116:119], v[178:181], v[194:197], v[116:119]
	v_mfma_f32_16x16x32_bf16 v[112:115], v[186:189], v[194:197], v[112:115]
	v_mfma_f32_16x16x32_bf16 v[100:103], v[178:181], v[202:205], v[100:103]
	v_mfma_f32_16x16x32_bf16 v[96:99], v[186:189], v[202:205], v[96:99]
	v_mfma_f32_16x16x32_bf16 v[84:87], v[178:181], v[210:213], v[84:87]
	v_mfma_f32_16x16x32_bf16 v[80:83], v[186:189], v[210:213], v[80:83]
	v_mfma_f32_16x16x32_bf16 v[68:71], v[178:181], v[218:221], v[68:71]
	v_mfma_f32_16x16x32_bf16 v[64:67], v[186:189], v[218:221], v[64:67]
	s_setprio 0
	s_barrier
	s_add_i32 s10, s10, s58
	s_mov_b32 m0, s10
	ds_read_b128 v[190:193], v172 offset:49152
	ds_read_b128 v[194:197], v172 offset:50176
	ds_read_b128 v[198:201], v172 offset:51200
	global_load_lds_dwordx4 v146, s[52:53]
	s_add_i32 m0, s10, 0x2000
	ds_read_b128 v[202:205], v172 offset:52224
	global_load_lds_dwordx4 v150, s[52:53]
	s_add_u32 s52, s52, 0x40000
	s_addc_u32 s53, s53, 0
	s_add_i32 s10, s83, s58
	s_mov_b32 m0, s10
	ds_read_b128 v[206:209], v172 offset:53248
	global_load_lds_dwordx4 v146, s[52:53]
	s_add_i32 m0, s10, 0x2000
	ds_read_b128 v[210:213], v172 offset:54272
	global_load_lds_dwordx4 v150, s[52:53]
	s_mov_b32 m0, s68
	ds_read_b128 v[214:217], v172 offset:55296
	global_load_lds_dwordx4 v144, s[50:51]
	s_mov_b32 m0, s69
	ds_read_b128 v[218:221], v172 offset:56320
	global_load_lds_dwordx4 v148, s[50:51]
	s_waitcnt vmcnt(8)
	s_waitcnt lgkmcnt(0)
	s_barrier
	s_setprio 1
	s_waitcnt lgkmcnt(0)
	v_mfma_f32_16x16x32_bf16 v[60:63], v[132:135], v[190:193], v[60:63]
	v_mfma_f32_16x16x32_bf16 v[56:59], v[140:143], v[190:193], v[56:59]
	v_mfma_f32_16x16x32_bf16 v[44:47], v[132:135], v[198:201], v[44:47]
	v_mfma_f32_16x16x32_bf16 v[40:43], v[140:143], v[198:201], v[40:43]
	v_mfma_f32_16x16x32_bf16 v[28:31], v[132:135], v[206:209], v[28:31]
	v_mfma_f32_16x16x32_bf16 v[24:27], v[140:143], v[206:209], v[24:27]
	v_mfma_f32_16x16x32_bf16 v[12:15], v[132:135], v[214:217], v[12:15]
	v_mfma_f32_16x16x32_bf16 v[8:11], v[140:143], v[214:217], v[8:11]
	v_mfma_f32_16x16x32_bf16 v[60:63], v[136:139], v[194:197], v[60:63]
	v_mfma_f32_16x16x32_bf16 v[56:59], v[164:167], v[194:197], v[56:59]
	v_mfma_f32_16x16x32_bf16 v[44:47], v[136:139], v[202:205], v[44:47]
	v_mfma_f32_16x16x32_bf16 v[40:43], v[164:167], v[202:205], v[40:43]
	v_mfma_f32_16x16x32_bf16 v[28:31], v[136:139], v[210:213], v[28:31]
	v_mfma_f32_16x16x32_bf16 v[24:27], v[164:167], v[210:213], v[24:27]
	v_mfma_f32_16x16x32_bf16 v[12:15], v[136:139], v[218:221], v[12:15]
	v_mfma_f32_16x16x32_bf16 v[8:11], v[164:167], v[218:221], v[8:11]
	s_setprio 0
	s_setprio 1
	v_mfma_f32_16x16x32_bf16 v[52:55], v[174:177], v[190:193], v[52:55]
	v_mfma_f32_16x16x32_bf16 v[48:51], v[182:185], v[190:193], v[48:51]
	v_mfma_f32_16x16x32_bf16 v[36:39], v[174:177], v[198:201], v[36:39]
	v_mfma_f32_16x16x32_bf16 v[32:35], v[182:185], v[198:201], v[32:35]
	v_mfma_f32_16x16x32_bf16 v[20:23], v[174:177], v[206:209], v[20:23]
	v_mfma_f32_16x16x32_bf16 v[16:19], v[182:185], v[206:209], v[16:19]
	v_mfma_f32_16x16x32_bf16 v[4:7], v[174:177], v[214:217], v[4:7]
	v_mfma_f32_16x16x32_bf16 v[0:3], v[182:185], v[214:217], v[0:3]
	v_mfma_f32_16x16x32_bf16 v[52:55], v[178:181], v[194:197], v[52:55]
	v_mfma_f32_16x16x32_bf16 v[48:51], v[186:189], v[194:197], v[48:51]
	v_mfma_f32_16x16x32_bf16 v[36:39], v[178:181], v[202:205], v[36:39]
	v_mfma_f32_16x16x32_bf16 v[32:35], v[186:189], v[202:205], v[32:35]
	v_mfma_f32_16x16x32_bf16 v[20:23], v[178:181], v[210:213], v[20:23]
	v_mfma_f32_16x16x32_bf16 v[16:19], v[186:189], v[210:213], v[16:19]
	v_mfma_f32_16x16x32_bf16 v[4:7], v[178:181], v[218:221], v[4:7]
	v_mfma_f32_16x16x32_bf16 v[0:3], v[186:189], v[218:221], v[0:3]
	s_setprio 0
	s_barrier
	s_add_i32 s10, s82, 2
	s_add_u32 s48, s48, 0x100
	s_addc_u32 s49, s49, 0
	s_cmp_gt_u32 s82, 13
	s_mov_b32 s82, s10
	s_cbranch_scc1 .LBB0_721
	s_branch .LBB0_715
.LBB0_714:
	v_add_u32_e32 v164, s72, v171
	v_add_u32_e32 v168, s73, v171
	ds_read_b128 v[132:135], v164
	ds_read_b128 v[136:139], v164 offset:1024
	ds_read_b128 v[140:143], v164 offset:2048
	ds_read_b128 v[164:167], v164 offset:3072
	ds_read_b128 v[174:177], v168
	ds_read_b128 v[178:181], v168 offset:1024
	ds_read_b128 v[182:185], v168 offset:2048
	ds_read_b128 v[186:189], v168 offset:3072
	s_add_u32 s10, s56, 0x100
	s_addc_u32 s85, s57, 0
	s_and_b64 s[56:57], exec, s[54:55]
	s_cselect_b32 s57, s23, s85
	s_cselect_b32 s56, s80, s10
	s_add_u32 s10, s84, 0x100
	s_addc_u32 s83, s83, 0
	s_and_b64 s[54:55], exec, s[54:55]
	s_cselect_b32 s55, s21, s83
	s_cselect_b32 s54, s81, s10
	v_lshl_add_u64 v[168:169], v[128:129], 0, s[48:49]
	s_add_i32 m0, s59, 0xc000
	ds_read_b128 v[190:193], v172
	ds_read_b128 v[194:197], v172 offset:1024
	ds_read_b128 v[198:201], v172 offset:2048
	ds_read_b128 v[202:205], v172 offset:3072
	ds_read_b128 v[206:209], v172 offset:4096
	ds_read_b128 v[210:213], v172 offset:5120
	ds_read_b128 v[214:217], v172 offset:6144
	global_load_lds_dwordx4 v[168:169], off
	v_lshl_add_u64 v[168:169], v[130:131], 0, s[48:49]
	s_add_i32 m0, s59, 0xe000
	ds_read_b128 v[218:221], v172 offset:7168
	global_load_lds_dwordx4 v[168:169], off
	s_waitcnt vmcnt(8)
	s_waitcnt lgkmcnt(0)
	s_barrier
	s_setprio 1
	s_waitcnt lgkmcnt(0)
	v_mfma_f32_16x16x32_bf16 v[124:127], v[132:135], v[190:193], v[124:127]
	v_mfma_f32_16x16x32_bf16 v[120:123], v[140:143], v[190:193], v[120:123]
	v_mfma_f32_16x16x32_bf16 v[108:111], v[132:135], v[198:201], v[108:111]
	v_mfma_f32_16x16x32_bf16 v[104:107], v[140:143], v[198:201], v[104:107]
	v_mfma_f32_16x16x32_bf16 v[92:95], v[132:135], v[206:209], v[92:95]
	v_mfma_f32_16x16x32_bf16 v[88:91], v[140:143], v[206:209], v[88:91]
	v_mfma_f32_16x16x32_bf16 v[76:79], v[132:135], v[214:217], v[76:79]
	v_mfma_f32_16x16x32_bf16 v[72:75], v[140:143], v[214:217], v[72:75]
	v_mfma_f32_16x16x32_bf16 v[124:127], v[136:139], v[194:197], v[124:127]
	v_mfma_f32_16x16x32_bf16 v[120:123], v[164:167], v[194:197], v[120:123]
	v_mfma_f32_16x16x32_bf16 v[108:111], v[136:139], v[202:205], v[108:111]
	v_mfma_f32_16x16x32_bf16 v[104:107], v[164:167], v[202:205], v[104:107]
	v_mfma_f32_16x16x32_bf16 v[92:95], v[136:139], v[210:213], v[92:95]
	v_mfma_f32_16x16x32_bf16 v[88:91], v[164:167], v[210:213], v[88:91]
	v_mfma_f32_16x16x32_bf16 v[76:79], v[136:139], v[218:221], v[76:79]
	v_mfma_f32_16x16x32_bf16 v[72:75], v[164:167], v[218:221], v[72:75]
	s_setprio 0
	s_setprio 1
	v_mfma_f32_16x16x32_bf16 v[116:119], v[174:177], v[190:193], v[116:119]
	v_mfma_f32_16x16x32_bf16 v[112:115], v[182:185], v[190:193], v[112:115]
	v_mfma_f32_16x16x32_bf16 v[100:103], v[174:177], v[198:201], v[100:103]
	v_mfma_f32_16x16x32_bf16 v[96:99], v[182:185], v[198:201], v[96:99]
	v_mfma_f32_16x16x32_bf16 v[84:87], v[174:177], v[206:209], v[84:87]
	v_mfma_f32_16x16x32_bf16 v[80:83], v[182:185], v[206:209], v[80:83]
	v_mfma_f32_16x16x32_bf16 v[68:71], v[174:177], v[214:217], v[68:71]
	v_mfma_f32_16x16x32_bf16 v[64:67], v[182:185], v[214:217], v[64:67]
	v_mfma_f32_16x16x32_bf16 v[116:119], v[178:181], v[194:197], v[116:119]
	v_mfma_f32_16x16x32_bf16 v[112:115], v[186:189], v[194:197], v[112:115]
	v_mfma_f32_16x16x32_bf16 v[100:103], v[178:181], v[202:205], v[100:103]
	v_mfma_f32_16x16x32_bf16 v[96:99], v[186:189], v[202:205], v[96:99]
	v_mfma_f32_16x16x32_bf16 v[84:87], v[178:181], v[210:213], v[84:87]
	v_mfma_f32_16x16x32_bf16 v[80:83], v[186:189], v[210:213], v[80:83]
	v_mfma_f32_16x16x32_bf16 v[68:71], v[178:181], v[218:221], v[68:71]
	v_mfma_f32_16x16x32_bf16 v[64:67], v[186:189], v[218:221], v[64:67]
	s_setprio 0
	s_barrier
	s_add_i32 s10, s72, s58
	s_mov_b32 m0, s10
	ds_read_b128 v[190:193], v172 offset:16384
	ds_read_b128 v[194:197], v172 offset:17408
	ds_read_b128 v[198:201], v172 offset:18432
	global_load_lds_dwordx4 v146, s[54:55]
	s_add_i32 m0, s10, 0x2000
	ds_read_b128 v[202:205], v172 offset:19456
	global_load_lds_dwordx4 v150, s[54:55]
	s_add_u32 s54, s54, 0x40000
	s_addc_u32 s55, s55, 0
	s_add_i32 s10, s73, s58
	s_mov_b32 m0, s10
	ds_read_b128 v[206:209], v172 offset:20480
	global_load_lds_dwordx4 v146, s[54:55]
	s_add_i32 m0, s10, 0x2000
	ds_read_b128 v[210:213], v172 offset:21504
	global_load_lds_dwordx4 v150, s[54:55]
	s_mov_b32 m0, s59
	ds_read_b128 v[214:217], v172 offset:22528
	global_load_lds_dwordx4 v144, s[56:57]
	s_mov_b32 m0, s60
	ds_read_b128 v[218:221], v172 offset:23552
	global_load_lds_dwordx4 v148, s[56:57]
	s_waitcnt vmcnt(8)
	s_waitcnt lgkmcnt(0)
	s_barrier
	s_setprio 1
	s_waitcnt lgkmcnt(0)
	v_mfma_f32_16x16x32_bf16 v[60:63], v[132:135], v[190:193], v[60:63]
	v_mfma_f32_16x16x32_bf16 v[56:59], v[140:143], v[190:193], v[56:59]
	v_mfma_f32_16x16x32_bf16 v[44:47], v[132:135], v[198:201], v[44:47]
	v_mfma_f32_16x16x32_bf16 v[40:43], v[140:143], v[198:201], v[40:43]
	v_mfma_f32_16x16x32_bf16 v[28:31], v[132:135], v[206:209], v[28:31]
	v_mfma_f32_16x16x32_bf16 v[24:27], v[140:143], v[206:209], v[24:27]
	v_mfma_f32_16x16x32_bf16 v[12:15], v[132:135], v[214:217], v[12:15]
	v_mfma_f32_16x16x32_bf16 v[8:11], v[140:143], v[214:217], v[8:11]
	v_mfma_f32_16x16x32_bf16 v[60:63], v[136:139], v[194:197], v[60:63]
	v_mfma_f32_16x16x32_bf16 v[56:59], v[164:167], v[194:197], v[56:59]
	v_mfma_f32_16x16x32_bf16 v[44:47], v[136:139], v[202:205], v[44:47]
	v_mfma_f32_16x16x32_bf16 v[40:43], v[164:167], v[202:205], v[40:43]
	v_mfma_f32_16x16x32_bf16 v[28:31], v[136:139], v[210:213], v[28:31]
	v_mfma_f32_16x16x32_bf16 v[24:27], v[164:167], v[210:213], v[24:27]
	v_mfma_f32_16x16x32_bf16 v[12:15], v[136:139], v[218:221], v[12:15]
	v_mfma_f32_16x16x32_bf16 v[8:11], v[164:167], v[218:221], v[8:11]
	s_setprio 0
	s_setprio 1
	v_mfma_f32_16x16x32_bf16 v[52:55], v[174:177], v[190:193], v[52:55]
	v_mfma_f32_16x16x32_bf16 v[48:51], v[182:185], v[190:193], v[48:51]
	v_mfma_f32_16x16x32_bf16 v[36:39], v[174:177], v[198:201], v[36:39]
	v_mfma_f32_16x16x32_bf16 v[32:35], v[182:185], v[198:201], v[32:35]
	v_mfma_f32_16x16x32_bf16 v[20:23], v[174:177], v[206:209], v[20:23]
	v_mfma_f32_16x16x32_bf16 v[16:19], v[182:185], v[206:209], v[16:19]
	v_mfma_f32_16x16x32_bf16 v[4:7], v[174:177], v[214:217], v[4:7]
	v_mfma_f32_16x16x32_bf16 v[0:3], v[182:185], v[214:217], v[0:3]
	v_mfma_f32_16x16x32_bf16 v[52:55], v[178:181], v[194:197], v[52:55]
	v_mfma_f32_16x16x32_bf16 v[48:51], v[186:189], v[194:197], v[48:51]
	v_mfma_f32_16x16x32_bf16 v[36:39], v[178:181], v[202:205], v[36:39]
	v_mfma_f32_16x16x32_bf16 v[32:35], v[186:189], v[202:205], v[32:35]
	v_mfma_f32_16x16x32_bf16 v[20:23], v[178:181], v[210:213], v[20:23]
	v_mfma_f32_16x16x32_bf16 v[16:19], v[186:189], v[210:213], v[16:19]
	v_mfma_f32_16x16x32_bf16 v[4:7], v[178:181], v[218:221], v[4:7]
	v_mfma_f32_16x16x32_bf16 v[0:3], v[186:189], v[218:221], v[0:3]
	s_setprio 0
	s_barrier
	s_add_i32 s10, 0, 0x18000
	s_add_i32 s83, 0, 0x1c000
	v_add_u32_e32 v164, s10, v171
	v_add_u32_e32 v168, s83, v171
	ds_read_b128 v[132:135], v164
	ds_read_b128 v[136:139], v164 offset:1024
	ds_read_b128 v[140:143], v164 offset:2048
	ds_read_b128 v[164:167], v164 offset:3072
	ds_read_b128 v[174:177], v168
	ds_read_b128 v[178:181], v168 offset:1024
	ds_read_b128 v[182:185], v168 offset:2048
	ds_read_b128 v[186:189], v168 offset:3072
	s_add_u32 s54, s56, 0x40000
	s_addc_u32 s55, s57, 0
	s_mov_b32 m0, s61
	ds_read_b128 v[190:193], v172 offset:32768
	ds_read_b128 v[194:197], v172 offset:33792
	ds_read_b128 v[198:201], v172 offset:34816
	ds_read_b128 v[202:205], v172 offset:35840
	ds_read_b128 v[206:209], v172 offset:36864
	ds_read_b128 v[210:213], v172 offset:37888
	ds_read_b128 v[214:217], v172 offset:38912
	global_load_lds_dwordx4 v144, s[54:55]
	s_mov_b32 m0, s62
	ds_read_b128 v[218:221], v172 offset:39936
	global_load_lds_dwordx4 v148, s[54:55]
	s_waitcnt vmcnt(8)
	s_waitcnt lgkmcnt(0)
	s_barrier
	s_setprio 1
	s_waitcnt lgkmcnt(0)
	v_mfma_f32_16x16x32_bf16 v[124:127], v[132:135], v[190:193], v[124:127]
	v_mfma_f32_16x16x32_bf16 v[120:123], v[140:143], v[190:193], v[120:123]
	v_mfma_f32_16x16x32_bf16 v[108:111], v[132:135], v[198:201], v[108:111]
	v_mfma_f32_16x16x32_bf16 v[104:107], v[140:143], v[198:201], v[104:107]
	v_mfma_f32_16x16x32_bf16 v[92:95], v[132:135], v[206:209], v[92:95]
	v_mfma_f32_16x16x32_bf16 v[88:91], v[140:143], v[206:209], v[88:91]
	v_mfma_f32_16x16x32_bf16 v[76:79], v[132:135], v[214:217], v[76:79]
	v_mfma_f32_16x16x32_bf16 v[72:75], v[140:143], v[214:217], v[72:75]
	v_mfma_f32_16x16x32_bf16 v[124:127], v[136:139], v[194:197], v[124:127]
	v_mfma_f32_16x16x32_bf16 v[120:123], v[164:167], v[194:197], v[120:123]
	v_mfma_f32_16x16x32_bf16 v[108:111], v[136:139], v[202:205], v[108:111]
	v_mfma_f32_16x16x32_bf16 v[104:107], v[164:167], v[202:205], v[104:107]
	v_mfma_f32_16x16x32_bf16 v[92:95], v[136:139], v[210:213], v[92:95]
	v_mfma_f32_16x16x32_bf16 v[88:91], v[164:167], v[210:213], v[88:91]
	v_mfma_f32_16x16x32_bf16 v[76:79], v[136:139], v[218:221], v[76:79]
	v_mfma_f32_16x16x32_bf16 v[72:75], v[164:167], v[218:221], v[72:75]
	s_setprio 0
	s_setprio 1
	v_mfma_f32_16x16x32_bf16 v[116:119], v[174:177], v[190:193], v[116:119]
	v_mfma_f32_16x16x32_bf16 v[112:115], v[182:185], v[190:193], v[112:115]
	v_mfma_f32_16x16x32_bf16 v[100:103], v[174:177], v[198:201], v[100:103]
	v_mfma_f32_16x16x32_bf16 v[96:99], v[182:185], v[198:201], v[96:99]
	v_mfma_f32_16x16x32_bf16 v[84:87], v[174:177], v[206:209], v[84:87]
	v_mfma_f32_16x16x32_bf16 v[80:83], v[182:185], v[206:209], v[80:83]
	v_mfma_f32_16x16x32_bf16 v[68:71], v[174:177], v[214:217], v[68:71]
	v_mfma_f32_16x16x32_bf16 v[64:67], v[182:185], v[214:217], v[64:67]
	v_mfma_f32_16x16x32_bf16 v[116:119], v[178:181], v[194:197], v[116:119]
	v_mfma_f32_16x16x32_bf16 v[112:115], v[186:189], v[194:197], v[112:115]
	v_mfma_f32_16x16x32_bf16 v[100:103], v[178:181], v[202:205], v[100:103]
	v_mfma_f32_16x16x32_bf16 v[96:99], v[186:189], v[202:205], v[96:99]
	v_mfma_f32_16x16x32_bf16 v[84:87], v[178:181], v[210:213], v[84:87]
	v_mfma_f32_16x16x32_bf16 v[80:83], v[186:189], v[210:213], v[80:83]
	v_mfma_f32_16x16x32_bf16 v[68:71], v[178:181], v[218:221], v[68:71]
	v_mfma_f32_16x16x32_bf16 v[64:67], v[186:189], v[218:221], v[64:67]
	s_setprio 0
	s_barrier
	s_add_i32 s10, s10, s58
	s_mov_b32 m0, s10
	ds_read_b128 v[190:193], v172 offset:49152
	ds_read_b128 v[194:197], v172 offset:50176
	ds_read_b128 v[198:201], v172 offset:51200
	global_load_lds_dwordx4 v146, s[52:53]
	s_add_i32 m0, s10, 0x2000
	ds_read_b128 v[202:205], v172 offset:52224
	global_load_lds_dwordx4 v150, s[52:53]
	s_add_u32 s52, s52, 0x40000
	s_addc_u32 s53, s53, 0
	s_add_i32 s10, s83, s58
	s_mov_b32 m0, s10
	ds_read_b128 v[206:209], v172 offset:53248
	global_load_lds_dwordx4 v146, s[52:53]
	s_add_i32 m0, s10, 0x2000
	ds_read_b128 v[210:213], v172 offset:54272
	global_load_lds_dwordx4 v150, s[52:53]
	s_mov_b32 m0, s68
	ds_read_b128 v[214:217], v172 offset:55296
	global_load_lds_dwordx4 v144, s[50:51]
	s_mov_b32 m0, s69
	ds_read_b128 v[218:221], v172 offset:56320
	global_load_lds_dwordx4 v148, s[50:51]
	s_waitcnt vmcnt(8)
	s_waitcnt lgkmcnt(0)
	s_barrier
	s_setprio 1
	s_waitcnt lgkmcnt(0)
	v_mfma_f32_16x16x32_bf16 v[60:63], v[132:135], v[190:193], v[60:63]
	v_mfma_f32_16x16x32_bf16 v[56:59], v[140:143], v[190:193], v[56:59]
	v_mfma_f32_16x16x32_bf16 v[44:47], v[132:135], v[198:201], v[44:47]
	v_mfma_f32_16x16x32_bf16 v[40:43], v[140:143], v[198:201], v[40:43]
	v_mfma_f32_16x16x32_bf16 v[28:31], v[132:135], v[206:209], v[28:31]
	v_mfma_f32_16x16x32_bf16 v[24:27], v[140:143], v[206:209], v[24:27]
	v_mfma_f32_16x16x32_bf16 v[12:15], v[132:135], v[214:217], v[12:15]
	v_mfma_f32_16x16x32_bf16 v[8:11], v[140:143], v[214:217], v[8:11]
	v_mfma_f32_16x16x32_bf16 v[60:63], v[136:139], v[194:197], v[60:63]
	v_mfma_f32_16x16x32_bf16 v[56:59], v[164:167], v[194:197], v[56:59]
	v_mfma_f32_16x16x32_bf16 v[44:47], v[136:139], v[202:205], v[44:47]
	v_mfma_f32_16x16x32_bf16 v[40:43], v[164:167], v[202:205], v[40:43]
	v_mfma_f32_16x16x32_bf16 v[28:31], v[136:139], v[210:213], v[28:31]
	v_mfma_f32_16x16x32_bf16 v[24:27], v[164:167], v[210:213], v[24:27]
	v_mfma_f32_16x16x32_bf16 v[12:15], v[136:139], v[218:221], v[12:15]
	v_mfma_f32_16x16x32_bf16 v[8:11], v[164:167], v[218:221], v[8:11]
	s_setprio 0
	s_setprio 1
	v_mfma_f32_16x16x32_bf16 v[52:55], v[174:177], v[190:193], v[52:55]
	v_mfma_f32_16x16x32_bf16 v[48:51], v[182:185], v[190:193], v[48:51]
	v_mfma_f32_16x16x32_bf16 v[36:39], v[174:177], v[198:201], v[36:39]
	v_mfma_f32_16x16x32_bf16 v[32:35], v[182:185], v[198:201], v[32:35]
	v_mfma_f32_16x16x32_bf16 v[20:23], v[174:177], v[206:209], v[20:23]
	v_mfma_f32_16x16x32_bf16 v[16:19], v[182:185], v[206:209], v[16:19]
	v_mfma_f32_16x16x32_bf16 v[4:7], v[174:177], v[214:217], v[4:7]
	v_mfma_f32_16x16x32_bf16 v[0:3], v[182:185], v[214:217], v[0:3]
	v_mfma_f32_16x16x32_bf16 v[52:55], v[178:181], v[194:197], v[52:55]
	v_mfma_f32_16x16x32_bf16 v[48:51], v[186:189], v[194:197], v[48:51]
	v_mfma_f32_16x16x32_bf16 v[36:39], v[178:181], v[202:205], v[36:39]
	v_mfma_f32_16x16x32_bf16 v[32:35], v[186:189], v[202:205], v[32:35]
	v_mfma_f32_16x16x32_bf16 v[20:23], v[178:181], v[210:213], v[20:23]
	v_mfma_f32_16x16x32_bf16 v[16:19], v[186:189], v[210:213], v[16:19]
	v_mfma_f32_16x16x32_bf16 v[4:7], v[178:181], v[218:221], v[4:7]
	v_mfma_f32_16x16x32_bf16 v[0:3], v[186:189], v[218:221], v[0:3]
	s_setprio 0
	s_barrier
	s_add_i32 s10, s82, 2
	s_add_u32 s48, s48, 0x100
	s_addc_u32 s49, s49, 0
	s_cmp_gt_u32 s82, 13
	s_mov_b32 s82, s10
	s_cbranch_scc1 .LBB0_721

.LBB0_805:
	s_add_u32 s27, s61, s4
	s_addc_u32 s72, s62, s5
	s_add_u32 s73, s63, s6
	s_addc_u32 s78, s64, s7
	s_ashr_i32 s21, s20, 31
	s_lshl_b64 s[4:5], s[20:21], 19
	s_add_u32 s22, s40, s4
	s_addc_u32 s23, s41, s5
	s_and_b64 s[6:7], s[0:1], exec
	s_cselect_b32 s21, s23, s31
	s_cselect_b32 s79, s22, s30
	s_ashr_i32 s19, s18, 31
	s_lshl_b64 s[6:7], s[18:19], 19
	s_add_u32 s24, s42, s6
	s_addc_u32 s25, s43, s7
	s_and_b64 s[36:37], s[0:1], exec
	s_cselect_b32 s19, s25, s29
	s_cselect_b32 s80, s24, s28
	s_add_u32 s36, s79, 0x80
	s_addc_u32 s37, s21, 0
	s_add_u32 s38, s80, 0x80
	s_addc_u32 s39, s19, 0
	v_lshl_add_u64 v[148:149], s[30:31], 0, v[140:141]
	v_lshl_add_u64 v[150:151], s[30:31], 0, v[142:143]
	s_mov_b32 s81, 0
	s_mov_b64 s[44:45], 0
	s_cmpk_eq_i32 s44, 0x700
	s_cselect_b64 s[50:51], -1, 0
	s_add_u32 s52, s30, s44
	s_addc_u32 s53, s31, s45
	s_add_u32 s83, s28, s44
	s_addc_u32 s82, s29, s45
	s_add_u32 s46, s52, 0x180
	s_addc_u32 s47, s53, 0
	s_add_u32 s48, s83, 0x180
	s_addc_u32 s49, s82, 0
	s_cmpk_eq_i32 s44, 0x700
	s_cselect_b32 s46, s36, s46
	s_cselect_b32 s47, s37, s47
	s_cselect_b32 s48, s38, s48
	s_cselect_b32 s49, s39, s49
	v_add_u32_e32 v152, s68, v157
	ds_read_b128 v[166:169], v152
	ds_read_b128 v[170:173], v152 offset:1024
	ds_read_b128 v[174:177], v152 offset:2048
	ds_read_b128 v[178:181], v152 offset:3072
	v_add_u32_e32 v152, s69, v157
	ds_read_b128 v[182:185], v152
	ds_read_b128 v[186:189], v152 offset:1024
	ds_read_b128 v[190:193], v152 offset:2048
	ds_read_b128 v[194:197], v152 offset:3072
	s_add_u32 s8, s52, 0x100
	s_addc_u32 s84, s53, 0
	s_and_b64 s[52:53], exec, s[50:51]
	s_cselect_b32 s53, s21, s84
	s_cselect_b32 s52, s79, s8
	s_add_u32 s8, s83, 0x100
	s_addc_u32 s82, s82, 0
	s_and_b64 s[50:51], exec, s[50:51]
	s_cselect_b32 s51, s19, s82
	s_cselect_b32 s50, s80, s8
	v_lshl_add_u64 v[154:155], v[148:149], 0, s[44:45]
	s_add_i32 m0, s57, 0xc000
	ds_read_b128 v[198:201], v161
	ds_read_b128 v[202:205], v161 offset:1024
	ds_read_b128 v[206:209], v161 offset:2048
	ds_read_b128 v[210:213], v161 offset:3072
	ds_read_b128 v[214:217], v161 offset:4096
	ds_read_b128 v[218:221], v161 offset:5120
	ds_read_b128 v[222:225], v161 offset:6144
	global_load_lds_dwordx4 v[154:155], off
	v_lshl_add_u64 v[154:155], v[150:151], 0, s[44:45]
	s_add_i32 m0, s57, 0xe000
	ds_read_b128 v[226:229], v161 offset:7168
	global_load_lds_dwordx4 v[154:155], off
	s_waitcnt vmcnt(8)
	s_waitcnt lgkmcnt(0)
	s_barrier
	s_setprio 1
	s_waitcnt lgkmcnt(0)
	v_mfma_f32_16x16x32_bf16 v[124:127], v[166:169], v[198:201], 0
	v_mfma_f32_16x16x32_bf16 v[120:123], v[174:177], v[198:201], 0
	v_mfma_f32_16x16x32_bf16 v[108:111], v[166:169], v[206:209], 0
	v_mfma_f32_16x16x32_bf16 v[104:107], v[174:177], v[206:209], 0
	v_mfma_f32_16x16x32_bf16 v[92:95], v[166:169], v[214:217], 0
	v_mfma_f32_16x16x32_bf16 v[88:91], v[174:177], v[214:217], 0
	v_mfma_f32_16x16x32_bf16 v[76:79], v[166:169], v[222:225], 0
	v_mfma_f32_16x16x32_bf16 v[72:75], v[174:177], v[222:225], 0
	v_mfma_f32_16x16x32_bf16 v[124:127], v[170:173], v[202:205], v[124:127]
	v_mfma_f32_16x16x32_bf16 v[120:123], v[178:181], v[202:205], v[120:123]
	v_mfma_f32_16x16x32_bf16 v[108:111], v[170:173], v[210:213], v[108:111]
	v_mfma_f32_16x16x32_bf16 v[104:107], v[178:181], v[210:213], v[104:107]
	v_mfma_f32_16x16x32_bf16 v[92:95], v[170:173], v[218:221], v[92:95]
	v_mfma_f32_16x16x32_bf16 v[88:91], v[178:181], v[218:221], v[88:91]
	v_mfma_f32_16x16x32_bf16 v[76:79], v[170:173], v[226:229], v[76:79]
	v_mfma_f32_16x16x32_bf16 v[72:75], v[178:181], v[226:229], v[72:75]
	s_setprio 0
	s_setprio 1
	v_mfma_f32_16x16x32_bf16 v[116:119], v[182:185], v[198:201], 0
	v_mfma_f32_16x16x32_bf16 v[112:115], v[190:193], v[198:201], 0
	v_mfma_f32_16x16x32_bf16 v[100:103], v[182:185], v[206:209], 0
	v_mfma_f32_16x16x32_bf16 v[96:99], v[190:193], v[206:209], 0
	v_mfma_f32_16x16x32_bf16 v[84:87], v[182:185], v[214:217], 0
	v_mfma_f32_16x16x32_bf16 v[80:83], v[190:193], v[214:217], 0
	v_mfma_f32_16x16x32_bf16 v[68:71], v[182:185], v[222:225], 0
	v_mfma_f32_16x16x32_bf16 v[64:67], v[190:193], v[222:225], 0
	v_mfma_f32_16x16x32_bf16 v[116:119], v[186:189], v[202:205], v[116:119]
	v_mfma_f32_16x16x32_bf16 v[112:115], v[194:197], v[202:205], v[112:115]
	v_mfma_f32_16x16x32_bf16 v[100:103], v[186:189], v[210:213], v[100:103]
	v_mfma_f32_16x16x32_bf16 v[96:99], v[194:197], v[210:213], v[96:99]
	v_mfma_f32_16x16x32_bf16 v[84:87], v[186:189], v[218:221], v[84:87]
	v_mfma_f32_16x16x32_bf16 v[80:83], v[194:197], v[218:221], v[80:83]
	v_mfma_f32_16x16x32_bf16 v[68:71], v[186:189], v[226:229], v[68:71]
	v_mfma_f32_16x16x32_bf16 v[64:67], v[194:197], v[226:229], v[64:67]
	s_setprio 0
	s_barrier
	s_add_i32 s8, s68, s54
	s_mov_b32 m0, s8
	ds_read_b128 v[198:201], v161 offset:16384
	ds_read_b128 v[202:205], v161 offset:17408
	ds_read_b128 v[206:209], v161 offset:18432
	global_load_lds_dwordx4 v128, s[50:51]
	s_add_i32 m0, s8, 0x2000
	ds_read_b128 v[210:213], v161 offset:19456
	global_load_lds_dwordx4 v130, s[50:51]
	s_add_u32 s50, s50, 0x40000
	s_addc_u32 s51, s51, 0
	s_add_i32 s8, s69, s54
	s_mov_b32 m0, s8
	ds_read_b128 v[214:217], v161 offset:20480
	global_load_lds_dwordx4 v128, s[50:51]
	s_add_i32 m0, s8, 0x2000
	ds_read_b128 v[218:221], v161 offset:21504
	global_load_lds_dwordx4 v130, s[50:51]
	s_mov_b32 m0, s57
	ds_read_b128 v[222:225], v161 offset:22528
	global_load_lds_dwordx4 v134, s[52:53]
	s_mov_b32 m0, s58
	ds_read_b128 v[226:229], v161 offset:23552
	global_load_lds_dwordx4 v132, s[52:53]
	s_waitcnt vmcnt(8)
	s_waitcnt lgkmcnt(0)
	s_barrier
	s_setprio 1
	s_waitcnt lgkmcnt(0)
	v_mfma_f32_16x16x32_bf16 v[60:63], v[166:169], v[198:201], 0
	v_mfma_f32_16x16x32_bf16 v[56:59], v[174:177], v[198:201], 0
	v_mfma_f32_16x16x32_bf16 v[44:47], v[166:169], v[206:209], 0
	v_mfma_f32_16x16x32_bf16 v[40:43], v[174:177], v[206:209], 0
	v_mfma_f32_16x16x32_bf16 v[28:31], v[166:169], v[214:217], 0
	v_mfma_f32_16x16x32_bf16 v[24:27], v[174:177], v[214:217], 0
	v_mfma_f32_16x16x32_bf16 v[12:15], v[166:169], v[222:225], 0
	v_mfma_f32_16x16x32_bf16 v[8:11], v[174:177], v[222:225], 0
	v_mfma_f32_16x16x32_bf16 v[60:63], v[170:173], v[202:205], v[60:63]
	v_mfma_f32_16x16x32_bf16 v[56:59], v[178:181], v[202:205], v[56:59]
	v_mfma_f32_16x16x32_bf16 v[44:47], v[170:173], v[210:213], v[44:47]
	v_mfma_f32_16x16x32_bf16 v[40:43], v[178:181], v[210:213], v[40:43]
	v_mfma_f32_16x16x32_bf16 v[28:31], v[170:173], v[218:221], v[28:31]
	v_mfma_f32_16x16x32_bf16 v[24:27], v[178:181], v[218:221], v[24:27]
	v_mfma_f32_16x16x32_bf16 v[12:15], v[170:173], v[226:229], v[12:15]
	v_mfma_f32_16x16x32_bf16 v[8:11], v[178:181], v[226:229], v[8:11]
	s_setprio 0
	s_setprio 1
	v_mfma_f32_16x16x32_bf16 v[52:55], v[182:185], v[198:201], 0
	v_mfma_f32_16x16x32_bf16 v[48:51], v[190:193], v[198:201], 0
	v_mfma_f32_16x16x32_bf16 v[36:39], v[182:185], v[206:209], 0
	v_mfma_f32_16x16x32_bf16 v[32:35], v[190:193], v[206:209], 0
	v_mfma_f32_16x16x32_bf16 v[20:23], v[182:185], v[214:217], 0
	v_mfma_f32_16x16x32_bf16 v[16:19], v[190:193], v[214:217], 0
	v_mfma_f32_16x16x32_bf16 v[4:7], v[182:185], v[222:225], 0
	v_mfma_f32_16x16x32_bf16 v[0:3], v[190:193], v[222:225], 0
	v_mfma_f32_16x16x32_bf16 v[52:55], v[186:189], v[202:205], v[52:55]
	v_mfma_f32_16x16x32_bf16 v[48:51], v[194:197], v[202:205], v[48:51]
	v_mfma_f32_16x16x32_bf16 v[36:39], v[186:189], v[210:213], v[36:39]
	v_mfma_f32_16x16x32_bf16 v[32:35], v[194:197], v[210:213], v[32:35]
	v_mfma_f32_16x16x32_bf16 v[20:23], v[186:189], v[218:221], v[20:23]
	v_mfma_f32_16x16x32_bf16 v[16:19], v[194:197], v[218:221], v[16:19]
	v_mfma_f32_16x16x32_bf16 v[4:7], v[186:189], v[226:229], v[4:7]
	v_mfma_f32_16x16x32_bf16 v[0:3], v[194:197], v[226:229], v[0:3]
	s_setprio 0
	s_barrier
	s_add_i32 s8, 0, 0x18000
	v_add_u32_e32 v152, s8, v157
	s_add_i32 s82, 0, 0x1c000
	ds_read_b128 v[166:169], v152
	ds_read_b128 v[170:173], v152 offset:1024
	ds_read_b128 v[174:177], v152 offset:2048
	ds_read_b128 v[178:181], v152 offset:3072
	v_add_u32_e32 v152, s82, v157
	ds_read_b128 v[182:185], v152
	ds_read_b128 v[186:189], v152 offset:1024
	ds_read_b128 v[190:193], v152 offset:2048
	ds_read_b128 v[194:197], v152 offset:3072
	s_add_u32 s50, s52, 0x40000
	s_addc_u32 s51, s53, 0
	s_mov_b32 m0, s59
	ds_read_b128 v[198:201], v161 offset:32768
	ds_read_b128 v[202:205], v161 offset:33792
	ds_read_b128 v[206:209], v161 offset:34816
	ds_read_b128 v[210:213], v161 offset:35840
	ds_read_b128 v[214:217], v161 offset:36864
	ds_read_b128 v[218:221], v161 offset:37888
	ds_read_b128 v[222:225], v161 offset:38912
	global_load_lds_dwordx4 v134, s[50:51]
	s_mov_b32 m0, s60
	ds_read_b128 v[226:229], v161 offset:39936
	global_load_lds_dwordx4 v132, s[50:51]
	s_waitcnt vmcnt(8)
	s_waitcnt lgkmcnt(0)
	s_barrier
	s_setprio 1
	s_waitcnt lgkmcnt(0)
	v_mfma_f32_16x16x32_bf16 v[124:127], v[166:169], v[198:201], v[124:127]
	v_mfma_f32_16x16x32_bf16 v[120:123], v[174:177], v[198:201], v[120:123]
	v_mfma_f32_16x16x32_bf16 v[108:111], v[166:169], v[206:209], v[108:111]
	v_mfma_f32_16x16x32_bf16 v[104:107], v[174:177], v[206:209], v[104:107]
	v_mfma_f32_16x16x32_bf16 v[92:95], v[166:169], v[214:217], v[92:95]
	v_mfma_f32_16x16x32_bf16 v[88:91], v[174:177], v[214:217], v[88:91]
	v_mfma_f32_16x16x32_bf16 v[76:79], v[166:169], v[222:225], v[76:79]
	v_mfma_f32_16x16x32_bf16 v[72:75], v[174:177], v[222:225], v[72:75]
	v_mfma_f32_16x16x32_bf16 v[124:127], v[170:173], v[202:205], v[124:127]
	v_mfma_f32_16x16x32_bf16 v[120:123], v[178:181], v[202:205], v[120:123]
	v_mfma_f32_16x16x32_bf16 v[108:111], v[170:173], v[210:213], v[108:111]
	v_mfma_f32_16x16x32_bf16 v[104:107], v[178:181], v[210:213], v[104:107]
	v_mfma_f32_16x16x32_bf16 v[92:95], v[170:173], v[218:221], v[92:95]
	v_mfma_f32_16x16x32_bf16 v[88:91], v[178:181], v[218:221], v[88:91]
	v_mfma_f32_16x16x32_bf16 v[76:79], v[170:173], v[226:229], v[76:79]
	v_mfma_f32_16x16x32_bf16 v[72:75], v[178:181], v[226:229], v[72:75]
	s_setprio 0
	s_setprio 1
	v_mfma_f32_16x16x32_bf16 v[116:119], v[182:185], v[198:201], v[116:119]
	v_mfma_f32_16x16x32_bf16 v[112:115], v[190:193], v[198:201], v[112:115]
	v_mfma_f32_16x16x32_bf16 v[100:103], v[182:185], v[206:209], v[100:103]
	v_mfma_f32_16x16x32_bf16 v[96:99], v[190:193], v[206:209], v[96:99]
	v_mfma_f32_16x16x32_bf16 v[84:87], v[182:185], v[214:217], v[84:87]
	v_mfma_f32_16x16x32_bf16 v[80:83], v[190:193], v[214:217], v[80:83]
	v_mfma_f32_16x16x32_bf16 v[68:71], v[182:185], v[222:225], v[68:71]
	v_mfma_f32_16x16x32_bf16 v[64:67], v[190:193], v[222:225], v[64:67]
	v_mfma_f32_16x16x32_bf16 v[116:119], v[186:189], v[202:205], v[116:119]
	v_mfma_f32_16x16x32_bf16 v[112:115], v[194:197], v[202:205], v[112:115]
	v_mfma_f32_16x16x32_bf16 v[100:103], v[186:189], v[210:213], v[100:103]
	v_mfma_f32_16x16x32_bf16 v[96:99], v[194:197], v[210:213], v[96:99]
	v_mfma_f32_16x16x32_bf16 v[84:87], v[186:189], v[218:221], v[84:87]
	v_mfma_f32_16x16x32_bf16 v[80:83], v[194:197], v[218:221], v[80:83]
	v_mfma_f32_16x16x32_bf16 v[68:71], v[186:189], v[226:229], v[68:71]
	v_mfma_f32_16x16x32_bf16 v[64:67], v[194:197], v[226:229], v[64:67]
	s_setprio 0
	s_barrier
	s_add_i32 s8, s8, s54
	s_mov_b32 m0, s8
	ds_read_b128 v[198:201], v161 offset:49152
	ds_read_b128 v[202:205], v161 offset:50176
	ds_read_b128 v[206:209], v161 offset:51200
	global_load_lds_dwordx4 v128, s[48:49]
	s_add_i32 m0, s8, 0x2000
	ds_read_b128 v[210:213], v161 offset:52224
	global_load_lds_dwordx4 v130, s[48:49]
	s_add_u32 s48, s48, 0x40000
	s_addc_u32 s49, s49, 0
	s_add_i32 s8, s82, s54
	s_mov_b32 m0, s8
	ds_read_b128 v[214:217], v161 offset:53248
	global_load_lds_dwordx4 v128, s[48:49]
	s_add_i32 m0, s8, 0x2000
	ds_read_b128 v[218:221], v161 offset:54272
	global_load_lds_dwordx4 v130, s[48:49]
	s_mov_b32 m0, s65
	ds_read_b128 v[222:225], v161 offset:55296
	global_load_lds_dwordx4 v134, s[46:47]
	s_mov_b32 m0, s66
	ds_read_b128 v[226:229], v161 offset:56320
	global_load_lds_dwordx4 v132, s[46:47]
	s_waitcnt vmcnt(8)
	s_waitcnt lgkmcnt(0)
	s_barrier
	s_setprio 1
	s_waitcnt lgkmcnt(0)
	v_mfma_f32_16x16x32_bf16 v[60:63], v[166:169], v[198:201], v[60:63]
	v_mfma_f32_16x16x32_bf16 v[56:59], v[174:177], v[198:201], v[56:59]
	v_mfma_f32_16x16x32_bf16 v[44:47], v[166:169], v[206:209], v[44:47]
	v_mfma_f32_16x16x32_bf16 v[40:43], v[174:177], v[206:209], v[40:43]
	v_mfma_f32_16x16x32_bf16 v[28:31], v[166:169], v[214:217], v[28:31]
	v_mfma_f32_16x16x32_bf16 v[24:27], v[174:177], v[214:217], v[24:27]
	v_mfma_f32_16x16x32_bf16 v[12:15], v[166:169], v[222:225], v[12:15]
	v_mfma_f32_16x16x32_bf16 v[8:11], v[174:177], v[222:225], v[8:11]
	v_mfma_f32_16x16x32_bf16 v[60:63], v[170:173], v[202:205], v[60:63]
	v_mfma_f32_16x16x32_bf16 v[56:59], v[178:181], v[202:205], v[56:59]
	v_mfma_f32_16x16x32_bf16 v[44:47], v[170:173], v[210:213], v[44:47]
	v_mfma_f32_16x16x32_bf16 v[40:43], v[178:181], v[210:213], v[40:43]
	v_mfma_f32_16x16x32_bf16 v[28:31], v[170:173], v[218:221], v[28:31]
	v_mfma_f32_16x16x32_bf16 v[24:27], v[178:181], v[218:221], v[24:27]
	v_mfma_f32_16x16x32_bf16 v[12:15], v[170:173], v[226:229], v[12:15]
	v_mfma_f32_16x16x32_bf16 v[8:11], v[178:181], v[226:229], v[8:11]
	s_setprio 0
	s_setprio 1
	v_mfma_f32_16x16x32_bf16 v[52:55], v[182:185], v[198:201], v[52:55]
	v_mfma_f32_16x16x32_bf16 v[48:51], v[190:193], v[198:201], v[48:51]
	v_mfma_f32_16x16x32_bf16 v[36:39], v[182:185], v[206:209], v[36:39]
	v_mfma_f32_16x16x32_bf16 v[32:35], v[190:193], v[206:209], v[32:35]
	v_mfma_f32_16x16x32_bf16 v[20:23], v[182:185], v[214:217], v[20:23]
	v_mfma_f32_16x16x32_bf16 v[16:19], v[190:193], v[214:217], v[16:19]
	v_mfma_f32_16x16x32_bf16 v[4:7], v[182:185], v[222:225], v[4:7]
	v_mfma_f32_16x16x32_bf16 v[0:3], v[190:193], v[222:225], v[0:3]
	v_mfma_f32_16x16x32_bf16 v[52:55], v[186:189], v[202:205], v[52:55]
	v_mfma_f32_16x16x32_bf16 v[48:51], v[194:197], v[202:205], v[48:51]
	v_mfma_f32_16x16x32_bf16 v[36:39], v[186:189], v[210:213], v[36:39]
	v_mfma_f32_16x16x32_bf16 v[32:35], v[194:197], v[210:213], v[32:35]
	v_mfma_f32_16x16x32_bf16 v[20:23], v[186:189], v[218:221], v[20:23]
	v_mfma_f32_16x16x32_bf16 v[16:19], v[194:197], v[218:221], v[16:19]
	v_mfma_f32_16x16x32_bf16 v[4:7], v[186:189], v[226:229], v[4:7]
	v_mfma_f32_16x16x32_bf16 v[0:3], v[194:197], v[226:229], v[0:3]
	s_setprio 0
	s_barrier
	s_add_i32 s8, s81, 2
	s_add_u32 s44, s44, 0x100
	s_addc_u32 s45, s45, 0
	s_cmp_gt_u32 s81, 13
	s_mov_b32 s81, s8
	s_cbranch_scc1 .LBB0_813
	s_branch .LBB0_807
.LBB0_806:
	v_add_u32_e32 v152, s68, v157
	ds_read_b128 v[166:169], v152
	ds_read_b128 v[170:173], v152 offset:1024
	ds_read_b128 v[174:177], v152 offset:2048
	ds_read_b128 v[178:181], v152 offset:3072
	v_add_u32_e32 v152, s69, v157
	ds_read_b128 v[182:185], v152
	ds_read_b128 v[186:189], v152 offset:1024
	ds_read_b128 v[190:193], v152 offset:2048
	ds_read_b128 v[194:197], v152 offset:3072
	s_add_u32 s8, s52, 0x100
	s_addc_u32 s84, s53, 0
	s_and_b64 s[52:53], exec, s[50:51]
	s_cselect_b32 s53, s21, s84
	s_cselect_b32 s52, s79, s8
	s_add_u32 s8, s83, 0x100
	s_addc_u32 s82, s82, 0
	s_and_b64 s[50:51], exec, s[50:51]
	s_cselect_b32 s51, s19, s82
	s_cselect_b32 s50, s80, s8
	v_lshl_add_u64 v[154:155], v[148:149], 0, s[44:45]
	s_add_i32 m0, s57, 0xc000
	ds_read_b128 v[198:201], v161
	ds_read_b128 v[202:205], v161 offset:1024
	ds_read_b128 v[206:209], v161 offset:2048
	ds_read_b128 v[210:213], v161 offset:3072
	ds_read_b128 v[214:217], v161 offset:4096
	ds_read_b128 v[218:221], v161 offset:5120
	ds_read_b128 v[222:225], v161 offset:6144
	global_load_lds_dwordx4 v[154:155], off
	v_lshl_add_u64 v[154:155], v[150:151], 0, s[44:45]
	s_add_i32 m0, s57, 0xe000
	ds_read_b128 v[226:229], v161 offset:7168
	global_load_lds_dwordx4 v[154:155], off
	s_waitcnt vmcnt(8)
	s_waitcnt lgkmcnt(0)
	s_barrier
	s_setprio 1
	s_waitcnt lgkmcnt(0)
	v_mfma_f32_16x16x32_bf16 v[124:127], v[166:169], v[198:201], v[124:127]
	v_mfma_f32_16x16x32_bf16 v[120:123], v[174:177], v[198:201], v[120:123]
	v_mfma_f32_16x16x32_bf16 v[108:111], v[166:169], v[206:209], v[108:111]
	v_mfma_f32_16x16x32_bf16 v[104:107], v[174:177], v[206:209], v[104:107]
	v_mfma_f32_16x16x32_bf16 v[92:95], v[166:169], v[214:217], v[92:95]
	v_mfma_f32_16x16x32_bf16 v[88:91], v[174:177], v[214:217], v[88:91]
	v_mfma_f32_16x16x32_bf16 v[76:79], v[166:169], v[222:225], v[76:79]
	v_mfma_f32_16x16x32_bf16 v[72:75], v[174:177], v[222:225], v[72:75]
	v_mfma_f32_16x16x32_bf16 v[124:127], v[170:173], v[202:205], v[124:127]
	v_mfma_f32_16x16x32_bf16 v[120:123], v[178:181], v[202:205], v[120:123]
	v_mfma_f32_16x16x32_bf16 v[108:111], v[170:173], v[210:213], v[108:111]
	v_mfma_f32_16x16x32_bf16 v[104:107], v[178:181], v[210:213], v[104:107]
	v_mfma_f32_16x16x32_bf16 v[92:95], v[170:173], v[218:221], v[92:95]
	v_mfma_f32_16x16x32_bf16 v[88:91], v[178:181], v[218:221], v[88:91]
	v_mfma_f32_16x16x32_bf16 v[76:79], v[170:173], v[226:229], v[76:79]
	v_mfma_f32_16x16x32_bf16 v[72:75], v[178:181], v[226:229], v[72:75]
	s_setprio 0
	s_setprio 1
	v_mfma_f32_16x16x32_bf16 v[116:119], v[182:185], v[198:201], v[116:119]
	v_mfma_f32_16x16x32_bf16 v[112:115], v[190:193], v[198:201], v[112:115]
	v_mfma_f32_16x16x32_bf16 v[100:103], v[182:185], v[206:209], v[100:103]
	v_mfma_f32_16x16x32_bf16 v[96:99], v[190:193], v[206:209], v[96:99]
	v_mfma_f32_16x16x32_bf16 v[84:87], v[182:185], v[214:217], v[84:87]
	v_mfma_f32_16x16x32_bf16 v[80:83], v[190:193], v[214:217], v[80:83]
	v_mfma_f32_16x16x32_bf16 v[68:71], v[182:185], v[222:225], v[68:71]
	v_mfma_f32_16x16x32_bf16 v[64:67], v[190:193], v[222:225], v[64:67]
	v_mfma_f32_16x16x32_bf16 v[116:119], v[186:189], v[202:205], v[116:119]
	v_mfma_f32_16x16x32_bf16 v[112:115], v[194:197], v[202:205], v[112:115]
	v_mfma_f32_16x16x32_bf16 v[100:103], v[186:189], v[210:213], v[100:103]
	v_mfma_f32_16x16x32_bf16 v[96:99], v[194:197], v[210:213], v[96:99]
	v_mfma_f32_16x16x32_bf16 v[84:87], v[186:189], v[218:221], v[84:87]
	v_mfma_f32_16x16x32_bf16 v[80:83], v[194:197], v[218:221], v[80:83]
	v_mfma_f32_16x16x32_bf16 v[68:71], v[186:189], v[226:229], v[68:71]
	v_mfma_f32_16x16x32_bf16 v[64:67], v[194:197], v[226:229], v[64:67]
	s_setprio 0
	s_barrier
	s_add_i32 s8, s68, s54
	s_mov_b32 m0, s8
	ds_read_b128 v[198:201], v161 offset:16384
	ds_read_b128 v[202:205], v161 offset:17408
	ds_read_b128 v[206:209], v161 offset:18432
	global_load_lds_dwordx4 v128, s[50:51]
	s_add_i32 m0, s8, 0x2000
	ds_read_b128 v[210:213], v161 offset:19456
	global_load_lds_dwordx4 v130, s[50:51]
	s_add_u32 s50, s50, 0x40000
	s_addc_u32 s51, s51, 0
	s_add_i32 s8, s69, s54
	s_mov_b32 m0, s8
	ds_read_b128 v[214:217], v161 offset:20480
	global_load_lds_dwordx4 v128, s[50:51]
	s_add_i32 m0, s8, 0x2000
	ds_read_b128 v[218:221], v161 offset:21504
	global_load_lds_dwordx4 v130, s[50:51]
	s_mov_b32 m0, s57
	ds_read_b128 v[222:225], v161 offset:22528
	global_load_lds_dwordx4 v134, s[52:53]
	s_mov_b32 m0, s58
	ds_read_b128 v[226:229], v161 offset:23552
	global_load_lds_dwordx4 v132, s[52:53]
	s_waitcnt vmcnt(8)
	s_waitcnt lgkmcnt(0)
	s_barrier
	s_setprio 1
	s_waitcnt lgkmcnt(0)
	v_mfma_f32_16x16x32_bf16 v[60:63], v[166:169], v[198:201], v[60:63]
	v_mfma_f32_16x16x32_bf16 v[56:59], v[174:177], v[198:201], v[56:59]
	v_mfma_f32_16x16x32_bf16 v[44:47], v[166:169], v[206:209], v[44:47]
	v_mfma_f32_16x16x32_bf16 v[40:43], v[174:177], v[206:209], v[40:43]
	v_mfma_f32_16x16x32_bf16 v[28:31], v[166:169], v[214:217], v[28:31]
	v_mfma_f32_16x16x32_bf16 v[24:27], v[174:177], v[214:217], v[24:27]
	v_mfma_f32_16x16x32_bf16 v[12:15], v[166:169], v[222:225], v[12:15]
	v_mfma_f32_16x16x32_bf16 v[8:11], v[174:177], v[222:225], v[8:11]
	v_mfma_f32_16x16x32_bf16 v[60:63], v[170:173], v[202:205], v[60:63]
	v_mfma_f32_16x16x32_bf16 v[56:59], v[178:181], v[202:205], v[56:59]
	v_mfma_f32_16x16x32_bf16 v[44:47], v[170:173], v[210:213], v[44:47]
	v_mfma_f32_16x16x32_bf16 v[40:43], v[178:181], v[210:213], v[40:43]
	v_mfma_f32_16x16x32_bf16 v[28:31], v[170:173], v[218:221], v[28:31]
	v_mfma_f32_16x16x32_bf16 v[24:27], v[178:181], v[218:221], v[24:27]
	v_mfma_f32_16x16x32_bf16 v[12:15], v[170:173], v[226:229], v[12:15]
	v_mfma_f32_16x16x32_bf16 v[8:11], v[178:181], v[226:229], v[8:11]
	s_setprio 0
	s_setprio 1
	v_mfma_f32_16x16x32_bf16 v[52:55], v[182:185], v[198:201], v[52:55]
	v_mfma_f32_16x16x32_bf16 v[48:51], v[190:193], v[198:201], v[48:51]
	v_mfma_f32_16x16x32_bf16 v[36:39], v[182:185], v[206:209], v[36:39]
	v_mfma_f32_16x16x32_bf16 v[32:35], v[190:193], v[206:209], v[32:35]
	v_mfma_f32_16x16x32_bf16 v[20:23], v[182:185], v[214:217], v[20:23]
	v_mfma_f32_16x16x32_bf16 v[16:19], v[190:193], v[214:217], v[16:19]
	v_mfma_f32_16x16x32_bf16 v[4:7], v[182:185], v[222:225], v[4:7]
	v_mfma_f32_16x16x32_bf16 v[0:3], v[190:193], v[222:225], v[0:3]
	v_mfma_f32_16x16x32_bf16 v[52:55], v[186:189], v[202:205], v[52:55]
	v_mfma_f32_16x16x32_bf16 v[48:51], v[194:197], v[202:205], v[48:51]
	v_mfma_f32_16x16x32_bf16 v[36:39], v[186:189], v[210:213], v[36:39]
	v_mfma_f32_16x16x32_bf16 v[32:35], v[194:197], v[210:213], v[32:35]
	v_mfma_f32_16x16x32_bf16 v[20:23], v[186:189], v[218:221], v[20:23]
	v_mfma_f32_16x16x32_bf16 v[16:19], v[194:197], v[218:221], v[16:19]
	v_mfma_f32_16x16x32_bf16 v[4:7], v[186:189], v[226:229], v[4:7]
	v_mfma_f32_16x16x32_bf16 v[0:3], v[194:197], v[226:229], v[0:3]
	s_setprio 0
	s_barrier
	s_add_i32 s8, 0, 0x18000
	v_add_u32_e32 v152, s8, v157
	s_add_i32 s82, 0, 0x1c000
	ds_read_b128 v[166:169], v152
	ds_read_b128 v[170:173], v152 offset:1024
	ds_read_b128 v[174:177], v152 offset:2048
	ds_read_b128 v[178:181], v152 offset:3072
	v_add_u32_e32 v152, s82, v157
	ds_read_b128 v[182:185], v152
	ds_read_b128 v[186:189], v152 offset:1024
	ds_read_b128 v[190:193], v152 offset:2048
	ds_read_b128 v[194:197], v152 offset:3072
	s_add_u32 s50, s52, 0x40000
	s_addc_u32 s51, s53, 0
	s_mov_b32 m0, s59
	ds_read_b128 v[198:201], v161 offset:32768
	ds_read_b128 v[202:205], v161 offset:33792
	ds_read_b128 v[206:209], v161 offset:34816
	ds_read_b128 v[210:213], v161 offset:35840
	ds_read_b128 v[214:217], v161 offset:36864
	ds_read_b128 v[218:221], v161 offset:37888
	ds_read_b128 v[222:225], v161 offset:38912
	global_load_lds_dwordx4 v134, s[50:51]
	s_mov_b32 m0, s60
	ds_read_b128 v[226:229], v161 offset:39936
	global_load_lds_dwordx4 v132, s[50:51]
	s_waitcnt vmcnt(8)
	s_waitcnt lgkmcnt(0)
	s_barrier
	s_setprio 1
	s_waitcnt lgkmcnt(0)
	v_mfma_f32_16x16x32_bf16 v[124:127], v[166:169], v[198:201], v[124:127]
	v_mfma_f32_16x16x32_bf16 v[120:123], v[174:177], v[198:201], v[120:123]
	v_mfma_f32_16x16x32_bf16 v[108:111], v[166:169], v[206:209], v[108:111]
	v_mfma_f32_16x16x32_bf16 v[104:107], v[174:177], v[206:209], v[104:107]
	v_mfma_f32_16x16x32_bf16 v[92:95], v[166:169], v[214:217], v[92:95]
	v_mfma_f32_16x16x32_bf16 v[88:91], v[174:177], v[214:217], v[88:91]
	v_mfma_f32_16x16x32_bf16 v[76:79], v[166:169], v[222:225], v[76:79]
	v_mfma_f32_16x16x32_bf16 v[72:75], v[174:177], v[222:225], v[72:75]
	v_mfma_f32_16x16x32_bf16 v[124:127], v[170:173], v[202:205], v[124:127]
	v_mfma_f32_16x16x32_bf16 v[120:123], v[178:181], v[202:205], v[120:123]
	v_mfma_f32_16x16x32_bf16 v[108:111], v[170:173], v[210:213], v[108:111]
	v_mfma_f32_16x16x32_bf16 v[104:107], v[178:181], v[210:213], v[104:107]
	v_mfma_f32_16x16x32_bf16 v[92:95], v[170:173], v[218:221], v[92:95]
	v_mfma_f32_16x16x32_bf16 v[88:91], v[178:181], v[218:221], v[88:91]
	v_mfma_f32_16x16x32_bf16 v[76:79], v[170:173], v[226:229], v[76:79]
	v_mfma_f32_16x16x32_bf16 v[72:75], v[178:181], v[226:229], v[72:75]
	s_setprio 0
	s_setprio 1
	v_mfma_f32_16x16x32_bf16 v[116:119], v[182:185], v[198:201], v[116:119]
	v_mfma_f32_16x16x32_bf16 v[112:115], v[190:193], v[198:201], v[112:115]
	v_mfma_f32_16x16x32_bf16 v[100:103], v[182:185], v[206:209], v[100:103]
	v_mfma_f32_16x16x32_bf16 v[96:99], v[190:193], v[206:209], v[96:99]
	v_mfma_f32_16x16x32_bf16 v[84:87], v[182:185], v[214:217], v[84:87]
	v_mfma_f32_16x16x32_bf16 v[80:83], v[190:193], v[214:217], v[80:83]
	v_mfma_f32_16x16x32_bf16 v[68:71], v[182:185], v[222:225], v[68:71]
	v_mfma_f32_16x16x32_bf16 v[64:67], v[190:193], v[222:225], v[64:67]
	v_mfma_f32_16x16x32_bf16 v[116:119], v[186:189], v[202:205], v[116:119]
	v_mfma_f32_16x16x32_bf16 v[112:115], v[194:197], v[202:205], v[112:115]
	v_mfma_f32_16x16x32_bf16 v[100:103], v[186:189], v[210:213], v[100:103]
	v_mfma_f32_16x16x32_bf16 v[96:99], v[194:197], v[210:213], v[96:99]
	v_mfma_f32_16x16x32_bf16 v[84:87], v[186:189], v[218:221], v[84:87]
	v_mfma_f32_16x16x32_bf16 v[80:83], v[194:197], v[218:221], v[80:83]
	v_mfma_f32_16x16x32_bf16 v[68:71], v[186:189], v[226:229], v[68:71]
	v_mfma_f32_16x16x32_bf16 v[64:67], v[194:197], v[226:229], v[64:67]
	s_setprio 0
	s_barrier
	s_add_i32 s8, s8, s54
	s_mov_b32 m0, s8
	ds_read_b128 v[198:201], v161 offset:49152
	ds_read_b128 v[202:205], v161 offset:50176
	ds_read_b128 v[206:209], v161 offset:51200
	global_load_lds_dwordx4 v128, s[48:49]
	s_add_i32 m0, s8, 0x2000
	ds_read_b128 v[210:213], v161 offset:52224
	global_load_lds_dwordx4 v130, s[48:49]
	s_add_u32 s48, s48, 0x40000
	s_addc_u32 s49, s49, 0
	s_add_i32 s8, s82, s54
	s_mov_b32 m0, s8
	ds_read_b128 v[214:217], v161 offset:53248
	global_load_lds_dwordx4 v128, s[48:49]
	s_add_i32 m0, s8, 0x2000
	ds_read_b128 v[218:221], v161 offset:54272
	global_load_lds_dwordx4 v130, s[48:49]
	s_mov_b32 m0, s65
	ds_read_b128 v[222:225], v161 offset:55296
	global_load_lds_dwordx4 v134, s[46:47]
	s_mov_b32 m0, s66
	ds_read_b128 v[226:229], v161 offset:56320
	global_load_lds_dwordx4 v132, s[46:47]
	s_waitcnt vmcnt(8)
	s_waitcnt lgkmcnt(0)
	s_barrier
	s_setprio 1
	s_waitcnt lgkmcnt(0)
	v_mfma_f32_16x16x32_bf16 v[60:63], v[166:169], v[198:201], v[60:63]
	v_mfma_f32_16x16x32_bf16 v[56:59], v[174:177], v[198:201], v[56:59]
	v_mfma_f32_16x16x32_bf16 v[44:47], v[166:169], v[206:209], v[44:47]
	v_mfma_f32_16x16x32_bf16 v[40:43], v[174:177], v[206:209], v[40:43]
	v_mfma_f32_16x16x32_bf16 v[28:31], v[166:169], v[214:217], v[28:31]
	v_mfma_f32_16x16x32_bf16 v[24:27], v[174:177], v[214:217], v[24:27]
	v_mfma_f32_16x16x32_bf16 v[12:15], v[166:169], v[222:225], v[12:15]
	v_mfma_f32_16x16x32_bf16 v[8:11], v[174:177], v[222:225], v[8:11]
	v_mfma_f32_16x16x32_bf16 v[60:63], v[170:173], v[202:205], v[60:63]
	v_mfma_f32_16x16x32_bf16 v[56:59], v[178:181], v[202:205], v[56:59]
	v_mfma_f32_16x16x32_bf16 v[44:47], v[170:173], v[210:213], v[44:47]
	v_mfma_f32_16x16x32_bf16 v[40:43], v[178:181], v[210:213], v[40:43]
	v_mfma_f32_16x16x32_bf16 v[28:31], v[170:173], v[218:221], v[28:31]
	v_mfma_f32_16x16x32_bf16 v[24:27], v[178:181], v[218:221], v[24:27]
	v_mfma_f32_16x16x32_bf16 v[12:15], v[170:173], v[226:229], v[12:15]
	v_mfma_f32_16x16x32_bf16 v[8:11], v[178:181], v[226:229], v[8:11]
	s_setprio 0
	s_setprio 1
	v_mfma_f32_16x16x32_bf16 v[52:55], v[182:185], v[198:201], v[52:55]
	v_mfma_f32_16x16x32_bf16 v[48:51], v[190:193], v[198:201], v[48:51]
	v_mfma_f32_16x16x32_bf16 v[36:39], v[182:185], v[206:209], v[36:39]
	v_mfma_f32_16x16x32_bf16 v[32:35], v[190:193], v[206:209], v[32:35]
	v_mfma_f32_16x16x32_bf16 v[20:23], v[182:185], v[214:217], v[20:23]
	v_mfma_f32_16x16x32_bf16 v[16:19], v[190:193], v[214:217], v[16:19]
	v_mfma_f32_16x16x32_bf16 v[4:7], v[182:185], v[222:225], v[4:7]
	v_mfma_f32_16x16x32_bf16 v[0:3], v[190:193], v[222:225], v[0:3]
	v_mfma_f32_16x16x32_bf16 v[52:55], v[186:189], v[202:205], v[52:55]
	v_mfma_f32_16x16x32_bf16 v[48:51], v[194:197], v[202:205], v[48:51]
	v_mfma_f32_16x16x32_bf16 v[36:39], v[186:189], v[210:213], v[36:39]
	v_mfma_f32_16x16x32_bf16 v[32:35], v[194:197], v[210:213], v[32:35]
	v_mfma_f32_16x16x32_bf16 v[20:23], v[186:189], v[218:221], v[20:23]
	v_mfma_f32_16x16x32_bf16 v[16:19], v[194:197], v[218:221], v[16:19]
	v_mfma_f32_16x16x32_bf16 v[4:7], v[186:189], v[226:229], v[4:7]
	v_mfma_f32_16x16x32_bf16 v[0:3], v[194:197], v[226:229], v[0:3]
	s_setprio 0
	s_barrier
	s_add_i32 s8, s81, 2
	s_add_u32 s44, s44, 0x100
	s_addc_u32 s45, s45, 0
	s_cmp_gt_u32 s81, 13
	s_mov_b32 s81, s8
	s_cbranch_scc1 .LBB0_813

.LBB0_895:
	s_add_u32 s70, s55, s28
	s_addc_u32 s71, s56, s29
	s_add_u32 s72, s57, s30
	s_addc_u32 s73, s58, s31
	s_add_u32 s28, s4, 0x80
	s_addc_u32 s29, s5, 0
	s_add_u32 s30, s20, 0x80
	s_addc_u32 s31, s21, 0
	v_lshl_add_u64 v[128:129], s[26:27], 0, v[148:149]
	v_lshl_add_u64 v[130:131], s[26:27], 0, v[150:151]
	s_mov_b32 s78, 0
	s_mov_b64 s[36:37], 0
	s_cmpk_eq_i32 s36, 0x1500
	s_cselect_b64 s[44:45], -1, 0
	s_add_u32 s46, s26, s36
	s_addc_u32 s47, s27, s37
	s_add_u32 s80, s24, s36
	s_addc_u32 s79, s25, s37
	s_add_u32 s38, s46, 0x180
	s_addc_u32 s39, s47, 0
	s_add_u32 s40, s80, 0x180
	s_addc_u32 s41, s79, 0
	s_cmpk_eq_i32 s36, 0x1500
	s_cselect_b32 s38, s28, s38
	s_cselect_b32 s39, s29, s39
	s_cselect_b32 s40, s30, s40
	s_cselect_b32 s41, s31, s41
	v_add_u32_e32 v167, s64, v165
	ds_read_b128 v[132:135], v167
	ds_read_b128 v[156:159], v167 offset:1024
	ds_read_b128 v[160:163], v167 offset:2048
	ds_read_b128 v[168:171], v167 offset:3072
	v_add_u32_e32 v167, s65, v165
	ds_read_b128 v[172:175], v167
	ds_read_b128 v[176:179], v167 offset:1024
	ds_read_b128 v[180:183], v167 offset:2048
	ds_read_b128 v[184:187], v167 offset:3072
	s_add_u32 s8, s46, 0x100
	s_addc_u32 s81, s47, 0
	s_and_b64 s[46:47], exec, s[44:45]
	s_cselect_b32 s47, s5, s81
	s_cselect_b32 s46, s4, s8
	s_add_u32 s8, s80, 0x100
	s_addc_u32 s79, s79, 0
	s_and_b64 s[44:45], exec, s[44:45]
	s_cselect_b32 s45, s21, s79
	s_cselect_b32 s44, s20, s8
	v_lshl_add_u64 v[220:221], v[128:129], 0, s[36:37]
	s_add_i32 m0, s51, 0xc000
	ds_read_b128 v[188:191], v166
	ds_read_b128 v[192:195], v166 offset:1024
	ds_read_b128 v[196:199], v166 offset:2048
	ds_read_b128 v[200:203], v166 offset:3072
	ds_read_b128 v[204:207], v166 offset:4096
	ds_read_b128 v[208:211], v166 offset:5120
	ds_read_b128 v[212:215], v166 offset:6144
	global_load_lds_dwordx4 v[220:221], off
	v_lshl_add_u64 v[220:221], v[130:131], 0, s[36:37]
	s_add_i32 m0, s51, 0xe000
	ds_read_b128 v[216:219], v166 offset:7168
	global_load_lds_dwordx4 v[220:221], off
	s_waitcnt vmcnt(8)
	s_waitcnt lgkmcnt(0)
	s_barrier
	s_setprio 1
	s_waitcnt lgkmcnt(0)
	v_mfma_f32_16x16x32_bf16 v[124:127], v[132:135], v[188:191], 0
	v_mfma_f32_16x16x32_bf16 v[120:123], v[160:163], v[188:191], 0
	v_mfma_f32_16x16x32_bf16 v[108:111], v[132:135], v[196:199], 0
	v_mfma_f32_16x16x32_bf16 v[104:107], v[160:163], v[196:199], 0
	v_mfma_f32_16x16x32_bf16 v[92:95], v[132:135], v[204:207], 0
	v_mfma_f32_16x16x32_bf16 v[88:91], v[160:163], v[204:207], 0
	v_mfma_f32_16x16x32_bf16 v[76:79], v[132:135], v[212:215], 0
	v_mfma_f32_16x16x32_bf16 v[72:75], v[160:163], v[212:215], 0
	v_mfma_f32_16x16x32_bf16 v[124:127], v[156:159], v[192:195], v[124:127]
	v_mfma_f32_16x16x32_bf16 v[120:123], v[168:171], v[192:195], v[120:123]
	v_mfma_f32_16x16x32_bf16 v[108:111], v[156:159], v[200:203], v[108:111]
	v_mfma_f32_16x16x32_bf16 v[104:107], v[168:171], v[200:203], v[104:107]
	v_mfma_f32_16x16x32_bf16 v[92:95], v[156:159], v[208:211], v[92:95]
	v_mfma_f32_16x16x32_bf16 v[88:91], v[168:171], v[208:211], v[88:91]
	v_mfma_f32_16x16x32_bf16 v[76:79], v[156:159], v[216:219], v[76:79]
	v_mfma_f32_16x16x32_bf16 v[72:75], v[168:171], v[216:219], v[72:75]
	s_setprio 0
	s_setprio 1
	v_mfma_f32_16x16x32_bf16 v[116:119], v[172:175], v[188:191], 0
	v_mfma_f32_16x16x32_bf16 v[112:115], v[180:183], v[188:191], 0
	v_mfma_f32_16x16x32_bf16 v[100:103], v[172:175], v[196:199], 0
	v_mfma_f32_16x16x32_bf16 v[96:99], v[180:183], v[196:199], 0
	v_mfma_f32_16x16x32_bf16 v[84:87], v[172:175], v[204:207], 0
	v_mfma_f32_16x16x32_bf16 v[80:83], v[180:183], v[204:207], 0
	v_mfma_f32_16x16x32_bf16 v[68:71], v[172:175], v[212:215], 0
	v_mfma_f32_16x16x32_bf16 v[64:67], v[180:183], v[212:215], 0
	v_mfma_f32_16x16x32_bf16 v[116:119], v[176:179], v[192:195], v[116:119]
	v_mfma_f32_16x16x32_bf16 v[112:115], v[184:187], v[192:195], v[112:115]
	v_mfma_f32_16x16x32_bf16 v[100:103], v[176:179], v[200:203], v[100:103]
	v_mfma_f32_16x16x32_bf16 v[96:99], v[184:187], v[200:203], v[96:99]
	v_mfma_f32_16x16x32_bf16 v[84:87], v[176:179], v[208:211], v[84:87]
	v_mfma_f32_16x16x32_bf16 v[80:83], v[184:187], v[208:211], v[80:83]
	v_mfma_f32_16x16x32_bf16 v[68:71], v[176:179], v[216:219], v[68:71]
	v_mfma_f32_16x16x32_bf16 v[64:67], v[184:187], v[216:219], v[64:67]
	s_setprio 0
	s_barrier
	s_add_i32 s8, s64, s50
	s_mov_b32 m0, s8
	ds_read_b128 v[188:191], v166 offset:16384
	ds_read_b128 v[192:195], v166 offset:17408
	ds_read_b128 v[196:199], v166 offset:18432
	global_load_lds_dwordx4 v138, s[44:45]
	s_add_i32 m0, s8, 0x2000
	ds_read_b128 v[200:203], v166 offset:19456
	global_load_lds_dwordx4 v142, s[44:45]
	s_add_u32 s44, s44, 0xb0000
	s_addc_u32 s45, s45, 0
	s_add_i32 s8, s65, s50
	s_mov_b32 m0, s8
	ds_read_b128 v[204:207], v166 offset:20480
	global_load_lds_dwordx4 v138, s[44:45]
	s_add_i32 m0, s8, 0x2000
	ds_read_b128 v[208:211], v166 offset:21504
	global_load_lds_dwordx4 v142, s[44:45]
	s_mov_b32 m0, s51
	ds_read_b128 v[212:215], v166 offset:22528
	global_load_lds_dwordx4 v136, s[46:47]
	s_mov_b32 m0, s52
	ds_read_b128 v[216:219], v166 offset:23552
	global_load_lds_dwordx4 v140, s[46:47]
	s_waitcnt vmcnt(8)
	s_waitcnt lgkmcnt(0)
	s_barrier
	s_setprio 1
	s_waitcnt lgkmcnt(0)
	v_mfma_f32_16x16x32_bf16 v[60:63], v[132:135], v[188:191], 0
	v_mfma_f32_16x16x32_bf16 v[56:59], v[160:163], v[188:191], 0
	v_mfma_f32_16x16x32_bf16 v[44:47], v[132:135], v[196:199], 0
	v_mfma_f32_16x16x32_bf16 v[40:43], v[160:163], v[196:199], 0
	v_mfma_f32_16x16x32_bf16 v[28:31], v[132:135], v[204:207], 0
	v_mfma_f32_16x16x32_bf16 v[24:27], v[160:163], v[204:207], 0
	v_mfma_f32_16x16x32_bf16 v[12:15], v[132:135], v[212:215], 0
	v_mfma_f32_16x16x32_bf16 v[8:11], v[160:163], v[212:215], 0
	v_mfma_f32_16x16x32_bf16 v[60:63], v[156:159], v[192:195], v[60:63]
	v_mfma_f32_16x16x32_bf16 v[56:59], v[168:171], v[192:195], v[56:59]
	v_mfma_f32_16x16x32_bf16 v[44:47], v[156:159], v[200:203], v[44:47]
	v_mfma_f32_16x16x32_bf16 v[40:43], v[168:171], v[200:203], v[40:43]
	v_mfma_f32_16x16x32_bf16 v[28:31], v[156:159], v[208:211], v[28:31]
	v_mfma_f32_16x16x32_bf16 v[24:27], v[168:171], v[208:211], v[24:27]
	v_mfma_f32_16x16x32_bf16 v[12:15], v[156:159], v[216:219], v[12:15]
	v_mfma_f32_16x16x32_bf16 v[8:11], v[168:171], v[216:219], v[8:11]
	s_setprio 0
	s_setprio 1
	v_mfma_f32_16x16x32_bf16 v[52:55], v[172:175], v[188:191], 0
	v_mfma_f32_16x16x32_bf16 v[48:51], v[180:183], v[188:191], 0
	v_mfma_f32_16x16x32_bf16 v[36:39], v[172:175], v[196:199], 0
	v_mfma_f32_16x16x32_bf16 v[32:35], v[180:183], v[196:199], 0
	v_mfma_f32_16x16x32_bf16 v[20:23], v[172:175], v[204:207], 0
	v_mfma_f32_16x16x32_bf16 v[16:19], v[180:183], v[204:207], 0
	v_mfma_f32_16x16x32_bf16 v[4:7], v[172:175], v[212:215], 0
	v_mfma_f32_16x16x32_bf16 v[0:3], v[180:183], v[212:215], 0
	v_mfma_f32_16x16x32_bf16 v[52:55], v[176:179], v[192:195], v[52:55]
	v_mfma_f32_16x16x32_bf16 v[48:51], v[184:187], v[192:195], v[48:51]
	v_mfma_f32_16x16x32_bf16 v[36:39], v[176:179], v[200:203], v[36:39]
	v_mfma_f32_16x16x32_bf16 v[32:35], v[184:187], v[200:203], v[32:35]
	v_mfma_f32_16x16x32_bf16 v[20:23], v[176:179], v[208:211], v[20:23]
	v_mfma_f32_16x16x32_bf16 v[16:19], v[184:187], v[208:211], v[16:19]
	v_mfma_f32_16x16x32_bf16 v[4:7], v[176:179], v[216:219], v[4:7]
	v_mfma_f32_16x16x32_bf16 v[0:3], v[184:187], v[216:219], v[0:3]
	s_setprio 0
	s_barrier
	s_add_i32 s8, 0, 0x18000
	v_add_u32_e32 v167, s8, v165
	s_add_i32 s79, 0, 0x1c000
	ds_read_b128 v[132:135], v167
	ds_read_b128 v[156:159], v167 offset:1024
	ds_read_b128 v[160:163], v167 offset:2048
	ds_read_b128 v[168:171], v167 offset:3072
	v_add_u32_e32 v167, s79, v165
	ds_read_b128 v[172:175], v167
	ds_read_b128 v[176:179], v167 offset:1024
	ds_read_b128 v[180:183], v167 offset:2048
	ds_read_b128 v[184:187], v167 offset:3072
	s_add_u32 s44, s46, 0xb0000
	s_addc_u32 s45, s47, 0
	s_mov_b32 m0, s53
	ds_read_b128 v[188:191], v166 offset:32768
	ds_read_b128 v[192:195], v166 offset:33792
	ds_read_b128 v[196:199], v166 offset:34816
	ds_read_b128 v[200:203], v166 offset:35840
	ds_read_b128 v[204:207], v166 offset:36864
	ds_read_b128 v[208:211], v166 offset:37888
	ds_read_b128 v[212:215], v166 offset:38912
	global_load_lds_dwordx4 v136, s[44:45]
	s_mov_b32 m0, s54
	ds_read_b128 v[216:219], v166 offset:39936
	global_load_lds_dwordx4 v140, s[44:45]
	s_waitcnt vmcnt(8)
	s_waitcnt lgkmcnt(0)
	s_barrier
	s_setprio 1
	s_waitcnt lgkmcnt(0)
	v_mfma_f32_16x16x32_bf16 v[124:127], v[132:135], v[188:191], v[124:127]
	v_mfma_f32_16x16x32_bf16 v[120:123], v[160:163], v[188:191], v[120:123]
	v_mfma_f32_16x16x32_bf16 v[108:111], v[132:135], v[196:199], v[108:111]
	v_mfma_f32_16x16x32_bf16 v[104:107], v[160:163], v[196:199], v[104:107]
	v_mfma_f32_16x16x32_bf16 v[92:95], v[132:135], v[204:207], v[92:95]
	v_mfma_f32_16x16x32_bf16 v[88:91], v[160:163], v[204:207], v[88:91]
	v_mfma_f32_16x16x32_bf16 v[76:79], v[132:135], v[212:215], v[76:79]
	v_mfma_f32_16x16x32_bf16 v[72:75], v[160:163], v[212:215], v[72:75]
	v_mfma_f32_16x16x32_bf16 v[124:127], v[156:159], v[192:195], v[124:127]
	v_mfma_f32_16x16x32_bf16 v[120:123], v[168:171], v[192:195], v[120:123]
	v_mfma_f32_16x16x32_bf16 v[108:111], v[156:159], v[200:203], v[108:111]
	v_mfma_f32_16x16x32_bf16 v[104:107], v[168:171], v[200:203], v[104:107]
	v_mfma_f32_16x16x32_bf16 v[92:95], v[156:159], v[208:211], v[92:95]
	v_mfma_f32_16x16x32_bf16 v[88:91], v[168:171], v[208:211], v[88:91]
	v_mfma_f32_16x16x32_bf16 v[76:79], v[156:159], v[216:219], v[76:79]
	v_mfma_f32_16x16x32_bf16 v[72:75], v[168:171], v[216:219], v[72:75]
	s_setprio 0
	s_setprio 1
	v_mfma_f32_16x16x32_bf16 v[116:119], v[172:175], v[188:191], v[116:119]
	v_mfma_f32_16x16x32_bf16 v[112:115], v[180:183], v[188:191], v[112:115]
	v_mfma_f32_16x16x32_bf16 v[100:103], v[172:175], v[196:199], v[100:103]
	v_mfma_f32_16x16x32_bf16 v[96:99], v[180:183], v[196:199], v[96:99]
	v_mfma_f32_16x16x32_bf16 v[84:87], v[172:175], v[204:207], v[84:87]
	v_mfma_f32_16x16x32_bf16 v[80:83], v[180:183], v[204:207], v[80:83]
	v_mfma_f32_16x16x32_bf16 v[68:71], v[172:175], v[212:215], v[68:71]
	v_mfma_f32_16x16x32_bf16 v[64:67], v[180:183], v[212:215], v[64:67]
	v_mfma_f32_16x16x32_bf16 v[116:119], v[176:179], v[192:195], v[116:119]
	v_mfma_f32_16x16x32_bf16 v[112:115], v[184:187], v[192:195], v[112:115]
	v_mfma_f32_16x16x32_bf16 v[100:103], v[176:179], v[200:203], v[100:103]
	v_mfma_f32_16x16x32_bf16 v[96:99], v[184:187], v[200:203], v[96:99]
	v_mfma_f32_16x16x32_bf16 v[84:87], v[176:179], v[208:211], v[84:87]
	v_mfma_f32_16x16x32_bf16 v[80:83], v[184:187], v[208:211], v[80:83]
	v_mfma_f32_16x16x32_bf16 v[68:71], v[176:179], v[216:219], v[68:71]
	v_mfma_f32_16x16x32_bf16 v[64:67], v[184:187], v[216:219], v[64:67]
	s_setprio 0
	s_barrier
	s_add_i32 s8, s8, s50
	s_mov_b32 m0, s8
	ds_read_b128 v[188:191], v166 offset:49152
	ds_read_b128 v[192:195], v166 offset:50176
	ds_read_b128 v[196:199], v166 offset:51200
	global_load_lds_dwordx4 v138, s[40:41]
	s_add_i32 m0, s8, 0x2000
	ds_read_b128 v[200:203], v166 offset:52224
	global_load_lds_dwordx4 v142, s[40:41]
	s_add_u32 s40, s40, 0xb0000
	s_addc_u32 s41, s41, 0
	s_add_i32 s8, s79, s50
	s_mov_b32 m0, s8
	ds_read_b128 v[204:207], v166 offset:53248
	global_load_lds_dwordx4 v138, s[40:41]
	s_add_i32 m0, s8, 0x2000
	ds_read_b128 v[208:211], v166 offset:54272
	global_load_lds_dwordx4 v142, s[40:41]
	s_mov_b32 m0, s60
	ds_read_b128 v[212:215], v166 offset:55296
	global_load_lds_dwordx4 v136, s[38:39]
	s_mov_b32 m0, s61
	ds_read_b128 v[216:219], v166 offset:56320
	global_load_lds_dwordx4 v140, s[38:39]
	s_waitcnt vmcnt(8)
	s_waitcnt lgkmcnt(0)
	s_barrier
	s_setprio 1
	s_waitcnt lgkmcnt(0)
	v_mfma_f32_16x16x32_bf16 v[60:63], v[132:135], v[188:191], v[60:63]
	v_mfma_f32_16x16x32_bf16 v[56:59], v[160:163], v[188:191], v[56:59]
	v_mfma_f32_16x16x32_bf16 v[44:47], v[132:135], v[196:199], v[44:47]
	v_mfma_f32_16x16x32_bf16 v[40:43], v[160:163], v[196:199], v[40:43]
	v_mfma_f32_16x16x32_bf16 v[28:31], v[132:135], v[204:207], v[28:31]
	v_mfma_f32_16x16x32_bf16 v[24:27], v[160:163], v[204:207], v[24:27]
	v_mfma_f32_16x16x32_bf16 v[12:15], v[132:135], v[212:215], v[12:15]
	v_mfma_f32_16x16x32_bf16 v[8:11], v[160:163], v[212:215], v[8:11]
	v_mfma_f32_16x16x32_bf16 v[60:63], v[156:159], v[192:195], v[60:63]
	v_mfma_f32_16x16x32_bf16 v[56:59], v[168:171], v[192:195], v[56:59]
	v_mfma_f32_16x16x32_bf16 v[44:47], v[156:159], v[200:203], v[44:47]
	v_mfma_f32_16x16x32_bf16 v[40:43], v[168:171], v[200:203], v[40:43]
	v_mfma_f32_16x16x32_bf16 v[28:31], v[156:159], v[208:211], v[28:31]
	v_mfma_f32_16x16x32_bf16 v[24:27], v[168:171], v[208:211], v[24:27]
	v_mfma_f32_16x16x32_bf16 v[12:15], v[156:159], v[216:219], v[12:15]
	v_mfma_f32_16x16x32_bf16 v[8:11], v[168:171], v[216:219], v[8:11]
	s_setprio 0
	s_setprio 1
	v_mfma_f32_16x16x32_bf16 v[52:55], v[172:175], v[188:191], v[52:55]
	v_mfma_f32_16x16x32_bf16 v[48:51], v[180:183], v[188:191], v[48:51]
	v_mfma_f32_16x16x32_bf16 v[36:39], v[172:175], v[196:199], v[36:39]
	v_mfma_f32_16x16x32_bf16 v[32:35], v[180:183], v[196:199], v[32:35]
	v_mfma_f32_16x16x32_bf16 v[20:23], v[172:175], v[204:207], v[20:23]
	v_mfma_f32_16x16x32_bf16 v[16:19], v[180:183], v[204:207], v[16:19]
	v_mfma_f32_16x16x32_bf16 v[4:7], v[172:175], v[212:215], v[4:7]
	v_mfma_f32_16x16x32_bf16 v[0:3], v[180:183], v[212:215], v[0:3]
	v_mfma_f32_16x16x32_bf16 v[52:55], v[176:179], v[192:195], v[52:55]
	v_mfma_f32_16x16x32_bf16 v[48:51], v[184:187], v[192:195], v[48:51]
	v_mfma_f32_16x16x32_bf16 v[36:39], v[176:179], v[200:203], v[36:39]
	v_mfma_f32_16x16x32_bf16 v[32:35], v[184:187], v[200:203], v[32:35]
	v_mfma_f32_16x16x32_bf16 v[20:23], v[176:179], v[208:211], v[20:23]
	v_mfma_f32_16x16x32_bf16 v[16:19], v[184:187], v[208:211], v[16:19]
	v_mfma_f32_16x16x32_bf16 v[4:7], v[176:179], v[216:219], v[4:7]
	v_mfma_f32_16x16x32_bf16 v[0:3], v[184:187], v[216:219], v[0:3]
	s_setprio 0
	s_barrier
	s_add_i32 s8, s78, 2
	s_add_u32 s36, s36, 0x100
	s_addc_u32 s37, s37, 0
	s_cmp_gt_u32 s78, 41
	s_mov_b32 s78, s8
	s_cbranch_scc1 .LBB0_903
	s_branch .LBB0_897
.LBB0_896:
	v_add_u32_e32 v167, s64, v165
	ds_read_b128 v[132:135], v167
	ds_read_b128 v[156:159], v167 offset:1024
	ds_read_b128 v[160:163], v167 offset:2048
	ds_read_b128 v[168:171], v167 offset:3072
	v_add_u32_e32 v167, s65, v165
	ds_read_b128 v[172:175], v167
	ds_read_b128 v[176:179], v167 offset:1024
	ds_read_b128 v[180:183], v167 offset:2048
	ds_read_b128 v[184:187], v167 offset:3072
	s_add_u32 s8, s46, 0x100
	s_addc_u32 s81, s47, 0
	s_and_b64 s[46:47], exec, s[44:45]
	s_cselect_b32 s47, s5, s81
	s_cselect_b32 s46, s4, s8
	s_add_u32 s8, s80, 0x100
	s_addc_u32 s79, s79, 0
	s_and_b64 s[44:45], exec, s[44:45]
	s_cselect_b32 s45, s21, s79
	s_cselect_b32 s44, s20, s8
	v_lshl_add_u64 v[220:221], v[128:129], 0, s[36:37]
	s_add_i32 m0, s51, 0xc000
	ds_read_b128 v[188:191], v166
	ds_read_b128 v[192:195], v166 offset:1024
	ds_read_b128 v[196:199], v166 offset:2048
	ds_read_b128 v[200:203], v166 offset:3072
	ds_read_b128 v[204:207], v166 offset:4096
	ds_read_b128 v[208:211], v166 offset:5120
	ds_read_b128 v[212:215], v166 offset:6144
	global_load_lds_dwordx4 v[220:221], off
	v_lshl_add_u64 v[220:221], v[130:131], 0, s[36:37]
	s_add_i32 m0, s51, 0xe000
	ds_read_b128 v[216:219], v166 offset:7168
	global_load_lds_dwordx4 v[220:221], off
	s_waitcnt vmcnt(8)
	s_waitcnt lgkmcnt(0)
	s_barrier
	s_setprio 1
	s_waitcnt lgkmcnt(0)
	v_mfma_f32_16x16x32_bf16 v[124:127], v[132:135], v[188:191], v[124:127]
	v_mfma_f32_16x16x32_bf16 v[120:123], v[160:163], v[188:191], v[120:123]
	v_mfma_f32_16x16x32_bf16 v[108:111], v[132:135], v[196:199], v[108:111]
	v_mfma_f32_16x16x32_bf16 v[104:107], v[160:163], v[196:199], v[104:107]
	v_mfma_f32_16x16x32_bf16 v[92:95], v[132:135], v[204:207], v[92:95]
	v_mfma_f32_16x16x32_bf16 v[88:91], v[160:163], v[204:207], v[88:91]
	v_mfma_f32_16x16x32_bf16 v[76:79], v[132:135], v[212:215], v[76:79]
	v_mfma_f32_16x16x32_bf16 v[72:75], v[160:163], v[212:215], v[72:75]
	v_mfma_f32_16x16x32_bf16 v[124:127], v[156:159], v[192:195], v[124:127]
	v_mfma_f32_16x16x32_bf16 v[120:123], v[168:171], v[192:195], v[120:123]
	v_mfma_f32_16x16x32_bf16 v[108:111], v[156:159], v[200:203], v[108:111]
	v_mfma_f32_16x16x32_bf16 v[104:107], v[168:171], v[200:203], v[104:107]
	v_mfma_f32_16x16x32_bf16 v[92:95], v[156:159], v[208:211], v[92:95]
	v_mfma_f32_16x16x32_bf16 v[88:91], v[168:171], v[208:211], v[88:91]
	v_mfma_f32_16x16x32_bf16 v[76:79], v[156:159], v[216:219], v[76:79]
	v_mfma_f32_16x16x32_bf16 v[72:75], v[168:171], v[216:219], v[72:75]
	s_setprio 0
	s_setprio 1
	v_mfma_f32_16x16x32_bf16 v[116:119], v[172:175], v[188:191], v[116:119]
	v_mfma_f32_16x16x32_bf16 v[112:115], v[180:183], v[188:191], v[112:115]
	v_mfma_f32_16x16x32_bf16 v[100:103], v[172:175], v[196:199], v[100:103]
	v_mfma_f32_16x16x32_bf16 v[96:99], v[180:183], v[196:199], v[96:99]
	v_mfma_f32_16x16x32_bf16 v[84:87], v[172:175], v[204:207], v[84:87]
	v_mfma_f32_16x16x32_bf16 v[80:83], v[180:183], v[204:207], v[80:83]
	v_mfma_f32_16x16x32_bf16 v[68:71], v[172:175], v[212:215], v[68:71]
	v_mfma_f32_16x16x32_bf16 v[64:67], v[180:183], v[212:215], v[64:67]
	v_mfma_f32_16x16x32_bf16 v[116:119], v[176:179], v[192:195], v[116:119]
	v_mfma_f32_16x16x32_bf16 v[112:115], v[184:187], v[192:195], v[112:115]
	v_mfma_f32_16x16x32_bf16 v[100:103], v[176:179], v[200:203], v[100:103]
	v_mfma_f32_16x16x32_bf16 v[96:99], v[184:187], v[200:203], v[96:99]
	v_mfma_f32_16x16x32_bf16 v[84:87], v[176:179], v[208:211], v[84:87]
	v_mfma_f32_16x16x32_bf16 v[80:83], v[184:187], v[208:211], v[80:83]
	v_mfma_f32_16x16x32_bf16 v[68:71], v[176:179], v[216:219], v[68:71]
	v_mfma_f32_16x16x32_bf16 v[64:67], v[184:187], v[216:219], v[64:67]
	s_setprio 0
	s_barrier
	s_add_i32 s8, s64, s50
	s_mov_b32 m0, s8
	ds_read_b128 v[188:191], v166 offset:16384
	ds_read_b128 v[192:195], v166 offset:17408
	ds_read_b128 v[196:199], v166 offset:18432
	global_load_lds_dwordx4 v138, s[44:45]
	s_add_i32 m0, s8, 0x2000
	ds_read_b128 v[200:203], v166 offset:19456
	global_load_lds_dwordx4 v142, s[44:45]
	s_add_u32 s44, s44, 0xb0000
	s_addc_u32 s45, s45, 0
	s_add_i32 s8, s65, s50
	s_mov_b32 m0, s8
	ds_read_b128 v[204:207], v166 offset:20480
	global_load_lds_dwordx4 v138, s[44:45]
	s_add_i32 m0, s8, 0x2000
	ds_read_b128 v[208:211], v166 offset:21504
	global_load_lds_dwordx4 v142, s[44:45]
	s_mov_b32 m0, s51
	ds_read_b128 v[212:215], v166 offset:22528
	global_load_lds_dwordx4 v136, s[46:47]
	s_mov_b32 m0, s52
	ds_read_b128 v[216:219], v166 offset:23552
	global_load_lds_dwordx4 v140, s[46:47]
	s_waitcnt vmcnt(8)
	s_waitcnt lgkmcnt(0)
	s_barrier
	s_setprio 1
	s_waitcnt lgkmcnt(0)
	v_mfma_f32_16x16x32_bf16 v[60:63], v[132:135], v[188:191], v[60:63]
	v_mfma_f32_16x16x32_bf16 v[56:59], v[160:163], v[188:191], v[56:59]
	v_mfma_f32_16x16x32_bf16 v[44:47], v[132:135], v[196:199], v[44:47]
	v_mfma_f32_16x16x32_bf16 v[40:43], v[160:163], v[196:199], v[40:43]
	v_mfma_f32_16x16x32_bf16 v[28:31], v[132:135], v[204:207], v[28:31]
	v_mfma_f32_16x16x32_bf16 v[24:27], v[160:163], v[204:207], v[24:27]
	v_mfma_f32_16x16x32_bf16 v[12:15], v[132:135], v[212:215], v[12:15]
	v_mfma_f32_16x16x32_bf16 v[8:11], v[160:163], v[212:215], v[8:11]
	v_mfma_f32_16x16x32_bf16 v[60:63], v[156:159], v[192:195], v[60:63]
	v_mfma_f32_16x16x32_bf16 v[56:59], v[168:171], v[192:195], v[56:59]
	v_mfma_f32_16x16x32_bf16 v[44:47], v[156:159], v[200:203], v[44:47]
	v_mfma_f32_16x16x32_bf16 v[40:43], v[168:171], v[200:203], v[40:43]
	v_mfma_f32_16x16x32_bf16 v[28:31], v[156:159], v[208:211], v[28:31]
	v_mfma_f32_16x16x32_bf16 v[24:27], v[168:171], v[208:211], v[24:27]
	v_mfma_f32_16x16x32_bf16 v[12:15], v[156:159], v[216:219], v[12:15]
	v_mfma_f32_16x16x32_bf16 v[8:11], v[168:171], v[216:219], v[8:11]
	s_setprio 0
	s_setprio 1
	v_mfma_f32_16x16x32_bf16 v[52:55], v[172:175], v[188:191], v[52:55]
	v_mfma_f32_16x16x32_bf16 v[48:51], v[180:183], v[188:191], v[48:51]
	v_mfma_f32_16x16x32_bf16 v[36:39], v[172:175], v[196:199], v[36:39]
	v_mfma_f32_16x16x32_bf16 v[32:35], v[180:183], v[196:199], v[32:35]
	v_mfma_f32_16x16x32_bf16 v[20:23], v[172:175], v[204:207], v[20:23]
	v_mfma_f32_16x16x32_bf16 v[16:19], v[180:183], v[204:207], v[16:19]
	v_mfma_f32_16x16x32_bf16 v[4:7], v[172:175], v[212:215], v[4:7]
	v_mfma_f32_16x16x32_bf16 v[0:3], v[180:183], v[212:215], v[0:3]
	v_mfma_f32_16x16x32_bf16 v[52:55], v[176:179], v[192:195], v[52:55]
	v_mfma_f32_16x16x32_bf16 v[48:51], v[184:187], v[192:195], v[48:51]
	v_mfma_f32_16x16x32_bf16 v[36:39], v[176:179], v[200:203], v[36:39]
	v_mfma_f32_16x16x32_bf16 v[32:35], v[184:187], v[200:203], v[32:35]
	v_mfma_f32_16x16x32_bf16 v[20:23], v[176:179], v[208:211], v[20:23]
	v_mfma_f32_16x16x32_bf16 v[16:19], v[184:187], v[208:211], v[16:19]
	v_mfma_f32_16x16x32_bf16 v[4:7], v[176:179], v[216:219], v[4:7]
	v_mfma_f32_16x16x32_bf16 v[0:3], v[184:187], v[216:219], v[0:3]
	s_setprio 0
	s_barrier
	s_add_i32 s8, 0, 0x18000
	v_add_u32_e32 v167, s8, v165
	s_add_i32 s79, 0, 0x1c000
	ds_read_b128 v[132:135], v167
	ds_read_b128 v[156:159], v167 offset:1024
	ds_read_b128 v[160:163], v167 offset:2048
	ds_read_b128 v[168:171], v167 offset:3072
	v_add_u32_e32 v167, s79, v165
	ds_read_b128 v[172:175], v167
	ds_read_b128 v[176:179], v167 offset:1024
	ds_read_b128 v[180:183], v167 offset:2048
	ds_read_b128 v[184:187], v167 offset:3072
	s_add_u32 s44, s46, 0xb0000
	s_addc_u32 s45, s47, 0
	s_mov_b32 m0, s53
	ds_read_b128 v[188:191], v166 offset:32768
	ds_read_b128 v[192:195], v166 offset:33792
	ds_read_b128 v[196:199], v166 offset:34816
	ds_read_b128 v[200:203], v166 offset:35840
	ds_read_b128 v[204:207], v166 offset:36864
	ds_read_b128 v[208:211], v166 offset:37888
	ds_read_b128 v[212:215], v166 offset:38912
	global_load_lds_dwordx4 v136, s[44:45]
	s_mov_b32 m0, s54
	ds_read_b128 v[216:219], v166 offset:39936
	global_load_lds_dwordx4 v140, s[44:45]
	s_waitcnt vmcnt(8)
	s_waitcnt lgkmcnt(0)
	s_barrier
	s_setprio 1
	s_waitcnt lgkmcnt(0)
	v_mfma_f32_16x16x32_bf16 v[124:127], v[132:135], v[188:191], v[124:127]
	v_mfma_f32_16x16x32_bf16 v[120:123], v[160:163], v[188:191], v[120:123]
	v_mfma_f32_16x16x32_bf16 v[108:111], v[132:135], v[196:199], v[108:111]
	v_mfma_f32_16x16x32_bf16 v[104:107], v[160:163], v[196:199], v[104:107]
	v_mfma_f32_16x16x32_bf16 v[92:95], v[132:135], v[204:207], v[92:95]
	v_mfma_f32_16x16x32_bf16 v[88:91], v[160:163], v[204:207], v[88:91]
	v_mfma_f32_16x16x32_bf16 v[76:79], v[132:135], v[212:215], v[76:79]
	v_mfma_f32_16x16x32_bf16 v[72:75], v[160:163], v[212:215], v[72:75]
	v_mfma_f32_16x16x32_bf16 v[124:127], v[156:159], v[192:195], v[124:127]
	v_mfma_f32_16x16x32_bf16 v[120:123], v[168:171], v[192:195], v[120:123]
	v_mfma_f32_16x16x32_bf16 v[108:111], v[156:159], v[200:203], v[108:111]
	v_mfma_f32_16x16x32_bf16 v[104:107], v[168:171], v[200:203], v[104:107]
	v_mfma_f32_16x16x32_bf16 v[92:95], v[156:159], v[208:211], v[92:95]
	v_mfma_f32_16x16x32_bf16 v[88:91], v[168:171], v[208:211], v[88:91]
	v_mfma_f32_16x16x32_bf16 v[76:79], v[156:159], v[216:219], v[76:79]
	v_mfma_f32_16x16x32_bf16 v[72:75], v[168:171], v[216:219], v[72:75]
	s_setprio 0
	s_setprio 1
	v_mfma_f32_16x16x32_bf16 v[116:119], v[172:175], v[188:191], v[116:119]
	v_mfma_f32_16x16x32_bf16 v[112:115], v[180:183], v[188:191], v[112:115]
	v_mfma_f32_16x16x32_bf16 v[100:103], v[172:175], v[196:199], v[100:103]
	v_mfma_f32_16x16x32_bf16 v[96:99], v[180:183], v[196:199], v[96:99]
	v_mfma_f32_16x16x32_bf16 v[84:87], v[172:175], v[204:207], v[84:87]
	v_mfma_f32_16x16x32_bf16 v[80:83], v[180:183], v[204:207], v[80:83]
	v_mfma_f32_16x16x32_bf16 v[68:71], v[172:175], v[212:215], v[68:71]
	v_mfma_f32_16x16x32_bf16 v[64:67], v[180:183], v[212:215], v[64:67]
	v_mfma_f32_16x16x32_bf16 v[116:119], v[176:179], v[192:195], v[116:119]
	v_mfma_f32_16x16x32_bf16 v[112:115], v[184:187], v[192:195], v[112:115]
	v_mfma_f32_16x16x32_bf16 v[100:103], v[176:179], v[200:203], v[100:103]
	v_mfma_f32_16x16x32_bf16 v[96:99], v[184:187], v[200:203], v[96:99]
	v_mfma_f32_16x16x32_bf16 v[84:87], v[176:179], v[208:211], v[84:87]
	v_mfma_f32_16x16x32_bf16 v[80:83], v[184:187], v[208:211], v[80:83]
	v_mfma_f32_16x16x32_bf16 v[68:71], v[176:179], v[216:219], v[68:71]
	v_mfma_f32_16x16x32_bf16 v[64:67], v[184:187], v[216:219], v[64:67]
	s_setprio 0
	s_barrier
	s_add_i32 s8, s8, s50
	s_mov_b32 m0, s8
	ds_read_b128 v[188:191], v166 offset:49152
	ds_read_b128 v[192:195], v166 offset:50176
	ds_read_b128 v[196:199], v166 offset:51200
	global_load_lds_dwordx4 v138, s[40:41]
	s_add_i32 m0, s8, 0x2000
	ds_read_b128 v[200:203], v166 offset:52224
	global_load_lds_dwordx4 v142, s[40:41]
	s_add_u32 s40, s40, 0xb0000
	s_addc_u32 s41, s41, 0
	s_add_i32 s8, s79, s50
	s_mov_b32 m0, s8
	ds_read_b128 v[204:207], v166 offset:53248
	global_load_lds_dwordx4 v138, s[40:41]
	s_add_i32 m0, s8, 0x2000
	ds_read_b128 v[208:211], v166 offset:54272
	global_load_lds_dwordx4 v142, s[40:41]
	s_mov_b32 m0, s60
	ds_read_b128 v[212:215], v166 offset:55296
	global_load_lds_dwordx4 v136, s[38:39]
	s_mov_b32 m0, s61
	ds_read_b128 v[216:219], v166 offset:56320
	global_load_lds_dwordx4 v140, s[38:39]
	s_waitcnt vmcnt(8)
	s_waitcnt lgkmcnt(0)
	s_barrier
	s_setprio 1
	s_waitcnt lgkmcnt(0)
	v_mfma_f32_16x16x32_bf16 v[60:63], v[132:135], v[188:191], v[60:63]
	v_mfma_f32_16x16x32_bf16 v[56:59], v[160:163], v[188:191], v[56:59]
	v_mfma_f32_16x16x32_bf16 v[44:47], v[132:135], v[196:199], v[44:47]
	v_mfma_f32_16x16x32_bf16 v[40:43], v[160:163], v[196:199], v[40:43]
	v_mfma_f32_16x16x32_bf16 v[28:31], v[132:135], v[204:207], v[28:31]
	v_mfma_f32_16x16x32_bf16 v[24:27], v[160:163], v[204:207], v[24:27]
	v_mfma_f32_16x16x32_bf16 v[12:15], v[132:135], v[212:215], v[12:15]
	v_mfma_f32_16x16x32_bf16 v[8:11], v[160:163], v[212:215], v[8:11]
	v_mfma_f32_16x16x32_bf16 v[60:63], v[156:159], v[192:195], v[60:63]
	v_mfma_f32_16x16x32_bf16 v[56:59], v[168:171], v[192:195], v[56:59]
	v_mfma_f32_16x16x32_bf16 v[44:47], v[156:159], v[200:203], v[44:47]
	v_mfma_f32_16x16x32_bf16 v[40:43], v[168:171], v[200:203], v[40:43]
	v_mfma_f32_16x16x32_bf16 v[28:31], v[156:159], v[208:211], v[28:31]
	v_mfma_f32_16x16x32_bf16 v[24:27], v[168:171], v[208:211], v[24:27]
	v_mfma_f32_16x16x32_bf16 v[12:15], v[156:159], v[216:219], v[12:15]
	v_mfma_f32_16x16x32_bf16 v[8:11], v[168:171], v[216:219], v[8:11]
	s_setprio 0
	s_setprio 1
	v_mfma_f32_16x16x32_bf16 v[52:55], v[172:175], v[188:191], v[52:55]
	v_mfma_f32_16x16x32_bf16 v[48:51], v[180:183], v[188:191], v[48:51]
	v_mfma_f32_16x16x32_bf16 v[36:39], v[172:175], v[196:199], v[36:39]
	v_mfma_f32_16x16x32_bf16 v[32:35], v[180:183], v[196:199], v[32:35]
	v_mfma_f32_16x16x32_bf16 v[20:23], v[172:175], v[204:207], v[20:23]
	v_mfma_f32_16x16x32_bf16 v[16:19], v[180:183], v[204:207], v[16:19]
	v_mfma_f32_16x16x32_bf16 v[4:7], v[172:175], v[212:215], v[4:7]
	v_mfma_f32_16x16x32_bf16 v[0:3], v[180:183], v[212:215], v[0:3]
	v_mfma_f32_16x16x32_bf16 v[52:55], v[176:179], v[192:195], v[52:55]
	v_mfma_f32_16x16x32_bf16 v[48:51], v[184:187], v[192:195], v[48:51]
	v_mfma_f32_16x16x32_bf16 v[36:39], v[176:179], v[200:203], v[36:39]
	v_mfma_f32_16x16x32_bf16 v[32:35], v[184:187], v[200:203], v[32:35]
	v_mfma_f32_16x16x32_bf16 v[20:23], v[176:179], v[208:211], v[20:23]
	v_mfma_f32_16x16x32_bf16 v[16:19], v[184:187], v[208:211], v[16:19]
	v_mfma_f32_16x16x32_bf16 v[4:7], v[176:179], v[216:219], v[4:7]
	v_mfma_f32_16x16x32_bf16 v[0:3], v[184:187], v[216:219], v[0:3]
	s_setprio 0
	s_barrier
	s_add_i32 s8, s78, 2
	s_add_u32 s36, s36, 0x100
	s_addc_u32 s37, s37, 0
	s_cmp_gt_u32 s78, 41
	s_mov_b32 s78, s8
	s_cbranch_scc1 .LBB0_903

.LBB0_1017:
	s_add_u32 s65, s54, s6
	s_addc_u32 s66, s55, s7
	s_add_u32 s67, s56, s8
	s_addc_u32 s68, s57, s9
	s_ashr_i32 s19, s18, 31
	s_lshl_b64 s[6:7], s[18:19], 19
	s_add_u32 s20, s34, s6
	s_addc_u32 s21, s35, s7
	s_and_b64 s[8:9], s[0:1], exec
	s_cselect_b32 s19, s21, s29
	s_cselect_b32 s69, s20, s28
	s_ashr_i32 s17, s16, 31
	s_lshl_b64 s[8:9], s[16:17], 19
	s_add_u32 s22, s48, s8
	s_addc_u32 s23, s49, s9
	s_and_b64 s[30:31], s[0:1], exec
	s_cselect_b32 s17, s23, s27
	s_cselect_b32 s70, s22, s26
	s_add_u32 s30, s69, 0x80
	s_addc_u32 s31, s19, 0
	s_add_u32 s36, s70, 0x80
	s_addc_u32 s37, s17, 0
	v_lshl_add_u64 v[128:129], s[28:29], 0, v[196:197]
	v_lshl_add_u64 v[130:131], s[28:29], 0, v[198:199]
	s_mov_b32 s71, 0
	s_mov_b64 s[38:39], 0
	s_cmpk_eq_i32 s38, 0x700
	s_cselect_b64 s[44:45], -1, 0
	s_add_u32 s46, s28, s38
	s_addc_u32 s47, s29, s39
	s_add_u32 s73, s26, s38
	s_addc_u32 s72, s27, s39
	s_add_u32 s40, s46, 0x180
	s_addc_u32 s41, s47, 0
	s_add_u32 s42, s73, 0x180
	s_addc_u32 s43, s72, 0
	s_cmpk_eq_i32 s38, 0x700
	s_cselect_b32 s40, s30, s40
	s_cselect_b32 s41, s31, s41
	s_cselect_b32 s42, s36, s42
	s_cselect_b32 s43, s37, s43
	v_add_u32_e32 v144, s61, v220
	v_add_u32_e32 v160, s62, v220
	ds_read_b128 v[132:135], v144
	ds_read_b128 v[136:139], v144 offset:1024
	ds_read_b128 v[140:143], v144 offset:2048
	ds_read_b128 v[144:147], v144 offset:3072
	ds_read_b128 v[148:151], v160
	ds_read_b128 v[152:155], v160 offset:1024
	ds_read_b128 v[156:159], v160 offset:2048
	ds_read_b128 v[160:163], v160 offset:3072
	s_add_u32 s10, s46, 0x100
	s_addc_u32 s76, s47, 0
	s_and_b64 s[46:47], exec, s[44:45]
	s_cselect_b32 s47, s19, s76
	s_cselect_b32 s46, s69, s10
	s_add_u32 s10, s73, 0x100
	s_addc_u32 s72, s72, 0
	s_and_b64 s[44:45], exec, s[44:45]
	s_cselect_b32 s45, s17, s72
	s_cselect_b32 s44, s70, s10
	v_lshl_add_u64 v[216:217], v[128:129], 0, s[38:39]
	s_add_i32 m0, s25, 0xc000
	ds_read_b128 v[164:167], v221
	ds_read_b128 v[168:171], v221 offset:1024
	ds_read_b128 v[172:175], v221 offset:2048
	ds_read_b128 v[176:179], v221 offset:3072
	ds_read_b128 v[180:183], v221 offset:4096
	ds_read_b128 v[204:207], v221 offset:5120
	ds_read_b128 v[208:211], v221 offset:6144
	global_load_lds_dwordx4 v[216:217], off
	v_lshl_add_u64 v[216:217], v[130:131], 0, s[38:39]
	s_add_i32 m0, s25, 0xe000
	ds_read_b128 v[212:215], v221 offset:7168
	global_load_lds_dwordx4 v[216:217], off
	s_waitcnt vmcnt(8)
	s_waitcnt lgkmcnt(0)
	s_barrier
	s_setprio 1
	s_waitcnt lgkmcnt(0)
	v_mfma_f32_16x16x32_bf16 v[124:127], v[132:135], v[164:167], 0
	v_mfma_f32_16x16x32_bf16 v[120:123], v[140:143], v[164:167], 0
	v_mfma_f32_16x16x32_bf16 v[108:111], v[132:135], v[172:175], 0
	v_mfma_f32_16x16x32_bf16 v[104:107], v[140:143], v[172:175], 0
	v_mfma_f32_16x16x32_bf16 v[92:95], v[132:135], v[180:183], 0
	v_mfma_f32_16x16x32_bf16 v[88:91], v[140:143], v[180:183], 0
	v_mfma_f32_16x16x32_bf16 v[76:79], v[132:135], v[208:211], 0
	v_mfma_f32_16x16x32_bf16 v[72:75], v[140:143], v[208:211], 0
	v_mfma_f32_16x16x32_bf16 v[124:127], v[136:139], v[168:171], v[124:127]
	v_mfma_f32_16x16x32_bf16 v[120:123], v[144:147], v[168:171], v[120:123]
	v_mfma_f32_16x16x32_bf16 v[108:111], v[136:139], v[176:179], v[108:111]
	v_mfma_f32_16x16x32_bf16 v[104:107], v[144:147], v[176:179], v[104:107]
	v_mfma_f32_16x16x32_bf16 v[92:95], v[136:139], v[204:207], v[92:95]
	v_mfma_f32_16x16x32_bf16 v[88:91], v[144:147], v[204:207], v[88:91]
	v_mfma_f32_16x16x32_bf16 v[76:79], v[136:139], v[212:215], v[76:79]
	v_mfma_f32_16x16x32_bf16 v[72:75], v[144:147], v[212:215], v[72:75]
	s_setprio 0
	s_setprio 1
	v_mfma_f32_16x16x32_bf16 v[116:119], v[148:151], v[164:167], 0
	v_mfma_f32_16x16x32_bf16 v[112:115], v[156:159], v[164:167], 0
	v_mfma_f32_16x16x32_bf16 v[100:103], v[148:151], v[172:175], 0
	v_mfma_f32_16x16x32_bf16 v[96:99], v[156:159], v[172:175], 0
	v_mfma_f32_16x16x32_bf16 v[84:87], v[148:151], v[180:183], 0
	v_mfma_f32_16x16x32_bf16 v[80:83], v[156:159], v[180:183], 0
	v_mfma_f32_16x16x32_bf16 v[68:71], v[148:151], v[208:211], 0
	v_mfma_f32_16x16x32_bf16 v[64:67], v[156:159], v[208:211], 0
	v_mfma_f32_16x16x32_bf16 v[116:119], v[152:155], v[168:171], v[116:119]
	v_mfma_f32_16x16x32_bf16 v[112:115], v[160:163], v[168:171], v[112:115]
	v_mfma_f32_16x16x32_bf16 v[100:103], v[152:155], v[176:179], v[100:103]
	v_mfma_f32_16x16x32_bf16 v[96:99], v[160:163], v[176:179], v[96:99]
	v_mfma_f32_16x16x32_bf16 v[84:87], v[152:155], v[204:207], v[84:87]
	v_mfma_f32_16x16x32_bf16 v[80:83], v[160:163], v[204:207], v[80:83]
	v_mfma_f32_16x16x32_bf16 v[68:71], v[152:155], v[212:215], v[68:71]
	v_mfma_f32_16x16x32_bf16 v[64:67], v[160:163], v[212:215], v[64:67]
	s_setprio 0
	s_barrier
	s_add_i32 s10, s61, s50
	s_mov_b32 m0, s10
	ds_read_b128 v[164:167], v221 offset:16384
	ds_read_b128 v[168:171], v221 offset:17408
	ds_read_b128 v[172:175], v221 offset:18432
	global_load_lds_dwordx4 v186, s[44:45]
	s_add_i32 m0, s10, 0x2000
	ds_read_b128 v[176:179], v221 offset:19456
	global_load_lds_dwordx4 v190, s[44:45]
	s_add_u32 s44, s44, 0x40000
	s_addc_u32 s45, s45, 0
	s_add_i32 s10, s62, s50
	s_mov_b32 m0, s10
	ds_read_b128 v[180:183], v221 offset:20480
	global_load_lds_dwordx4 v186, s[44:45]
	s_add_i32 m0, s10, 0x2000
	ds_read_b128 v[204:207], v221 offset:21504
	global_load_lds_dwordx4 v190, s[44:45]
	s_mov_b32 m0, s25
	ds_read_b128 v[208:211], v221 offset:22528
	global_load_lds_dwordx4 v184, s[46:47]
	s_mov_b32 m0, s51
	ds_read_b128 v[212:215], v221 offset:23552
	global_load_lds_dwordx4 v188, s[46:47]
	s_waitcnt vmcnt(8)
	s_waitcnt lgkmcnt(0)
	s_barrier
	s_setprio 1
	s_waitcnt lgkmcnt(0)
	v_mfma_f32_16x16x32_bf16 v[60:63], v[132:135], v[164:167], 0
	v_mfma_f32_16x16x32_bf16 v[56:59], v[140:143], v[164:167], 0
	v_mfma_f32_16x16x32_bf16 v[44:47], v[132:135], v[172:175], 0
	v_mfma_f32_16x16x32_bf16 v[40:43], v[140:143], v[172:175], 0
	v_mfma_f32_16x16x32_bf16 v[28:31], v[132:135], v[180:183], 0
	v_mfma_f32_16x16x32_bf16 v[24:27], v[140:143], v[180:183], 0
	v_mfma_f32_16x16x32_bf16 v[12:15], v[132:135], v[208:211], 0
	v_mfma_f32_16x16x32_bf16 v[8:11], v[140:143], v[208:211], 0
	v_mfma_f32_16x16x32_bf16 v[60:63], v[136:139], v[168:171], v[60:63]
	v_mfma_f32_16x16x32_bf16 v[56:59], v[144:147], v[168:171], v[56:59]
	v_mfma_f32_16x16x32_bf16 v[44:47], v[136:139], v[176:179], v[44:47]
	v_mfma_f32_16x16x32_bf16 v[40:43], v[144:147], v[176:179], v[40:43]
	v_mfma_f32_16x16x32_bf16 v[28:31], v[136:139], v[204:207], v[28:31]
	v_mfma_f32_16x16x32_bf16 v[24:27], v[144:147], v[204:207], v[24:27]
	v_mfma_f32_16x16x32_bf16 v[12:15], v[136:139], v[212:215], v[12:15]
	v_mfma_f32_16x16x32_bf16 v[8:11], v[144:147], v[212:215], v[8:11]
	s_setprio 0
	s_setprio 1
	v_mfma_f32_16x16x32_bf16 v[52:55], v[148:151], v[164:167], 0
	v_mfma_f32_16x16x32_bf16 v[48:51], v[156:159], v[164:167], 0
	v_mfma_f32_16x16x32_bf16 v[36:39], v[148:151], v[172:175], 0
	v_mfma_f32_16x16x32_bf16 v[32:35], v[156:159], v[172:175], 0
	v_mfma_f32_16x16x32_bf16 v[20:23], v[148:151], v[180:183], 0
	v_mfma_f32_16x16x32_bf16 v[16:19], v[156:159], v[180:183], 0
	v_mfma_f32_16x16x32_bf16 v[4:7], v[148:151], v[208:211], 0
	v_mfma_f32_16x16x32_bf16 v[0:3], v[156:159], v[208:211], 0
	v_mfma_f32_16x16x32_bf16 v[52:55], v[152:155], v[168:171], v[52:55]
	v_mfma_f32_16x16x32_bf16 v[48:51], v[160:163], v[168:171], v[48:51]
	v_mfma_f32_16x16x32_bf16 v[36:39], v[152:155], v[176:179], v[36:39]
	v_mfma_f32_16x16x32_bf16 v[32:35], v[160:163], v[176:179], v[32:35]
	v_mfma_f32_16x16x32_bf16 v[20:23], v[152:155], v[204:207], v[20:23]
	v_mfma_f32_16x16x32_bf16 v[16:19], v[160:163], v[204:207], v[16:19]
	v_mfma_f32_16x16x32_bf16 v[4:7], v[152:155], v[212:215], v[4:7]
	v_mfma_f32_16x16x32_bf16 v[0:3], v[160:163], v[212:215], v[0:3]
	s_setprio 0
	s_barrier
	s_add_i32 s10, 0, 0x18000
	s_add_i32 s72, 0, 0x1c000
	v_add_u32_e32 v144, s10, v220
	v_add_u32_e32 v160, s72, v220
	ds_read_b128 v[132:135], v144
	ds_read_b128 v[136:139], v144 offset:1024
	ds_read_b128 v[140:143], v144 offset:2048
	ds_read_b128 v[144:147], v144 offset:3072
	ds_read_b128 v[148:151], v160
	ds_read_b128 v[152:155], v160 offset:1024
	ds_read_b128 v[156:159], v160 offset:2048
	ds_read_b128 v[160:163], v160 offset:3072
	s_add_u32 s44, s46, 0x40000
	s_addc_u32 s45, s47, 0
	s_mov_b32 m0, s52
	ds_read_b128 v[164:167], v221 offset:32768
	ds_read_b128 v[168:171], v221 offset:33792
	ds_read_b128 v[172:175], v221 offset:34816
	ds_read_b128 v[176:179], v221 offset:35840
	ds_read_b128 v[180:183], v221 offset:36864
	ds_read_b128 v[204:207], v221 offset:37888
	ds_read_b128 v[208:211], v221 offset:38912
	global_load_lds_dwordx4 v184, s[44:45]
	s_mov_b32 m0, s53
	ds_read_b128 v[212:215], v221 offset:39936
	global_load_lds_dwordx4 v188, s[44:45]
	s_waitcnt vmcnt(8)
	s_waitcnt lgkmcnt(0)
	s_barrier
	s_setprio 1
	s_waitcnt lgkmcnt(0)
	v_mfma_f32_16x16x32_bf16 v[124:127], v[132:135], v[164:167], v[124:127]
	v_mfma_f32_16x16x32_bf16 v[120:123], v[140:143], v[164:167], v[120:123]
	v_mfma_f32_16x16x32_bf16 v[108:111], v[132:135], v[172:175], v[108:111]
	v_mfma_f32_16x16x32_bf16 v[104:107], v[140:143], v[172:175], v[104:107]
	v_mfma_f32_16x16x32_bf16 v[92:95], v[132:135], v[180:183], v[92:95]
	v_mfma_f32_16x16x32_bf16 v[88:91], v[140:143], v[180:183], v[88:91]
	v_mfma_f32_16x16x32_bf16 v[76:79], v[132:135], v[208:211], v[76:79]
	v_mfma_f32_16x16x32_bf16 v[72:75], v[140:143], v[208:211], v[72:75]
	v_mfma_f32_16x16x32_bf16 v[124:127], v[136:139], v[168:171], v[124:127]
	v_mfma_f32_16x16x32_bf16 v[120:123], v[144:147], v[168:171], v[120:123]
	v_mfma_f32_16x16x32_bf16 v[108:111], v[136:139], v[176:179], v[108:111]
	v_mfma_f32_16x16x32_bf16 v[104:107], v[144:147], v[176:179], v[104:107]
	v_mfma_f32_16x16x32_bf16 v[92:95], v[136:139], v[204:207], v[92:95]
	v_mfma_f32_16x16x32_bf16 v[88:91], v[144:147], v[204:207], v[88:91]
	v_mfma_f32_16x16x32_bf16 v[76:79], v[136:139], v[212:215], v[76:79]
	v_mfma_f32_16x16x32_bf16 v[72:75], v[144:147], v[212:215], v[72:75]
	s_setprio 0
	s_setprio 1
	v_mfma_f32_16x16x32_bf16 v[116:119], v[148:151], v[164:167], v[116:119]
	v_mfma_f32_16x16x32_bf16 v[112:115], v[156:159], v[164:167], v[112:115]
	v_mfma_f32_16x16x32_bf16 v[100:103], v[148:151], v[172:175], v[100:103]
	v_mfma_f32_16x16x32_bf16 v[96:99], v[156:159], v[172:175], v[96:99]
	v_mfma_f32_16x16x32_bf16 v[84:87], v[148:151], v[180:183], v[84:87]
	v_mfma_f32_16x16x32_bf16 v[80:83], v[156:159], v[180:183], v[80:83]
	v_mfma_f32_16x16x32_bf16 v[68:71], v[148:151], v[208:211], v[68:71]
	v_mfma_f32_16x16x32_bf16 v[64:67], v[156:159], v[208:211], v[64:67]
	v_mfma_f32_16x16x32_bf16 v[116:119], v[152:155], v[168:171], v[116:119]
	v_mfma_f32_16x16x32_bf16 v[112:115], v[160:163], v[168:171], v[112:115]
	v_mfma_f32_16x16x32_bf16 v[100:103], v[152:155], v[176:179], v[100:103]
	v_mfma_f32_16x16x32_bf16 v[96:99], v[160:163], v[176:179], v[96:99]
	v_mfma_f32_16x16x32_bf16 v[84:87], v[152:155], v[204:207], v[84:87]
	v_mfma_f32_16x16x32_bf16 v[80:83], v[160:163], v[204:207], v[80:83]
	v_mfma_f32_16x16x32_bf16 v[68:71], v[152:155], v[212:215], v[68:71]
	v_mfma_f32_16x16x32_bf16 v[64:67], v[160:163], v[212:215], v[64:67]
	s_setprio 0
	s_barrier
	s_add_i32 s10, s10, s50
	s_mov_b32 m0, s10
	ds_read_b128 v[164:167], v221 offset:49152
	ds_read_b128 v[168:171], v221 offset:50176
	ds_read_b128 v[172:175], v221 offset:51200
	global_load_lds_dwordx4 v186, s[42:43]
	s_add_i32 m0, s10, 0x2000
	ds_read_b128 v[176:179], v221 offset:52224
	global_load_lds_dwordx4 v190, s[42:43]
	s_add_u32 s42, s42, 0x40000
	s_addc_u32 s43, s43, 0
	s_add_i32 s10, s72, s50
	s_mov_b32 m0, s10
	ds_read_b128 v[180:183], v221 offset:53248
	global_load_lds_dwordx4 v186, s[42:43]
	s_add_i32 m0, s10, 0x2000
	ds_read_b128 v[204:207], v221 offset:54272
	global_load_lds_dwordx4 v190, s[42:43]
	s_mov_b32 m0, s58
	ds_read_b128 v[208:211], v221 offset:55296
	global_load_lds_dwordx4 v184, s[40:41]
	s_mov_b32 m0, s59
	ds_read_b128 v[212:215], v221 offset:56320
	global_load_lds_dwordx4 v188, s[40:41]
	s_waitcnt vmcnt(8)
	s_waitcnt lgkmcnt(0)
	s_barrier
	s_setprio 1
	s_waitcnt lgkmcnt(0)
	v_mfma_f32_16x16x32_bf16 v[60:63], v[132:135], v[164:167], v[60:63]
	v_mfma_f32_16x16x32_bf16 v[56:59], v[140:143], v[164:167], v[56:59]
	v_mfma_f32_16x16x32_bf16 v[44:47], v[132:135], v[172:175], v[44:47]
	v_mfma_f32_16x16x32_bf16 v[40:43], v[140:143], v[172:175], v[40:43]
	v_mfma_f32_16x16x32_bf16 v[28:31], v[132:135], v[180:183], v[28:31]
	v_mfma_f32_16x16x32_bf16 v[24:27], v[140:143], v[180:183], v[24:27]
	v_mfma_f32_16x16x32_bf16 v[12:15], v[132:135], v[208:211], v[12:15]
	v_mfma_f32_16x16x32_bf16 v[8:11], v[140:143], v[208:211], v[8:11]
	v_mfma_f32_16x16x32_bf16 v[60:63], v[136:139], v[168:171], v[60:63]
	v_mfma_f32_16x16x32_bf16 v[56:59], v[144:147], v[168:171], v[56:59]
	v_mfma_f32_16x16x32_bf16 v[44:47], v[136:139], v[176:179], v[44:47]
	v_mfma_f32_16x16x32_bf16 v[40:43], v[144:147], v[176:179], v[40:43]
	v_mfma_f32_16x16x32_bf16 v[28:31], v[136:139], v[204:207], v[28:31]
	v_mfma_f32_16x16x32_bf16 v[24:27], v[144:147], v[204:207], v[24:27]
	v_mfma_f32_16x16x32_bf16 v[12:15], v[136:139], v[212:215], v[12:15]
	v_mfma_f32_16x16x32_bf16 v[8:11], v[144:147], v[212:215], v[8:11]
	s_setprio 0
	s_setprio 1
	v_mfma_f32_16x16x32_bf16 v[52:55], v[148:151], v[164:167], v[52:55]
	v_mfma_f32_16x16x32_bf16 v[48:51], v[156:159], v[164:167], v[48:51]
	v_mfma_f32_16x16x32_bf16 v[36:39], v[148:151], v[172:175], v[36:39]
	v_mfma_f32_16x16x32_bf16 v[32:35], v[156:159], v[172:175], v[32:35]
	v_mfma_f32_16x16x32_bf16 v[20:23], v[148:151], v[180:183], v[20:23]
	v_mfma_f32_16x16x32_bf16 v[16:19], v[156:159], v[180:183], v[16:19]
	v_mfma_f32_16x16x32_bf16 v[4:7], v[148:151], v[208:211], v[4:7]
	v_mfma_f32_16x16x32_bf16 v[0:3], v[156:159], v[208:211], v[0:3]
	v_mfma_f32_16x16x32_bf16 v[52:55], v[152:155], v[168:171], v[52:55]
	v_mfma_f32_16x16x32_bf16 v[48:51], v[160:163], v[168:171], v[48:51]
	v_mfma_f32_16x16x32_bf16 v[36:39], v[152:155], v[176:179], v[36:39]
	v_mfma_f32_16x16x32_bf16 v[32:35], v[160:163], v[176:179], v[32:35]
	v_mfma_f32_16x16x32_bf16 v[20:23], v[152:155], v[204:207], v[20:23]
	v_mfma_f32_16x16x32_bf16 v[16:19], v[160:163], v[204:207], v[16:19]
	v_mfma_f32_16x16x32_bf16 v[4:7], v[152:155], v[212:215], v[4:7]
	v_mfma_f32_16x16x32_bf16 v[0:3], v[160:163], v[212:215], v[0:3]
	s_setprio 0
	s_barrier
	s_add_i32 s10, s71, 2
	s_add_u32 s38, s38, 0x100
	s_addc_u32 s39, s39, 0
	s_cmp_gt_u32 s71, 13
	s_mov_b32 s71, s10
	s_cbranch_scc1 .LBB0_1025
	s_branch .LBB0_1019
.LBB0_1018:
	v_add_u32_e32 v144, s61, v220
	v_add_u32_e32 v160, s62, v220
	ds_read_b128 v[132:135], v144
	ds_read_b128 v[136:139], v144 offset:1024
	ds_read_b128 v[140:143], v144 offset:2048
	ds_read_b128 v[144:147], v144 offset:3072
	ds_read_b128 v[148:151], v160
	ds_read_b128 v[152:155], v160 offset:1024
	ds_read_b128 v[156:159], v160 offset:2048
	ds_read_b128 v[160:163], v160 offset:3072
	s_add_u32 s10, s46, 0x100
	s_addc_u32 s76, s47, 0
	s_and_b64 s[46:47], exec, s[44:45]
	s_cselect_b32 s47, s19, s76
	s_cselect_b32 s46, s69, s10
	s_add_u32 s10, s73, 0x100
	s_addc_u32 s72, s72, 0
	s_and_b64 s[44:45], exec, s[44:45]
	s_cselect_b32 s45, s17, s72
	s_cselect_b32 s44, s70, s10
	v_lshl_add_u64 v[216:217], v[128:129], 0, s[38:39]
	s_add_i32 m0, s25, 0xc000
	ds_read_b128 v[164:167], v221
	ds_read_b128 v[168:171], v221 offset:1024
	ds_read_b128 v[172:175], v221 offset:2048
	ds_read_b128 v[176:179], v221 offset:3072
	ds_read_b128 v[180:183], v221 offset:4096
	ds_read_b128 v[204:207], v221 offset:5120
	ds_read_b128 v[208:211], v221 offset:6144
	global_load_lds_dwordx4 v[216:217], off
	v_lshl_add_u64 v[216:217], v[130:131], 0, s[38:39]
	s_add_i32 m0, s25, 0xe000
	ds_read_b128 v[212:215], v221 offset:7168
	global_load_lds_dwordx4 v[216:217], off
	s_waitcnt vmcnt(8)
	s_waitcnt lgkmcnt(0)
	s_barrier
	s_setprio 1
	s_waitcnt lgkmcnt(0)
	v_mfma_f32_16x16x32_bf16 v[124:127], v[132:135], v[164:167], v[124:127]
	v_mfma_f32_16x16x32_bf16 v[120:123], v[140:143], v[164:167], v[120:123]
	v_mfma_f32_16x16x32_bf16 v[108:111], v[132:135], v[172:175], v[108:111]
	v_mfma_f32_16x16x32_bf16 v[104:107], v[140:143], v[172:175], v[104:107]
	v_mfma_f32_16x16x32_bf16 v[92:95], v[132:135], v[180:183], v[92:95]
	v_mfma_f32_16x16x32_bf16 v[88:91], v[140:143], v[180:183], v[88:91]
	v_mfma_f32_16x16x32_bf16 v[76:79], v[132:135], v[208:211], v[76:79]
	v_mfma_f32_16x16x32_bf16 v[72:75], v[140:143], v[208:211], v[72:75]
	v_mfma_f32_16x16x32_bf16 v[124:127], v[136:139], v[168:171], v[124:127]
	v_mfma_f32_16x16x32_bf16 v[120:123], v[144:147], v[168:171], v[120:123]
	v_mfma_f32_16x16x32_bf16 v[108:111], v[136:139], v[176:179], v[108:111]
	v_mfma_f32_16x16x32_bf16 v[104:107], v[144:147], v[176:179], v[104:107]
	v_mfma_f32_16x16x32_bf16 v[92:95], v[136:139], v[204:207], v[92:95]
	v_mfma_f32_16x16x32_bf16 v[88:91], v[144:147], v[204:207], v[88:91]
	v_mfma_f32_16x16x32_bf16 v[76:79], v[136:139], v[212:215], v[76:79]
	v_mfma_f32_16x16x32_bf16 v[72:75], v[144:147], v[212:215], v[72:75]
	s_setprio 0
	s_setprio 1
	v_mfma_f32_16x16x32_bf16 v[116:119], v[148:151], v[164:167], v[116:119]
	v_mfma_f32_16x16x32_bf16 v[112:115], v[156:159], v[164:167], v[112:115]
	v_mfma_f32_16x16x32_bf16 v[100:103], v[148:151], v[172:175], v[100:103]
	v_mfma_f32_16x16x32_bf16 v[96:99], v[156:159], v[172:175], v[96:99]
	v_mfma_f32_16x16x32_bf16 v[84:87], v[148:151], v[180:183], v[84:87]
	v_mfma_f32_16x16x32_bf16 v[80:83], v[156:159], v[180:183], v[80:83]
	v_mfma_f32_16x16x32_bf16 v[68:71], v[148:151], v[208:211], v[68:71]
	v_mfma_f32_16x16x32_bf16 v[64:67], v[156:159], v[208:211], v[64:67]
	v_mfma_f32_16x16x32_bf16 v[116:119], v[152:155], v[168:171], v[116:119]
	v_mfma_f32_16x16x32_bf16 v[112:115], v[160:163], v[168:171], v[112:115]
	v_mfma_f32_16x16x32_bf16 v[100:103], v[152:155], v[176:179], v[100:103]
	v_mfma_f32_16x16x32_bf16 v[96:99], v[160:163], v[176:179], v[96:99]
	v_mfma_f32_16x16x32_bf16 v[84:87], v[152:155], v[204:207], v[84:87]
	v_mfma_f32_16x16x32_bf16 v[80:83], v[160:163], v[204:207], v[80:83]
	v_mfma_f32_16x16x32_bf16 v[68:71], v[152:155], v[212:215], v[68:71]
	v_mfma_f32_16x16x32_bf16 v[64:67], v[160:163], v[212:215], v[64:67]
	s_setprio 0
	s_barrier
	s_add_i32 s10, s61, s50
	s_mov_b32 m0, s10
	ds_read_b128 v[164:167], v221 offset:16384
	ds_read_b128 v[168:171], v221 offset:17408
	ds_read_b128 v[172:175], v221 offset:18432
	global_load_lds_dwordx4 v186, s[44:45]
	s_add_i32 m0, s10, 0x2000
	ds_read_b128 v[176:179], v221 offset:19456
	global_load_lds_dwordx4 v190, s[44:45]
	s_add_u32 s44, s44, 0x40000
	s_addc_u32 s45, s45, 0
	s_add_i32 s10, s62, s50
	s_mov_b32 m0, s10
	ds_read_b128 v[180:183], v221 offset:20480
	global_load_lds_dwordx4 v186, s[44:45]
	s_add_i32 m0, s10, 0x2000
	ds_read_b128 v[204:207], v221 offset:21504
	global_load_lds_dwordx4 v190, s[44:45]
	s_mov_b32 m0, s25
	ds_read_b128 v[208:211], v221 offset:22528
	global_load_lds_dwordx4 v184, s[46:47]
	s_mov_b32 m0, s51
	ds_read_b128 v[212:215], v221 offset:23552
	global_load_lds_dwordx4 v188, s[46:47]
	s_waitcnt vmcnt(8)
	s_waitcnt lgkmcnt(0)
	s_barrier
	s_setprio 1
	s_waitcnt lgkmcnt(0)
	v_mfma_f32_16x16x32_bf16 v[60:63], v[132:135], v[164:167], v[60:63]
	v_mfma_f32_16x16x32_bf16 v[56:59], v[140:143], v[164:167], v[56:59]
	v_mfma_f32_16x16x32_bf16 v[44:47], v[132:135], v[172:175], v[44:47]
	v_mfma_f32_16x16x32_bf16 v[40:43], v[140:143], v[172:175], v[40:43]
	v_mfma_f32_16x16x32_bf16 v[28:31], v[132:135], v[180:183], v[28:31]
	v_mfma_f32_16x16x32_bf16 v[24:27], v[140:143], v[180:183], v[24:27]
	v_mfma_f32_16x16x32_bf16 v[12:15], v[132:135], v[208:211], v[12:15]
	v_mfma_f32_16x16x32_bf16 v[8:11], v[140:143], v[208:211], v[8:11]
	v_mfma_f32_16x16x32_bf16 v[60:63], v[136:139], v[168:171], v[60:63]
	v_mfma_f32_16x16x32_bf16 v[56:59], v[144:147], v[168:171], v[56:59]
	v_mfma_f32_16x16x32_bf16 v[44:47], v[136:139], v[176:179], v[44:47]
	v_mfma_f32_16x16x32_bf16 v[40:43], v[144:147], v[176:179], v[40:43]
	v_mfma_f32_16x16x32_bf16 v[28:31], v[136:139], v[204:207], v[28:31]
	v_mfma_f32_16x16x32_bf16 v[24:27], v[144:147], v[204:207], v[24:27]
	v_mfma_f32_16x16x32_bf16 v[12:15], v[136:139], v[212:215], v[12:15]
	v_mfma_f32_16x16x32_bf16 v[8:11], v[144:147], v[212:215], v[8:11]
	s_setprio 0
	s_setprio 1
	v_mfma_f32_16x16x32_bf16 v[52:55], v[148:151], v[164:167], v[52:55]
	v_mfma_f32_16x16x32_bf16 v[48:51], v[156:159], v[164:167], v[48:51]
	v_mfma_f32_16x16x32_bf16 v[36:39], v[148:151], v[172:175], v[36:39]
	v_mfma_f32_16x16x32_bf16 v[32:35], v[156:159], v[172:175], v[32:35]
	v_mfma_f32_16x16x32_bf16 v[20:23], v[148:151], v[180:183], v[20:23]
	v_mfma_f32_16x16x32_bf16 v[16:19], v[156:159], v[180:183], v[16:19]
	v_mfma_f32_16x16x32_bf16 v[4:7], v[148:151], v[208:211], v[4:7]
	v_mfma_f32_16x16x32_bf16 v[0:3], v[156:159], v[208:211], v[0:3]
	v_mfma_f32_16x16x32_bf16 v[52:55], v[152:155], v[168:171], v[52:55]
	v_mfma_f32_16x16x32_bf16 v[48:51], v[160:163], v[168:171], v[48:51]
	v_mfma_f32_16x16x32_bf16 v[36:39], v[152:155], v[176:179], v[36:39]
	v_mfma_f32_16x16x32_bf16 v[32:35], v[160:163], v[176:179], v[32:35]
	v_mfma_f32_16x16x32_bf16 v[20:23], v[152:155], v[204:207], v[20:23]
	v_mfma_f32_16x16x32_bf16 v[16:19], v[160:163], v[204:207], v[16:19]
	v_mfma_f32_16x16x32_bf16 v[4:7], v[152:155], v[212:215], v[4:7]
	v_mfma_f32_16x16x32_bf16 v[0:3], v[160:163], v[212:215], v[0:3]
	s_setprio 0
	s_barrier
	s_add_i32 s10, 0, 0x18000
	s_add_i32 s72, 0, 0x1c000
	v_add_u32_e32 v144, s10, v220
	v_add_u32_e32 v160, s72, v220
	ds_read_b128 v[132:135], v144
	ds_read_b128 v[136:139], v144 offset:1024
	ds_read_b128 v[140:143], v144 offset:2048
	ds_read_b128 v[144:147], v144 offset:3072
	ds_read_b128 v[148:151], v160
	ds_read_b128 v[152:155], v160 offset:1024
	ds_read_b128 v[156:159], v160 offset:2048
	ds_read_b128 v[160:163], v160 offset:3072
	s_add_u32 s44, s46, 0x40000
	s_addc_u32 s45, s47, 0
	s_mov_b32 m0, s52
	ds_read_b128 v[164:167], v221 offset:32768
	ds_read_b128 v[168:171], v221 offset:33792
	ds_read_b128 v[172:175], v221 offset:34816
	ds_read_b128 v[176:179], v221 offset:35840
	ds_read_b128 v[180:183], v221 offset:36864
	ds_read_b128 v[204:207], v221 offset:37888
	ds_read_b128 v[208:211], v221 offset:38912
	global_load_lds_dwordx4 v184, s[44:45]
	s_mov_b32 m0, s53
	ds_read_b128 v[212:215], v221 offset:39936
	global_load_lds_dwordx4 v188, s[44:45]
	s_waitcnt vmcnt(8)
	s_waitcnt lgkmcnt(0)
	s_barrier
	s_setprio 1
	s_waitcnt lgkmcnt(0)
	v_mfma_f32_16x16x32_bf16 v[124:127], v[132:135], v[164:167], v[124:127]
	v_mfma_f32_16x16x32_bf16 v[120:123], v[140:143], v[164:167], v[120:123]
	v_mfma_f32_16x16x32_bf16 v[108:111], v[132:135], v[172:175], v[108:111]
	v_mfma_f32_16x16x32_bf16 v[104:107], v[140:143], v[172:175], v[104:107]
	v_mfma_f32_16x16x32_bf16 v[92:95], v[132:135], v[180:183], v[92:95]
	v_mfma_f32_16x16x32_bf16 v[88:91], v[140:143], v[180:183], v[88:91]
	v_mfma_f32_16x16x32_bf16 v[76:79], v[132:135], v[208:211], v[76:79]
	v_mfma_f32_16x16x32_bf16 v[72:75], v[140:143], v[208:211], v[72:75]
	v_mfma_f32_16x16x32_bf16 v[124:127], v[136:139], v[168:171], v[124:127]
	v_mfma_f32_16x16x32_bf16 v[120:123], v[144:147], v[168:171], v[120:123]
	v_mfma_f32_16x16x32_bf16 v[108:111], v[136:139], v[176:179], v[108:111]
	v_mfma_f32_16x16x32_bf16 v[104:107], v[144:147], v[176:179], v[104:107]
	v_mfma_f32_16x16x32_bf16 v[92:95], v[136:139], v[204:207], v[92:95]
	v_mfma_f32_16x16x32_bf16 v[88:91], v[144:147], v[204:207], v[88:91]
	v_mfma_f32_16x16x32_bf16 v[76:79], v[136:139], v[212:215], v[76:79]
	v_mfma_f32_16x16x32_bf16 v[72:75], v[144:147], v[212:215], v[72:75]
	s_setprio 0
	s_setprio 1
	v_mfma_f32_16x16x32_bf16 v[116:119], v[148:151], v[164:167], v[116:119]
	v_mfma_f32_16x16x32_bf16 v[112:115], v[156:159], v[164:167], v[112:115]
	v_mfma_f32_16x16x32_bf16 v[100:103], v[148:151], v[172:175], v[100:103]
	v_mfma_f32_16x16x32_bf16 v[96:99], v[156:159], v[172:175], v[96:99]
	v_mfma_f32_16x16x32_bf16 v[84:87], v[148:151], v[180:183], v[84:87]
	v_mfma_f32_16x16x32_bf16 v[80:83], v[156:159], v[180:183], v[80:83]
	v_mfma_f32_16x16x32_bf16 v[68:71], v[148:151], v[208:211], v[68:71]
	v_mfma_f32_16x16x32_bf16 v[64:67], v[156:159], v[208:211], v[64:67]
	v_mfma_f32_16x16x32_bf16 v[116:119], v[152:155], v[168:171], v[116:119]
	v_mfma_f32_16x16x32_bf16 v[112:115], v[160:163], v[168:171], v[112:115]
	v_mfma_f32_16x16x32_bf16 v[100:103], v[152:155], v[176:179], v[100:103]
	v_mfma_f32_16x16x32_bf16 v[96:99], v[160:163], v[176:179], v[96:99]
	v_mfma_f32_16x16x32_bf16 v[84:87], v[152:155], v[204:207], v[84:87]
	v_mfma_f32_16x16x32_bf16 v[80:83], v[160:163], v[204:207], v[80:83]
	v_mfma_f32_16x16x32_bf16 v[68:71], v[152:155], v[212:215], v[68:71]
	v_mfma_f32_16x16x32_bf16 v[64:67], v[160:163], v[212:215], v[64:67]
	s_setprio 0
	s_barrier
	s_add_i32 s10, s10, s50
	s_mov_b32 m0, s10
	ds_read_b128 v[164:167], v221 offset:49152
	ds_read_b128 v[168:171], v221 offset:50176
	ds_read_b128 v[172:175], v221 offset:51200
	global_load_lds_dwordx4 v186, s[42:43]
	s_add_i32 m0, s10, 0x2000
	ds_read_b128 v[176:179], v221 offset:52224
	global_load_lds_dwordx4 v190, s[42:43]
	s_add_u32 s42, s42, 0x40000
	s_addc_u32 s43, s43, 0
	s_add_i32 s10, s72, s50
	s_mov_b32 m0, s10
	ds_read_b128 v[180:183], v221 offset:53248
	global_load_lds_dwordx4 v186, s[42:43]
	s_add_i32 m0, s10, 0x2000
	ds_read_b128 v[204:207], v221 offset:54272
	global_load_lds_dwordx4 v190, s[42:43]
	s_mov_b32 m0, s58
	ds_read_b128 v[208:211], v221 offset:55296
	global_load_lds_dwordx4 v184, s[40:41]
	s_mov_b32 m0, s59
	ds_read_b128 v[212:215], v221 offset:56320
	global_load_lds_dwordx4 v188, s[40:41]
	s_waitcnt vmcnt(8)
	s_waitcnt lgkmcnt(0)
	s_barrier
	s_setprio 1
	s_waitcnt lgkmcnt(0)
	v_mfma_f32_16x16x32_bf16 v[60:63], v[132:135], v[164:167], v[60:63]
	v_mfma_f32_16x16x32_bf16 v[56:59], v[140:143], v[164:167], v[56:59]
	v_mfma_f32_16x16x32_bf16 v[44:47], v[132:135], v[172:175], v[44:47]
	v_mfma_f32_16x16x32_bf16 v[40:43], v[140:143], v[172:175], v[40:43]
	v_mfma_f32_16x16x32_bf16 v[28:31], v[132:135], v[180:183], v[28:31]
	v_mfma_f32_16x16x32_bf16 v[24:27], v[140:143], v[180:183], v[24:27]
	v_mfma_f32_16x16x32_bf16 v[12:15], v[132:135], v[208:211], v[12:15]
	v_mfma_f32_16x16x32_bf16 v[8:11], v[140:143], v[208:211], v[8:11]
	v_mfma_f32_16x16x32_bf16 v[60:63], v[136:139], v[168:171], v[60:63]
	v_mfma_f32_16x16x32_bf16 v[56:59], v[144:147], v[168:171], v[56:59]
	v_mfma_f32_16x16x32_bf16 v[44:47], v[136:139], v[176:179], v[44:47]
	v_mfma_f32_16x16x32_bf16 v[40:43], v[144:147], v[176:179], v[40:43]
	v_mfma_f32_16x16x32_bf16 v[28:31], v[136:139], v[204:207], v[28:31]
	v_mfma_f32_16x16x32_bf16 v[24:27], v[144:147], v[204:207], v[24:27]
	v_mfma_f32_16x16x32_bf16 v[12:15], v[136:139], v[212:215], v[12:15]
	v_mfma_f32_16x16x32_bf16 v[8:11], v[144:147], v[212:215], v[8:11]
	s_setprio 0
	s_setprio 1
	v_mfma_f32_16x16x32_bf16 v[52:55], v[148:151], v[164:167], v[52:55]
	v_mfma_f32_16x16x32_bf16 v[48:51], v[156:159], v[164:167], v[48:51]
	v_mfma_f32_16x16x32_bf16 v[36:39], v[148:151], v[172:175], v[36:39]
	v_mfma_f32_16x16x32_bf16 v[32:35], v[156:159], v[172:175], v[32:35]
	v_mfma_f32_16x16x32_bf16 v[20:23], v[148:151], v[180:183], v[20:23]
	v_mfma_f32_16x16x32_bf16 v[16:19], v[156:159], v[180:183], v[16:19]
	v_mfma_f32_16x16x32_bf16 v[4:7], v[148:151], v[208:211], v[4:7]
	v_mfma_f32_16x16x32_bf16 v[0:3], v[156:159], v[208:211], v[0:3]
	v_mfma_f32_16x16x32_bf16 v[52:55], v[152:155], v[168:171], v[52:55]
	v_mfma_f32_16x16x32_bf16 v[48:51], v[160:163], v[168:171], v[48:51]
	v_mfma_f32_16x16x32_bf16 v[36:39], v[152:155], v[176:179], v[36:39]
	v_mfma_f32_16x16x32_bf16 v[32:35], v[160:163], v[176:179], v[32:35]
	v_mfma_f32_16x16x32_bf16 v[20:23], v[152:155], v[204:207], v[20:23]
	v_mfma_f32_16x16x32_bf16 v[16:19], v[160:163], v[204:207], v[16:19]
	v_mfma_f32_16x16x32_bf16 v[4:7], v[152:155], v[212:215], v[4:7]
	v_mfma_f32_16x16x32_bf16 v[0:3], v[160:163], v[212:215], v[0:3]
	s_setprio 0
	s_barrier
	s_add_i32 s10, s71, 2
	s_add_u32 s38, s38, 0x100
	s_addc_u32 s39, s39, 0
	s_cmp_gt_u32 s71, 13
	s_mov_b32 s71, s10
	s_cbranch_scc1 .LBB0_1025
